# GEMM K-loops: accumulator-chained MFMA pairs, chains visited n-major (B-fragment operand constant over 4 chains); bit-identical
# speedup vs baseline: 1.0138x; 1.0067x over previous
; #define PG8_WAIT_V(n) asm volatile("s_waitcnt vmcnt(" #n ")" ::: "memory")
; #define PG8_WAIT_L(n) asm volatile("s_waitcnt lgkmcnt(" #n ")" ::: "memory")
; #define PG8_BAR __builtin_amdgcn_s_barrier()
; #define PG8_SCHED __builtin_amdgcn_sched_barrier(0)
; template <class Epi, class AddrA, class AddrB>
; __device__ __forceinline__ void gemm_phase(const Sched S, const int lda, const int ldb, const int K, const AddrA addrA,
;                                            const AddrB addrB, const Epi E) {
;     ...
;     for (int t = 0; t < nt; t += 2) {
;       const bool last = (t == nt - 2);
;       const char* a1 = cA + (size_t)(t + 1) * kstep;
;       const char* a2 = last ? nA : cA + (size_t)(t + 2) * kstep;
;       const char* b2 = last ? nB : cB + (size_t)(t + 2) * kstep;
;       const char* a3 = a2 + kstep;
;       const char* b3 = b2 + kstep;
;       PG8_LDB(B0, 0, 0); PG8_SCHED; PG8_LDA(At, 0, 0); PG8_STAGE(PG8_SA(1, 1), a1 + hstepA, voffA);
;       PG8_WAIT_L(8); PG8_BAR; PG8_WAIT_L(0); PG8_MMA(0, 0, At, B0); PG8_BAR; PG8_SCHED;
;       PG8_LDB(B1, 0, 1); PG8_STAGE(PG8_SB(0, 0), b2, voffB);
;       PG8_BAR; PG8_WAIT_L(0); PG8_MMA(0, 1, At, B1); PG8_BAR;
;       PG8_LDA(At, 0, 1); PG8_STAGE(PG8_SA(0, 0), a2, voffA);
;       PG8_BAR; PG8_WAIT_L(0); PG8_MMA(1, 0, At, B0); PG8_BAR; PG8_SCHED;
;       PG8_STAGE(PG8_SB(0, 1), b2 + hstepB, voffB);
;       PG8_WAIT_V(6); PG8_BAR; PG8_MMA(1, 1, At, B1); PG8_BAR;
.LBB0_109:
	s_add_u32 s14, s12, 0xfff80080
	s_addc_u32 s15, s13, -1
	s_add_i32 s40, 0, 0x10000
	v_add_u32_e32 v142, s40, v145
	ds_read_b128 v[148:151], v142
	ds_read_b128 v[152:155], v142 offset:1024
	ds_read_b128 v[156:159], v142 offset:2048
	ds_read_b128 v[160:163], v142 offset:3072
	s_cmp_eq_u32 s39, 28
	s_cselect_b32 s17, s1, s15
	s_cselect_b32 s16, s11, s14
	s_cselect_b32 s15, s3, s38
	s_cselect_b32 s14, s36, s37
	v_lshl_add_u64 v[142:143], s[12:13], 0, v[140:141]
	s_add_i32 m0, s24, 0xc000
	ds_read_b128 v[168:171], v146
	ds_read_b128 v[172:175], v146 offset:1024
	ds_read_b128 v[176:179], v146 offset:2048
	ds_read_b128 v[180:183], v146 offset:3072
	ds_read_b128 v[184:187], v146 offset:4096
	ds_read_b128 v[188:191], v146 offset:5120
	ds_read_b128 v[192:195], v146 offset:6144
	ds_read_b128 v[212:215], v146 offset:7168
	global_load_lds_dwordx4 v[142:143], off
	v_lshl_add_u64 v[142:143], s[12:13], 0, v[138:139]
	s_add_i32 m0, s24, 0xe000
	s_nop 0
	global_load_lds_dwordx4 v[142:143], off
	s_waitcnt lgkmcnt(8)
	s_barrier
	s_waitcnt lgkmcnt(0)
	s_setprio 1
	s_waitcnt lgkmcnt(0)
	v_mfma_f32_16x16x32_bf16 v[128:131], v[148:151], v[168:171], v[128:131]
	v_mfma_f32_16x16x32_bf16 v[128:131], v[152:155], v[172:175], v[128:131]
	v_mfma_f32_16x16x32_bf16 v[120:123], v[148:151], v[176:179], v[120:123]
	v_mfma_f32_16x16x32_bf16 v[120:123], v[152:155], v[180:183], v[120:123]
	v_mfma_f32_16x16x32_bf16 v[104:107], v[148:151], v[184:187], v[104:107]
	v_mfma_f32_16x16x32_bf16 v[104:107], v[152:155], v[188:191], v[104:107]
	v_mfma_f32_16x16x32_bf16 v[88:91], v[148:151], v[192:195], v[88:91]
	v_mfma_f32_16x16x32_bf16 v[88:91], v[152:155], v[212:215], v[88:91]
	v_mfma_f32_16x16x32_bf16 v[124:127], v[156:159], v[168:171], v[124:127]
	v_mfma_f32_16x16x32_bf16 v[124:127], v[160:163], v[172:175], v[124:127]
	v_mfma_f32_16x16x32_bf16 v[112:115], v[156:159], v[176:179], v[112:115]
	v_mfma_f32_16x16x32_bf16 v[112:115], v[160:163], v[180:183], v[112:115]
	v_mfma_f32_16x16x32_bf16 v[96:99], v[156:159], v[184:187], v[96:99]
	v_mfma_f32_16x16x32_bf16 v[96:99], v[160:163], v[188:191], v[96:99]
	v_mfma_f32_16x16x32_bf16 v[80:83], v[156:159], v[192:195], v[80:83]
	v_mfma_f32_16x16x32_bf16 v[80:83], v[160:163], v[212:215], v[80:83]
	s_setprio 0
	s_barrier
	s_add_i32 s42, 0, 0x14000
	v_add_u32_e32 v142, s42, v145
	s_add_i32 s40, s40, s19
	ds_read_b128 v[216:219], v142
	ds_read_b128 v[220:223], v142 offset:1024
	ds_read_b128 v[224:227], v142 offset:2048
	ds_read_b128 v[228:231], v142 offset:3072
	v_lshl_add_u64 v[142:143], s[14:15], 0, v[134:135]
	s_mov_b32 m0, s40
	v_lshl_add_u64 v[196:197], s[14:15], 0, v[0:1]
	global_load_lds_dwordx4 v[142:143], off
	s_add_i32 m0, s40, 0x2000
	s_nop 0
	global_load_lds_dwordx4 v[196:197], off
	s_barrier
	s_waitcnt lgkmcnt(0)
	s_setprio 1
	s_waitcnt lgkmcnt(0)
	v_mfma_f32_16x16x32_bf16 v[116:119], v[216:219], v[168:171], v[116:119]
	v_mfma_f32_16x16x32_bf16 v[116:119], v[220:223], v[172:175], v[116:119]
	v_mfma_f32_16x16x32_bf16 v[100:103], v[216:219], v[176:179], v[100:103]
	v_mfma_f32_16x16x32_bf16 v[100:103], v[220:223], v[180:183], v[100:103]
	v_mfma_f32_16x16x32_bf16 v[84:87], v[216:219], v[184:187], v[84:87]
	v_mfma_f32_16x16x32_bf16 v[84:87], v[220:223], v[188:191], v[84:87]
	v_mfma_f32_16x16x32_bf16 v[72:75], v[216:219], v[192:195], v[72:75]
	v_mfma_f32_16x16x32_bf16 v[72:75], v[220:223], v[212:215], v[72:75]
	v_mfma_f32_16x16x32_bf16 v[108:111], v[224:227], v[168:171], v[108:111]
	v_mfma_f32_16x16x32_bf16 v[108:111], v[228:231], v[172:175], v[108:111]
	v_mfma_f32_16x16x32_bf16 v[92:95], v[224:227], v[176:179], v[92:95]
	v_mfma_f32_16x16x32_bf16 v[92:95], v[228:231], v[180:183], v[92:95]
	v_mfma_f32_16x16x32_bf16 v[76:79], v[224:227], v[184:187], v[76:79]
	v_mfma_f32_16x16x32_bf16 v[76:79], v[228:231], v[188:191], v[76:79]
	v_mfma_f32_16x16x32_bf16 v[68:71], v[224:227], v[192:195], v[68:71]
	v_mfma_f32_16x16x32_bf16 v[68:71], v[228:231], v[212:215], v[68:71]
	s_setprio 0
	s_mov_b32 m0, s24
	v_lshl_add_u64 v[232:233], s[16:17], 0, v[136:137]
	s_barrier
	ds_read_b128 v[168:171], v146 offset:16384
	ds_read_b128 v[172:175], v146 offset:17408
	ds_read_b128 v[176:179], v146 offset:18432
	ds_read_b128 v[180:183], v146 offset:19456
	ds_read_b128 v[184:187], v146 offset:20480
	ds_read_b128 v[188:191], v146 offset:21504
	ds_read_b128 v[192:195], v146 offset:22528
	ds_read_b128 v[212:215], v146 offset:23552
	global_load_lds_dwordx4 v[232:233], off
	v_lshl_add_u64 v[234:235], s[16:17], 0, v[132:133]
	s_mov_b32 m0, s25
	s_nop 0
	global_load_lds_dwordx4 v[234:235], off
	s_barrier
	s_waitcnt lgkmcnt(0)
	s_setprio 1
	s_waitcnt lgkmcnt(0)
	v_mfma_f32_16x16x32_bf16 v[64:67], v[148:151], v[168:171], v[64:67]
	v_mfma_f32_16x16x32_bf16 v[64:67], v[152:155], v[172:175], v[64:67]
	v_mfma_f32_16x16x32_bf16 v[56:59], v[148:151], v[176:179], v[56:59]
	v_mfma_f32_16x16x32_bf16 v[56:59], v[152:155], v[180:183], v[56:59]
	v_mfma_f32_16x16x32_bf16 v[40:43], v[148:151], v[184:187], v[40:43]
	v_mfma_f32_16x16x32_bf16 v[40:43], v[152:155], v[188:191], v[40:43]
	v_mfma_f32_16x16x32_bf16 v[24:27], v[148:151], v[192:195], v[24:27]
	v_mfma_f32_16x16x32_bf16 v[24:27], v[152:155], v[212:215], v[24:27]
	v_mfma_f32_16x16x32_bf16 v[60:63], v[156:159], v[168:171], v[60:63]
	v_mfma_f32_16x16x32_bf16 v[60:63], v[160:163], v[172:175], v[60:63]
	v_mfma_f32_16x16x32_bf16 v[48:51], v[156:159], v[176:179], v[48:51]
	v_mfma_f32_16x16x32_bf16 v[48:51], v[160:163], v[180:183], v[48:51]
	v_mfma_f32_16x16x32_bf16 v[32:35], v[156:159], v[184:187], v[32:35]
	v_mfma_f32_16x16x32_bf16 v[32:35], v[160:163], v[188:191], v[32:35]
	v_mfma_f32_16x16x32_bf16 v[16:19], v[156:159], v[192:195], v[16:19]
	v_mfma_f32_16x16x32_bf16 v[16:19], v[160:163], v[212:215], v[16:19]
	s_setprio 0
	s_barrier
; #define PG8_WAIT_V(n) asm volatile("s_waitcnt vmcnt(" #n ")" ::: "memory")
; #define PG8_WAIT_L(n) asm volatile("s_waitcnt lgkmcnt(" #n ")" ::: "memory")
; #define PG8_BAR __builtin_amdgcn_s_barrier()
; #define PG8_SCHED __builtin_amdgcn_sched_barrier(0)
; template <class Epi, class AddrA, class AddrB>
; __device__ __forceinline__ void gemm_phase(const Sched S, const int lda, const int ldb, const int K, const AddrA addrA,
;                                            const AddrB addrB, const Epi E) {
;     ...
;       PG8_WAIT_V(6); PG8_BAR; PG8_MMA(1, 1, At, B1); PG8_BAR;
;       PG8_LDB(B0, 1, 0); PG8_SCHED; PG8_LDA(At, 1, 0); PG8_STAGE(PG8_SA(0, 1), a2 + hstepA, voffA);
;       PG8_WAIT_L(8); PG8_BAR; PG8_WAIT_L(0); PG8_MMA(0, 0, At, B0); PG8_BAR; PG8_SCHED;
;       PG8_LDB(B1, 1, 1); PG8_STAGE(PG8_SB(1, 0), b3, voffB);
;       PG8_BAR; PG8_WAIT_L(0); PG8_MMA(0, 1, At, B1); PG8_BAR;
;       PG8_LDA(At, 1, 1); PG8_STAGE(PG8_SA(1, 0), a3, voffA);
;       PG8_BAR; PG8_WAIT_L(0); PG8_MMA(1, 0, At, B0); PG8_BAR; PG8_SCHED;
	s_add_u32 s40, s14, 0x80000
	s_addc_u32 s41, s15, 0
	s_add_i32 s42, s42, s19
	v_lshl_add_u64 v[148:149], s[40:41], 0, v[134:135]
	s_mov_b32 m0, s42
	s_nop 0
	global_load_lds_dwordx4 v[148:149], off
	v_lshl_add_u64 v[148:149], s[40:41], 0, v[0:1]
	s_add_i32 m0, s42, 0x2000
	s_nop 0
	global_load_lds_dwordx4 v[148:149], off
	s_waitcnt vmcnt(6)
	s_barrier
	s_setprio 1
	v_mfma_f32_16x16x32_bf16 v[52:55], v[216:219], v[168:171], v[52:55]
	v_mfma_f32_16x16x32_bf16 v[52:55], v[220:223], v[172:175], v[52:55]
	v_mfma_f32_16x16x32_bf16 v[36:39], v[216:219], v[176:179], v[36:39]
	v_mfma_f32_16x16x32_bf16 v[36:39], v[220:223], v[180:183], v[36:39]
	v_mfma_f32_16x16x32_bf16 v[20:23], v[216:219], v[184:187], v[20:23]
	v_mfma_f32_16x16x32_bf16 v[20:23], v[220:223], v[188:191], v[20:23]
	v_mfma_f32_16x16x32_bf16 v[8:11], v[216:219], v[192:195], v[8:11]
	v_mfma_f32_16x16x32_bf16 v[8:11], v[220:223], v[212:215], v[8:11]
	v_mfma_f32_16x16x32_bf16 v[44:47], v[224:227], v[168:171], v[44:47]
	v_mfma_f32_16x16x32_bf16 v[44:47], v[228:231], v[172:175], v[44:47]
	v_mfma_f32_16x16x32_bf16 v[28:31], v[224:227], v[176:179], v[28:31]
	v_mfma_f32_16x16x32_bf16 v[28:31], v[228:231], v[180:183], v[28:31]
	v_mfma_f32_16x16x32_bf16 v[12:15], v[224:227], v[184:187], v[12:15]
	v_mfma_f32_16x16x32_bf16 v[12:15], v[228:231], v[188:191], v[12:15]
	v_mfma_f32_16x16x32_bf16 v[4:7], v[224:227], v[192:195], v[4:7]
	v_mfma_f32_16x16x32_bf16 v[4:7], v[228:231], v[212:215], v[4:7]
	s_setprio 0
	s_add_i32 s40, 0, 0x18000
	v_add_u32_e32 v147, s40, v145
	s_barrier
	ds_read_b128 v[148:151], v147
	ds_read_b128 v[152:155], v147 offset:1024
	ds_read_b128 v[156:159], v147 offset:2048
	ds_read_b128 v[160:163], v147 offset:3072
	s_add_u32 s16, s16, 0x80000
	s_addc_u32 s17, s17, 0
	s_mov_b32 m0, s26
	v_lshl_add_u64 v[216:217], s[16:17], 0, v[136:137]
	ds_read_b128 v[168:171], v146 offset:32768
	ds_read_b128 v[172:175], v146 offset:33792
	ds_read_b128 v[176:179], v146 offset:34816
	ds_read_b128 v[180:183], v146 offset:35840
	ds_read_b128 v[184:187], v146 offset:36864
	ds_read_b128 v[188:191], v146 offset:37888
	ds_read_b128 v[192:195], v146 offset:38912
	ds_read_b128 v[212:215], v146 offset:39936
	global_load_lds_dwordx4 v[216:217], off
	v_lshl_add_u64 v[216:217], s[16:17], 0, v[132:133]
	s_mov_b32 m0, s27
	s_nop 0
	global_load_lds_dwordx4 v[216:217], off
	s_waitcnt lgkmcnt(8)
	s_barrier
	s_waitcnt lgkmcnt(0)
	s_setprio 1
	s_waitcnt lgkmcnt(0)
	v_mfma_f32_16x16x32_bf16 v[128:131], v[148:151], v[168:171], v[128:131]
	v_mfma_f32_16x16x32_bf16 v[128:131], v[152:155], v[172:175], v[128:131]
	v_mfma_f32_16x16x32_bf16 v[120:123], v[148:151], v[176:179], v[120:123]
	v_mfma_f32_16x16x32_bf16 v[120:123], v[152:155], v[180:183], v[120:123]
	v_mfma_f32_16x16x32_bf16 v[104:107], v[148:151], v[184:187], v[104:107]
	v_mfma_f32_16x16x32_bf16 v[104:107], v[152:155], v[188:191], v[104:107]
	v_mfma_f32_16x16x32_bf16 v[88:91], v[148:151], v[192:195], v[88:91]
	v_mfma_f32_16x16x32_bf16 v[88:91], v[152:155], v[212:215], v[88:91]
	v_mfma_f32_16x16x32_bf16 v[124:127], v[156:159], v[168:171], v[124:127]
	v_mfma_f32_16x16x32_bf16 v[124:127], v[160:163], v[172:175], v[124:127]
	v_mfma_f32_16x16x32_bf16 v[112:115], v[156:159], v[176:179], v[112:115]
	v_mfma_f32_16x16x32_bf16 v[112:115], v[160:163], v[180:183], v[112:115]
	v_mfma_f32_16x16x32_bf16 v[96:99], v[156:159], v[184:187], v[96:99]
	v_mfma_f32_16x16x32_bf16 v[96:99], v[160:163], v[188:191], v[96:99]
	v_mfma_f32_16x16x32_bf16 v[80:83], v[156:159], v[192:195], v[80:83]
	v_mfma_f32_16x16x32_bf16 v[80:83], v[160:163], v[212:215], v[80:83]
	s_setprio 0
	s_barrier
	s_add_i32 s16, 0, 0x1c000
	s_add_i32 s17, s40, s19
	v_add_u32_e32 v147, s16, v145
	v_lshl_add_u64 v[142:143], v[142:143], 0, s[52:53]
	s_mov_b32 m0, s17
	ds_read_b128 v[216:219], v147
	ds_read_b128 v[220:223], v147 offset:1024
	ds_read_b128 v[224:227], v147 offset:2048
	ds_read_b128 v[228:231], v147 offset:3072
	global_load_lds_dwordx4 v[142:143], off
	v_lshl_add_u64 v[142:143], v[196:197], 0, s[52:53]
	s_add_i32 m0, s17, 0x2000
	s_nop 0
	global_load_lds_dwordx4 v[142:143], off
	s_barrier
	s_waitcnt lgkmcnt(0)
	s_setprio 1
	s_waitcnt lgkmcnt(0)
	v_mfma_f32_16x16x32_bf16 v[116:119], v[216:219], v[168:171], v[116:119]
	v_mfma_f32_16x16x32_bf16 v[116:119], v[220:223], v[172:175], v[116:119]
	v_mfma_f32_16x16x32_bf16 v[100:103], v[216:219], v[176:179], v[100:103]
	v_mfma_f32_16x16x32_bf16 v[100:103], v[220:223], v[180:183], v[100:103]
	v_mfma_f32_16x16x32_bf16 v[84:87], v[216:219], v[184:187], v[84:87]
	v_mfma_f32_16x16x32_bf16 v[84:87], v[220:223], v[188:191], v[84:87]
	v_mfma_f32_16x16x32_bf16 v[72:75], v[216:219], v[192:195], v[72:75]
	v_mfma_f32_16x16x32_bf16 v[72:75], v[220:223], v[212:215], v[72:75]
	v_mfma_f32_16x16x32_bf16 v[108:111], v[224:227], v[168:171], v[108:111]
	v_mfma_f32_16x16x32_bf16 v[108:111], v[228:231], v[172:175], v[108:111]
	v_mfma_f32_16x16x32_bf16 v[92:95], v[224:227], v[176:179], v[92:95]
	v_mfma_f32_16x16x32_bf16 v[92:95], v[228:231], v[180:183], v[92:95]
	v_mfma_f32_16x16x32_bf16 v[76:79], v[224:227], v[184:187], v[76:79]
	v_mfma_f32_16x16x32_bf16 v[76:79], v[228:231], v[188:191], v[76:79]
	v_mfma_f32_16x16x32_bf16 v[68:71], v[224:227], v[192:195], v[68:71]
	v_mfma_f32_16x16x32_bf16 v[68:71], v[228:231], v[212:215], v[68:71]
	s_setprio 0
	s_mov_b32 m0, s30
	v_lshl_add_u64 v[142:143], v[232:233], 0, s[52:53]
	s_barrier
	ds_read_b128 v[168:171], v146 offset:49152
	ds_read_b128 v[172:175], v146 offset:50176
	ds_read_b128 v[176:179], v146 offset:51200
	ds_read_b128 v[180:183], v146 offset:52224
	ds_read_b128 v[184:187], v146 offset:53248
	ds_read_b128 v[188:191], v146 offset:54272
	ds_read_b128 v[192:195], v146 offset:55296
	ds_read_b128 v[212:215], v146 offset:56320
	global_load_lds_dwordx4 v[142:143], off
	v_lshl_add_u64 v[142:143], v[234:235], 0, s[52:53]
	s_mov_b32 m0, s31
	s_nop 0
	global_load_lds_dwordx4 v[142:143], off
	s_barrier
; #define PG8_WAIT_V(n) asm volatile("s_waitcnt vmcnt(" #n ")" ::: "memory")
; #define PG8_WAIT_L(n) asm volatile("s_waitcnt lgkmcnt(" #n ")" ::: "memory")
; #define PG8_BAR __builtin_amdgcn_s_barrier()
; #define PG8_SCHED __builtin_amdgcn_sched_barrier(0)
; template <class Epi, class AddrA, class AddrB>
; __device__ __forceinline__ void gemm_phase(const Sched S, const int lda, const int ldb, const int K, const AddrA addrA,
;                                            const AddrB addrB, const Epi E) {
;     ...
;       PG8_BAR; PG8_WAIT_L(0); PG8_MMA(1, 0, At, B0); PG8_BAR; PG8_SCHED;
;       PG8_STAGE(PG8_SB(1, 1), b3 + hstepB, voffB);
;       PG8_WAIT_V(6); PG8_BAR; PG8_MMA(1, 1, At, B1); PG8_BAR;
	s_waitcnt lgkmcnt(0)
	s_setprio 1
	s_waitcnt lgkmcnt(0)
	v_mfma_f32_16x16x32_bf16 v[64:67], v[148:151], v[168:171], v[64:67]
	v_mfma_f32_16x16x32_bf16 v[64:67], v[152:155], v[172:175], v[64:67]
	v_mfma_f32_16x16x32_bf16 v[56:59], v[148:151], v[176:179], v[56:59]
	v_mfma_f32_16x16x32_bf16 v[56:59], v[152:155], v[180:183], v[56:59]
	v_mfma_f32_16x16x32_bf16 v[40:43], v[148:151], v[184:187], v[40:43]
	v_mfma_f32_16x16x32_bf16 v[40:43], v[152:155], v[188:191], v[40:43]
	v_mfma_f32_16x16x32_bf16 v[24:27], v[148:151], v[192:195], v[24:27]
	v_mfma_f32_16x16x32_bf16 v[24:27], v[152:155], v[212:215], v[24:27]
	v_mfma_f32_16x16x32_bf16 v[60:63], v[156:159], v[168:171], v[60:63]
	v_mfma_f32_16x16x32_bf16 v[60:63], v[160:163], v[172:175], v[60:63]
	v_mfma_f32_16x16x32_bf16 v[48:51], v[156:159], v[176:179], v[48:51]
	v_mfma_f32_16x16x32_bf16 v[48:51], v[160:163], v[180:183], v[48:51]
	v_mfma_f32_16x16x32_bf16 v[32:35], v[156:159], v[184:187], v[32:35]
	v_mfma_f32_16x16x32_bf16 v[32:35], v[160:163], v[188:191], v[32:35]
	v_mfma_f32_16x16x32_bf16 v[16:19], v[156:159], v[192:195], v[16:19]
	v_mfma_f32_16x16x32_bf16 v[16:19], v[160:163], v[212:215], v[16:19]
	s_setprio 0
	s_barrier
	s_add_u32 s14, s14, 0x80080
	s_addc_u32 s15, s15, 0
	s_add_i32 s16, s16, s19
	v_lshl_add_u64 v[142:143], s[14:15], 0, v[134:135]
	s_mov_b32 m0, s16
	s_nop 0
	global_load_lds_dwordx4 v[142:143], off
	v_lshl_add_u64 v[142:143], s[14:15], 0, v[0:1]
	s_add_i32 m0, s16, 0x2000
	s_nop 0
	global_load_lds_dwordx4 v[142:143], off
	s_waitcnt vmcnt(6)
	s_barrier
	s_setprio 1
	v_mfma_f32_16x16x32_bf16 v[52:55], v[216:219], v[168:171], v[52:55]
	v_mfma_f32_16x16x32_bf16 v[52:55], v[220:223], v[172:175], v[52:55]
	v_mfma_f32_16x16x32_bf16 v[36:39], v[216:219], v[176:179], v[36:39]
	v_mfma_f32_16x16x32_bf16 v[36:39], v[220:223], v[180:183], v[36:39]
	v_mfma_f32_16x16x32_bf16 v[20:23], v[216:219], v[184:187], v[20:23]
	v_mfma_f32_16x16x32_bf16 v[20:23], v[220:223], v[188:191], v[20:23]
	v_mfma_f32_16x16x32_bf16 v[8:11], v[216:219], v[192:195], v[8:11]
	v_mfma_f32_16x16x32_bf16 v[8:11], v[220:223], v[212:215], v[8:11]
	v_mfma_f32_16x16x32_bf16 v[44:47], v[224:227], v[168:171], v[44:47]
	v_mfma_f32_16x16x32_bf16 v[44:47], v[228:231], v[172:175], v[44:47]
	v_mfma_f32_16x16x32_bf16 v[28:31], v[224:227], v[176:179], v[28:31]
	v_mfma_f32_16x16x32_bf16 v[28:31], v[228:231], v[180:183], v[28:31]
	v_mfma_f32_16x16x32_bf16 v[12:15], v[224:227], v[184:187], v[12:15]
	v_mfma_f32_16x16x32_bf16 v[12:15], v[228:231], v[188:191], v[12:15]
	v_mfma_f32_16x16x32_bf16 v[4:7], v[224:227], v[192:195], v[4:7]
	v_mfma_f32_16x16x32_bf16 v[4:7], v[228:231], v[212:215], v[4:7]
	s_setprio 0
	s_add_i32 s39, s39, 2
	s_add_u32 s37, s37, 0x100
	s_addc_u32 s38, s38, 0
	s_add_u32 s12, s12, 0x100
	s_addc_u32 s13, s13, 0
	s_cmp_gt_u32 s39, 29
	s_barrier
	s_cbranch_scc0 .LBB0_109
; template <class Epi, class AddrA, class AddrB>
; __device__ __forceinline__ void gemm_phase(const Sched S, const int lda, const int ldb, const int K, const AddrA addrA,
;                                            const AddrB addrB, const Epi E) {
;     ...
;     E(acc, cur, wr, wc, fr, fq);
;     if (!has_next) break;
;     if (!(Epi::KEEP && cur.br + 1 < S.nbr)) {
; #pragma unroll
;       for (int a = 0; a < 2; ++a)
; #pragma unroll
;         for (int b = 0; b < 2; ++b)
; #pragma unroll
;           for (int m = 0; m < 4; ++m)
; #pragma unroll
;             for (int n = 0; n < 2; ++n) acc[a][b][m][n] = (f32x4){0.f, 0.f, 0.f, 0.f};
;     }
;     cur = nxt; cA = nA; cB = nB; ++ui;
;   __device__ __forceinline__ void operator()(EPI_ARGS) const {
;     bf16_t* base = proj + ((size_t)u.pn * MTOK + (size_t)(u.pm * 256 + wr * 64 + fr)) * PLD + wc * 32 + 8 * fq;
; #pragma unroll
;     for (int ai = 0; ai < 2; ++ai)
; #pragma unroll
;       for (int m = 0; m < 4; ++m) {
;         bf16_t* rowp = base + (size_t)(ai * HALF + m * 16) * PLD;
; #pragma unroll
;         for (int bj = 0; bj < 2; ++bj) {
;           const f32x4 v0 = acc[ai][bj][m][0], v1 = acc[ai][bj][m][1];
;           u32x4 o;
;           o.x = pack2(v0[0], v0[1]); o.y = pack2(v0[2], v0[3]); o.z = pack2(v1[0], v1[1]); o.w = pack2(v1[2], v1[3]);
;           *(u32x4*)(rowp + bj * HALF) = o;
;         }
;       }
	s_ashr_i32 s11, s10, 31
	v_lshl_add_u32 v142, s35, 8, v144
	s_lshl_b64 s[10:11], s[10:11], 23
	v_ashrrev_i32_e32 v143, 31, v142
	s_add_u32 s10, s28, s10
	s_addc_u32 s11, s29, s11
	v_lshlrev_b64 v[142:143], 9, v[142:143]
	v_lshl_add_u64 v[142:143], s[10:11], 0, v[142:143]
	v_lshl_add_u64 v[142:143], v[142:143], 0, s[72:73]
	v_lshl_add_u64 v[142:143], v[142:143], 0, v[2:3]
	v_cvt_pk_bf16_f32 v116, v116, v117
	v_cvt_pk_bf16_f32 v117, v118, v119
	v_cvt_pk_bf16_f32 v119, v110, v111
	v_cvt_pk_bf16_f32 v110, v112, v113
	v_add_co_u32_e32 v112, vcc, s96, v142
	s_movk_i32 s1, 0x4000
	s_nop 0
	v_addc_co_u32_e32 v113, vcc, 0, v143, vcc
	v_cvt_pk_bf16_f32 v100, v100, v101
	v_cvt_pk_bf16_f32 v101, v102, v103
	v_cvt_pk_bf16_f32 v103, v94, v95
	v_cvt_pk_bf16_f32 v94, v96, v97
	v_add_co_u32_e32 v96, vcc, s1, v142
	s_movk_i32 s1, 0x6000
	s_nop 0
	v_addc_co_u32_e32 v97, vcc, 0, v143, vcc
	v_cvt_pk_bf16_f32 v84, v84, v85
	v_cvt_pk_bf16_f32 v85, v86, v87
	v_cvt_pk_bf16_f32 v87, v78, v79
	v_cvt_pk_bf16_f32 v78, v80, v81
	v_add_co_u32_e32 v80, vcc, s1, v142
	v_cvt_pk_bf16_f32 v64, v64, v65
	v_cvt_pk_bf16_f32 v65, v66, v67
	v_cvt_pk_bf16_f32 v66, v60, v61
	s_mov_b32 s1, 0x12000
	s_nop 0
	v_addc_co_u32_e32 v81, vcc, 0, v143, vcc
	v_add_co_u32_e32 v60, vcc, s67, v142
	v_cvt_pk_bf16_f32 v52, v52, v53
	v_cvt_pk_bf16_f32 v53, v54, v55
	v_cvt_pk_bf16_f32 v55, v46, v47
	v_cvt_pk_bf16_f32 v46, v48, v49
	s_nop 1
	v_addc_co_u32_e32 v61, vcc, 0, v143, vcc
	v_add_co_u32_e32 v48, vcc, s1, v142
	s_mov_b32 s1, 0x14000
	s_nop 0
	v_addc_co_u32_e32 v49, vcc, 0, v143, vcc
	v_cvt_pk_bf16_f32 v36, v36, v37
	v_cvt_pk_bf16_f32 v37, v38, v39
	v_cvt_pk_bf16_f32 v39, v30, v31
	v_cvt_pk_bf16_f32 v30, v32, v33
	v_add_co_u32_e32 v32, vcc, s1, v142
	s_mov_b32 s1, 0x16000
	s_nop 0
	v_addc_co_u32_e32 v33, vcc, 0, v143, vcc
	v_cvt_pk_bf16_f32 v20, v20, v21
	v_cvt_pk_bf16_f32 v21, v22, v23
	v_cvt_pk_bf16_f32 v23, v14, v15
	v_cvt_pk_bf16_f32 v14, v16, v17
	v_add_co_u32_e32 v16, vcc, s1, v142
	s_mov_b32 s10, s2
	s_nop 0
	v_addc_co_u32_e32 v17, vcc, 0, v143, vcc
	s_and_b64 vcc, exec, s[4:5]
	s_mov_b32 s35, s0
	s_mov_b64 s[12:13], s[8:9]
	s_mov_b64 s[14:15], s[6:7]
	v_cvt_pk_bf16_f32 v128, v128, v129
	v_cvt_pk_bf16_f32 v129, v130, v131
	v_cvt_pk_bf16_f32 v130, v124, v125
	v_cvt_pk_bf16_f32 v131, v126, v127
	flat_store_dwordx4 v[142:143], v[128:131]
	v_cvt_pk_bf16_f32 v118, v108, v109
	flat_store_dwordx4 v[142:143], v[116:119] offset:256
	v_cvt_pk_bf16_f32 v108, v120, v121
	v_cvt_pk_bf16_f32 v109, v122, v123
	v_cvt_pk_bf16_f32 v111, v114, v115
	flat_store_dwordx4 v[112:113], v[108:111]
	v_cvt_pk_bf16_f32 v102, v92, v93
	flat_store_dwordx4 v[112:113], v[100:103] offset:256
	v_cvt_pk_bf16_f32 v92, v104, v105
	v_cvt_pk_bf16_f32 v93, v106, v107
	v_cvt_pk_bf16_f32 v95, v98, v99
	flat_store_dwordx4 v[96:97], v[92:95]
	v_cvt_pk_bf16_f32 v86, v76, v77
	flat_store_dwordx4 v[96:97], v[84:87] offset:256
	v_cvt_pk_bf16_f32 v76, v88, v89
	v_cvt_pk_bf16_f32 v77, v90, v91
	v_cvt_pk_bf16_f32 v79, v82, v83
	flat_store_dwordx4 v[80:81], v[76:79]
	v_cvt_pk_bf16_f32 v72, v72, v73
	v_cvt_pk_bf16_f32 v73, v74, v75
	v_cvt_pk_bf16_f32 v74, v68, v69
	v_cvt_pk_bf16_f32 v75, v70, v71
	flat_store_dwordx4 v[80:81], v[72:75] offset:256
	v_cvt_pk_bf16_f32 v67, v62, v63
	flat_store_dwordx4 v[60:61], v[64:67]
	v_cvt_pk_bf16_f32 v54, v44, v45
	flat_store_dwordx4 v[60:61], v[52:55] offset:256
	v_cvt_pk_bf16_f32 v44, v56, v57
	v_cvt_pk_bf16_f32 v45, v58, v59
	v_cvt_pk_bf16_f32 v47, v50, v51
	flat_store_dwordx4 v[48:49], v[44:47]
	v_cvt_pk_bf16_f32 v38, v28, v29
	flat_store_dwordx4 v[48:49], v[36:39] offset:256
	v_cvt_pk_bf16_f32 v28, v40, v41
	v_cvt_pk_bf16_f32 v29, v42, v43
	v_cvt_pk_bf16_f32 v31, v34, v35
	flat_store_dwordx4 v[32:33], v[28:31]
	v_cvt_pk_bf16_f32 v22, v12, v13
	flat_store_dwordx4 v[32:33], v[20:23] offset:256
	v_cvt_pk_bf16_f32 v12, v24, v25
	v_cvt_pk_bf16_f32 v13, v26, v27
	v_cvt_pk_bf16_f32 v15, v18, v19
	flat_store_dwordx4 v[16:17], v[12:15]
	v_cvt_pk_bf16_f32 v8, v8, v9
	v_cvt_pk_bf16_f32 v9, v10, v11
	v_cvt_pk_bf16_f32 v10, v4, v5
	v_cvt_pk_bf16_f32 v11, v6, v7
	flat_store_dwordx4 v[16:17], v[8:11] offset:256
	s_cbranch_vccz .LBB0_106
	s_waitcnt vmcnt(0)
	s_cmpk_gt_u32 s18, 0xff
	s_cbranch_scc1 .LBB0_113
	s_barrier

; #define PG8_WAIT_V(n) asm volatile("s_waitcnt vmcnt(" #n ")" ::: "memory")
; #define PG8_WAIT_L(n) asm volatile("s_waitcnt lgkmcnt(" #n ")" ::: "memory")
; #define PG8_BAR __builtin_amdgcn_s_barrier()
; #define PG8_SCHED __builtin_amdgcn_sched_barrier(0)
; template <class Epi, class AddrA, class AddrB>
; __device__ __forceinline__ void gemm_phase(const Sched S, const int lda, const int ldb, const int K, const AddrA addrA,
;                                            const AddrB addrB, const Epi E) {
;     ...
;     for (int t = 0; t < nt; t += 2) {
;       const bool last = (t == nt - 2);
;       const char* a1 = cA + (size_t)(t + 1) * kstep;
;       const char* a2 = last ? nA : cA + (size_t)(t + 2) * kstep;
;       const char* b2 = last ? nB : cB + (size_t)(t + 2) * kstep;
;       const char* a3 = a2 + kstep;
;       const char* b3 = b2 + kstep;
;       PG8_LDB(B0, 0, 0); PG8_SCHED; PG8_LDA(At, 0, 0); PG8_STAGE(PG8_SA(1, 1), a1 + hstepA, voffA);
;       PG8_WAIT_L(8); PG8_BAR; PG8_WAIT_L(0); PG8_MMA(0, 0, At, B0); PG8_BAR; PG8_SCHED;
;       PG8_LDB(B1, 0, 1); PG8_STAGE(PG8_SB(0, 0), b2, voffB);
;       PG8_BAR; PG8_WAIT_L(0); PG8_MMA(0, 1, At, B1); PG8_BAR;
;       PG8_LDA(At, 0, 1); PG8_STAGE(PG8_SA(0, 0), a2, voffA);
;       PG8_BAR; PG8_WAIT_L(0); PG8_MMA(1, 0, At, B0); PG8_BAR; PG8_SCHED;
;       PG8_STAGE(PG8_SB(0, 1), b2 + hstepB, voffB);
;       PG8_WAIT_V(6); PG8_BAR; PG8_MMA(1, 1, At, B1); PG8_BAR;
.LBB0_485:
	s_add_u32 s6, s4, 0xfff80080
	s_addc_u32 s7, s5, -1
	s_add_i32 s44, 0, 0x10000
	v_add_u32_e32 v2, s44, v167
	ds_read_b128 v[92:95], v2
	ds_read_b128 v[100:103], v2 offset:1024
	ds_read_b128 v[132:135], v2 offset:2048
	ds_read_b128 v[144:147], v2 offset:3072
	s_cmp_eq_u32 s43, 4
	s_cselect_b32 s11, s3, s7
	s_cselect_b32 s10, s15, s6
	s_cselect_b32 s7, s17, s42
	s_cselect_b32 s6, s40, s41
	v_lshl_add_u64 v[196:197], s[4:5], 0, v[172:173]
	s_add_i32 m0, s30, 0xc000
	ds_read_b128 v[148:151], v169
	ds_read_b128 v[152:155], v169 offset:1024
	ds_read_b128 v[176:179], v169 offset:2048
	ds_read_b128 v[180:183], v169 offset:3072
	ds_read_b128 v[184:187], v169 offset:4096
	ds_read_b128 v[188:191], v169 offset:5120
	ds_read_b128 v[192:195], v169 offset:6144
	ds_read_b128 v[212:215], v169 offset:7168
	global_load_lds_dwordx4 v[196:197], off
	v_lshl_add_u64 v[196:197], s[4:5], 0, v[170:171]
	s_add_i32 m0, s30, 0xe000
	s_nop 0
	global_load_lds_dwordx4 v[196:197], off
	s_waitcnt lgkmcnt(8)
	s_barrier
	s_waitcnt lgkmcnt(0)
	s_setprio 1
	s_waitcnt lgkmcnt(0)
	v_mfma_f32_16x16x32_bf16 v[140:143], v[92:95], v[148:151], v[140:143]
	v_mfma_f32_16x16x32_bf16 v[140:143], v[100:103], v[152:155], v[140:143]
	v_mfma_f32_16x16x32_bf16 v[128:131], v[92:95], v[176:179], v[128:131]
	v_mfma_f32_16x16x32_bf16 v[128:131], v[100:103], v[180:183], v[128:131]
	v_mfma_f32_16x16x32_bf16 v[120:123], v[92:95], v[184:187], v[120:123]
	v_mfma_f32_16x16x32_bf16 v[120:123], v[100:103], v[188:191], v[120:123]
	v_mfma_f32_16x16x32_bf16 v[112:115], v[92:95], v[192:195], v[112:115]
	v_mfma_f32_16x16x32_bf16 v[112:115], v[100:103], v[212:215], v[112:115]
	v_mfma_f32_16x16x32_bf16 v[136:139], v[132:135], v[148:151], v[136:139]
	v_mfma_f32_16x16x32_bf16 v[136:139], v[144:147], v[152:155], v[136:139]
	v_mfma_f32_16x16x32_bf16 v[124:127], v[132:135], v[176:179], v[124:127]
	v_mfma_f32_16x16x32_bf16 v[124:127], v[144:147], v[180:183], v[124:127]
	v_mfma_f32_16x16x32_bf16 v[116:119], v[132:135], v[184:187], v[116:119]
	v_mfma_f32_16x16x32_bf16 v[116:119], v[144:147], v[188:191], v[116:119]
	v_mfma_f32_16x16x32_bf16 v[108:111], v[132:135], v[192:195], v[108:111]
	v_mfma_f32_16x16x32_bf16 v[108:111], v[144:147], v[212:215], v[108:111]
	s_setprio 0
	s_barrier
	s_add_i32 s46, 0, 0x14000
	s_add_i32 s44, s44, s29
	v_add_u32_e32 v2, s46, v167
	v_lshl_add_u64 v[196:197], s[6:7], 0, v[158:159]
	s_mov_b32 m0, s44
	ds_read_b128 v[216:219], v2
	ds_read_b128 v[220:223], v2 offset:1024
	ds_read_b128 v[224:227], v2 offset:2048
	ds_read_b128 v[228:231], v2 offset:3072
	global_load_lds_dwordx4 v[196:197], off
	v_lshl_add_u64 v[232:233], s[6:7], 0, v[0:1]
	s_add_i32 m0, s44, 0x2000
	s_nop 0
	global_load_lds_dwordx4 v[232:233], off
	s_barrier
	s_waitcnt lgkmcnt(0)
	s_setprio 1
	s_waitcnt lgkmcnt(0)
	v_mfma_f32_16x16x32_bf16 v[64:67], v[216:219], v[148:151], v[64:67]
	v_mfma_f32_16x16x32_bf16 v[64:67], v[220:223], v[152:155], v[64:67]
	v_mfma_f32_16x16x32_bf16 v[56:59], v[216:219], v[176:179], v[56:59]
	v_mfma_f32_16x16x32_bf16 v[56:59], v[220:223], v[180:183], v[56:59]
	v_mfma_f32_16x16x32_bf16 v[48:51], v[216:219], v[184:187], v[48:51]
	v_mfma_f32_16x16x32_bf16 v[48:51], v[220:223], v[188:191], v[48:51]
	v_mfma_f32_16x16x32_bf16 v[40:43], v[216:219], v[192:195], v[40:43]
	v_mfma_f32_16x16x32_bf16 v[40:43], v[220:223], v[212:215], v[40:43]
	v_mfma_f32_16x16x32_bf16 v[60:63], v[224:227], v[148:151], v[60:63]
	v_mfma_f32_16x16x32_bf16 v[60:63], v[228:231], v[152:155], v[60:63]
	v_mfma_f32_16x16x32_bf16 v[52:55], v[224:227], v[176:179], v[52:55]
	v_mfma_f32_16x16x32_bf16 v[52:55], v[228:231], v[180:183], v[52:55]
	v_mfma_f32_16x16x32_bf16 v[44:47], v[224:227], v[184:187], v[44:47]
	v_mfma_f32_16x16x32_bf16 v[44:47], v[228:231], v[188:191], v[44:47]
	v_mfma_f32_16x16x32_bf16 v[36:39], v[224:227], v[192:195], v[36:39]
	v_mfma_f32_16x16x32_bf16 v[36:39], v[228:231], v[212:215], v[36:39]
	s_setprio 0
	s_mov_b32 m0, s30
	v_lshl_add_u64 v[234:235], s[10:11], 0, v[160:161]
	s_barrier
	ds_read_b128 v[148:151], v169 offset:16384
	ds_read_b128 v[152:155], v169 offset:17408
	ds_read_b128 v[176:179], v169 offset:18432
	ds_read_b128 v[180:183], v169 offset:19456
	ds_read_b128 v[184:187], v169 offset:20480
	ds_read_b128 v[188:191], v169 offset:21504
	ds_read_b128 v[192:195], v169 offset:22528
	ds_read_b128 v[212:215], v169 offset:23552
	global_load_lds_dwordx4 v[234:235], off
	v_lshl_add_u64 v[236:237], s[10:11], 0, v[156:157]
	s_mov_b32 m0, s31
	s_nop 0
	global_load_lds_dwordx4 v[236:237], off
	s_barrier
	s_waitcnt lgkmcnt(0)
	s_setprio 1
	s_waitcnt lgkmcnt(0)
	v_mfma_f32_16x16x32_bf16 v[104:107], v[92:95], v[148:151], v[104:107]
	v_mfma_f32_16x16x32_bf16 v[104:107], v[100:103], v[152:155], v[104:107]
	v_mfma_f32_16x16x32_bf16 v[88:91], v[92:95], v[176:179], v[88:91]
	v_mfma_f32_16x16x32_bf16 v[88:91], v[100:103], v[180:183], v[88:91]
	v_mfma_f32_16x16x32_bf16 v[80:83], v[92:95], v[184:187], v[80:83]
	v_mfma_f32_16x16x32_bf16 v[80:83], v[100:103], v[188:191], v[80:83]
	v_mfma_f32_16x16x32_bf16 v[72:75], v[92:95], v[192:195], v[72:75]
	v_mfma_f32_16x16x32_bf16 v[72:75], v[100:103], v[212:215], v[72:75]
	v_mfma_f32_16x16x32_bf16 v[96:99], v[132:135], v[148:151], v[96:99]
	v_mfma_f32_16x16x32_bf16 v[96:99], v[144:147], v[152:155], v[96:99]
	v_mfma_f32_16x16x32_bf16 v[84:87], v[132:135], v[176:179], v[84:87]
	v_mfma_f32_16x16x32_bf16 v[84:87], v[144:147], v[180:183], v[84:87]
	v_mfma_f32_16x16x32_bf16 v[76:79], v[132:135], v[184:187], v[76:79]
	v_mfma_f32_16x16x32_bf16 v[76:79], v[144:147], v[188:191], v[76:79]
	v_mfma_f32_16x16x32_bf16 v[68:71], v[132:135], v[192:195], v[68:71]
	v_mfma_f32_16x16x32_bf16 v[68:71], v[144:147], v[212:215], v[68:71]
	s_setprio 0
	s_barrier
; #define PG8_WAIT_V(n) asm volatile("s_waitcnt vmcnt(" #n ")" ::: "memory")
; #define PG8_WAIT_L(n) asm volatile("s_waitcnt lgkmcnt(" #n ")" ::: "memory")
; #define PG8_BAR __builtin_amdgcn_s_barrier()
; #define PG8_SCHED __builtin_amdgcn_sched_barrier(0)
; template <class Epi, class AddrA, class AddrB>
; __device__ __forceinline__ void gemm_phase(const Sched S, const int lda, const int ldb, const int K, const AddrA addrA,
;                                            const AddrB addrB, const Epi E) {
;     ...
;       PG8_WAIT_V(6); PG8_BAR; PG8_MMA(1, 1, At, B1); PG8_BAR;
;       PG8_LDB(B0, 1, 0); PG8_SCHED; PG8_LDA(At, 1, 0); PG8_STAGE(PG8_SA(0, 1), a2 + hstepA, voffA);
;       PG8_WAIT_L(8); PG8_BAR; PG8_WAIT_L(0); PG8_MMA(0, 0, At, B0); PG8_BAR; PG8_SCHED;
;       PG8_LDB(B1, 1, 1); PG8_STAGE(PG8_SB(1, 0), b3, voffB);
;       PG8_BAR; PG8_WAIT_L(0); PG8_MMA(0, 1, At, B1); PG8_BAR;
;       PG8_LDA(At, 1, 1); PG8_STAGE(PG8_SA(1, 0), a3, voffA);
;       PG8_BAR; PG8_WAIT_L(0); PG8_MMA(1, 0, At, B0); PG8_BAR; PG8_SCHED;
	s_add_u32 s44, s6, 0x20000
	s_addc_u32 s45, s7, 0
	s_add_i32 s46, s46, s29
	v_lshl_add_u64 v[92:93], s[44:45], 0, v[158:159]
	s_mov_b32 m0, s46
	s_nop 0
	global_load_lds_dwordx4 v[92:93], off
	v_lshl_add_u64 v[92:93], s[44:45], 0, v[0:1]
	s_add_i32 m0, s46, 0x2000
	s_nop 0
	global_load_lds_dwordx4 v[92:93], off
	s_waitcnt vmcnt(6)
	s_barrier
	s_setprio 1
	v_mfma_f32_16x16x32_bf16 v[32:35], v[216:219], v[148:151], v[32:35]
	v_mfma_f32_16x16x32_bf16 v[32:35], v[220:223], v[152:155], v[32:35]
	v_mfma_f32_16x16x32_bf16 v[24:27], v[216:219], v[176:179], v[24:27]
	v_mfma_f32_16x16x32_bf16 v[24:27], v[220:223], v[180:183], v[24:27]
	v_mfma_f32_16x16x32_bf16 v[16:19], v[216:219], v[184:187], v[16:19]
	v_mfma_f32_16x16x32_bf16 v[16:19], v[220:223], v[188:191], v[16:19]
	v_mfma_f32_16x16x32_bf16 v[8:11], v[216:219], v[192:195], v[8:11]
	v_mfma_f32_16x16x32_bf16 v[8:11], v[220:223], v[212:215], v[8:11]
	v_mfma_f32_16x16x32_bf16 v[28:31], v[224:227], v[148:151], v[28:31]
	v_mfma_f32_16x16x32_bf16 v[28:31], v[228:231], v[152:155], v[28:31]
	v_mfma_f32_16x16x32_bf16 v[20:23], v[224:227], v[176:179], v[20:23]
	v_mfma_f32_16x16x32_bf16 v[20:23], v[228:231], v[180:183], v[20:23]
	v_mfma_f32_16x16x32_bf16 v[12:15], v[224:227], v[184:187], v[12:15]
	v_mfma_f32_16x16x32_bf16 v[12:15], v[228:231], v[188:191], v[12:15]
	v_mfma_f32_16x16x32_bf16 v[4:7], v[224:227], v[192:195], v[4:7]
	v_mfma_f32_16x16x32_bf16 v[4:7], v[228:231], v[212:215], v[4:7]
	s_setprio 0
	s_add_i32 s44, 0, 0x18000
	v_add_u32_e32 v2, s44, v167
	s_barrier
	ds_read_b128 v[92:95], v2
	ds_read_b128 v[100:103], v2 offset:1024
	ds_read_b128 v[132:135], v2 offset:2048
	ds_read_b128 v[144:147], v2 offset:3072
	s_add_u32 s10, s10, 0x80000
	s_addc_u32 s11, s11, 0
	s_mov_b32 m0, s34
	v_lshl_add_u64 v[216:217], s[10:11], 0, v[160:161]
	ds_read_b128 v[148:151], v169 offset:32768
	ds_read_b128 v[152:155], v169 offset:33792
	ds_read_b128 v[176:179], v169 offset:34816
	ds_read_b128 v[180:183], v169 offset:35840
	ds_read_b128 v[184:187], v169 offset:36864
	ds_read_b128 v[188:191], v169 offset:37888
	ds_read_b128 v[192:195], v169 offset:38912
	ds_read_b128 v[212:215], v169 offset:39936
	global_load_lds_dwordx4 v[216:217], off
	v_lshl_add_u64 v[216:217], s[10:11], 0, v[156:157]
	s_mov_b32 m0, s35
	s_nop 0
	global_load_lds_dwordx4 v[216:217], off
	s_waitcnt lgkmcnt(8)
	s_barrier
	s_waitcnt lgkmcnt(0)
	s_setprio 1
	s_waitcnt lgkmcnt(0)
	v_mfma_f32_16x16x32_bf16 v[140:143], v[92:95], v[148:151], v[140:143]
	v_mfma_f32_16x16x32_bf16 v[140:143], v[100:103], v[152:155], v[140:143]
	v_mfma_f32_16x16x32_bf16 v[128:131], v[92:95], v[176:179], v[128:131]
	v_mfma_f32_16x16x32_bf16 v[128:131], v[100:103], v[180:183], v[128:131]
	v_mfma_f32_16x16x32_bf16 v[120:123], v[92:95], v[184:187], v[120:123]
	v_mfma_f32_16x16x32_bf16 v[120:123], v[100:103], v[188:191], v[120:123]
	v_mfma_f32_16x16x32_bf16 v[112:115], v[92:95], v[192:195], v[112:115]
	v_mfma_f32_16x16x32_bf16 v[112:115], v[100:103], v[212:215], v[112:115]
	v_mfma_f32_16x16x32_bf16 v[136:139], v[132:135], v[148:151], v[136:139]
	v_mfma_f32_16x16x32_bf16 v[136:139], v[144:147], v[152:155], v[136:139]
	v_mfma_f32_16x16x32_bf16 v[124:127], v[132:135], v[176:179], v[124:127]
	v_mfma_f32_16x16x32_bf16 v[124:127], v[144:147], v[180:183], v[124:127]
	v_mfma_f32_16x16x32_bf16 v[116:119], v[132:135], v[184:187], v[116:119]
	v_mfma_f32_16x16x32_bf16 v[116:119], v[144:147], v[188:191], v[116:119]
	v_mfma_f32_16x16x32_bf16 v[108:111], v[132:135], v[192:195], v[108:111]
	v_mfma_f32_16x16x32_bf16 v[108:111], v[144:147], v[212:215], v[108:111]
	s_setprio 0
	s_barrier
	s_add_i32 s10, 0, 0x1c000
	s_add_i32 s11, s44, s29
	v_add_u32_e32 v2, s10, v167
	v_lshl_add_u64 v[196:197], v[196:197], 0, s[52:53]
	s_mov_b32 m0, s11
	ds_read_b128 v[216:219], v2
	ds_read_b128 v[220:223], v2 offset:1024
	ds_read_b128 v[224:227], v2 offset:2048
	ds_read_b128 v[228:231], v2 offset:3072
	global_load_lds_dwordx4 v[196:197], off
	v_lshl_add_u64 v[196:197], v[232:233], 0, s[52:53]
	s_add_i32 m0, s11, 0x2000
	s_nop 0
	global_load_lds_dwordx4 v[196:197], off
	s_barrier
	s_waitcnt lgkmcnt(0)
	s_setprio 1
	s_waitcnt lgkmcnt(0)
	v_mfma_f32_16x16x32_bf16 v[64:67], v[216:219], v[148:151], v[64:67]
	v_mfma_f32_16x16x32_bf16 v[64:67], v[220:223], v[152:155], v[64:67]
	v_mfma_f32_16x16x32_bf16 v[56:59], v[216:219], v[176:179], v[56:59]
	v_mfma_f32_16x16x32_bf16 v[56:59], v[220:223], v[180:183], v[56:59]
	v_mfma_f32_16x16x32_bf16 v[48:51], v[216:219], v[184:187], v[48:51]
	v_mfma_f32_16x16x32_bf16 v[48:51], v[220:223], v[188:191], v[48:51]
	v_mfma_f32_16x16x32_bf16 v[40:43], v[216:219], v[192:195], v[40:43]
	v_mfma_f32_16x16x32_bf16 v[40:43], v[220:223], v[212:215], v[40:43]
	v_mfma_f32_16x16x32_bf16 v[60:63], v[224:227], v[148:151], v[60:63]
	v_mfma_f32_16x16x32_bf16 v[60:63], v[228:231], v[152:155], v[60:63]
	v_mfma_f32_16x16x32_bf16 v[52:55], v[224:227], v[176:179], v[52:55]
	v_mfma_f32_16x16x32_bf16 v[52:55], v[228:231], v[180:183], v[52:55]
	v_mfma_f32_16x16x32_bf16 v[44:47], v[224:227], v[184:187], v[44:47]
	v_mfma_f32_16x16x32_bf16 v[44:47], v[228:231], v[188:191], v[44:47]
	v_mfma_f32_16x16x32_bf16 v[36:39], v[224:227], v[192:195], v[36:39]
	v_mfma_f32_16x16x32_bf16 v[36:39], v[228:231], v[212:215], v[36:39]
	s_setprio 0
	s_mov_b32 m0, s37
	v_lshl_add_u64 v[196:197], v[234:235], 0, s[52:53]
	s_barrier
	ds_read_b128 v[148:151], v169 offset:49152
	ds_read_b128 v[152:155], v169 offset:50176
	ds_read_b128 v[176:179], v169 offset:51200
	ds_read_b128 v[180:183], v169 offset:52224
	ds_read_b128 v[184:187], v169 offset:53248
	ds_read_b128 v[188:191], v169 offset:54272
	ds_read_b128 v[192:195], v169 offset:55296
	ds_read_b128 v[212:215], v169 offset:56320
	global_load_lds_dwordx4 v[196:197], off
	v_lshl_add_u64 v[196:197], v[236:237], 0, s[52:53]
	s_mov_b32 m0, s38
	s_nop 0
	global_load_lds_dwordx4 v[196:197], off
	s_barrier
; __device__ __forceinline__ size_t pidx(size_t row, int col) { return ((size_t)(col >> 8) * MTOK + row) * PLD + (col & 255); }
; __device__ __forceinline__ float bflo(unsigned v) { return __uint_as_float(v << 16); }
; __device__ __forceinline__ float bfhi(unsigned v) { return __uint_as_float(v & 0xffff0000u); }
; __device__ __forceinline__ float siluf_(float x) { return x * __builtin_amdgcn_rcpf(1.0f + __expf(-x)); }
; #define PG8_WAIT_V(n) asm volatile("s_waitcnt vmcnt(" #n ")" ::: "memory")
; #define PG8_WAIT_L(n) asm volatile("s_waitcnt lgkmcnt(" #n ")" ::: "memory")
; #define PG8_BAR __builtin_amdgcn_s_barrier()
; template <class Epi, class AddrA, class AddrB>
; __device__ __forceinline__ void gemm_phase(const Sched S, const int lda, const int ldb, const int K, const AddrA addrA,
;                                            const AddrB addrB, const Epi E) {
;     ...
;       PG8_BAR; PG8_WAIT_L(0); PG8_MMA(1, 0, At, B0); PG8_BAR; PG8_SCHED;
;       PG8_STAGE(PG8_SB(1, 1), b3 + hstepB, voffB);
;       PG8_WAIT_V(6); PG8_BAR; PG8_MMA(1, 1, At, B1); PG8_BAR;
;   __device__ __forceinline__ void operator()(EPI_ARGS) const {
;     const size_t row0 = (size_t)u.pm * 256 + wr * 64 + fr;
;     const int col0 = u.pn * 256 + wc * 32 + 8 * fq;
; #pragma unroll
;     for (int bj = 0; bj < 2; ++bj) {
;       const int c = col0 + bj * HALF;
;       const f32x4 s0 = *(const f32x4*)(psc + c), s1 = *(const f32x4*)(psc + c + 4);
; #pragma unroll
;       for (int ai = 0; ai < 2; ++ai) {
;         u32x4 z[4];
; #pragma unroll
;         for (int m = 0; m < 4; ++m) z[m] = *(const u32x4*)(proj + pidx(row0 + ai * HALF + m * 16, PZ + c));
;         __builtin_amdgcn_sched_barrier(0);
; #pragma unroll
;         for (int m = 0; m < 4; ++m) {
;           const size_t row = row0 + ai * HALF + m * 16;
;           const f32x4 v0 = acc[ai][bj][m][0], v1 = acc[ai][bj][m][1];
;           u32x4 o;
;           o.x = pack2(v0[0] * s0[0] * siluf_(bflo(z[m].x)), v0[1] * s0[1] * siluf_(bfhi(z[m].x)));
;           o.y = pack2(v0[2] * s0[2] * siluf_(bflo(z[m].y)), v0[3] * s0[3] * siluf_(bfhi(z[m].y)));
;           o.z = pack2(v1[0] * s1[0] * siluf_(bflo(z[m].z)), v1[1] * s1[1] * siluf_(bfhi(z[m].z)));
;           o.w = pack2(v1[2] * s1[2] * siluf_(bflo(z[m].w)), v1[3] * s1[3] * siluf_(bfhi(z[m].w)));
;           *(u32x4*)(y0 + row * DM + c) = o;
;         }
	s_waitcnt lgkmcnt(0)
	s_setprio 1
	s_waitcnt lgkmcnt(0)
	v_mfma_f32_16x16x32_bf16 v[104:107], v[92:95], v[148:151], v[104:107]
	v_mfma_f32_16x16x32_bf16 v[104:107], v[100:103], v[152:155], v[104:107]
	v_mfma_f32_16x16x32_bf16 v[88:91], v[92:95], v[176:179], v[88:91]
	v_mfma_f32_16x16x32_bf16 v[88:91], v[100:103], v[180:183], v[88:91]
	v_mfma_f32_16x16x32_bf16 v[80:83], v[92:95], v[184:187], v[80:83]
	v_mfma_f32_16x16x32_bf16 v[80:83], v[100:103], v[188:191], v[80:83]
	v_mfma_f32_16x16x32_bf16 v[72:75], v[92:95], v[192:195], v[72:75]
	v_mfma_f32_16x16x32_bf16 v[72:75], v[100:103], v[212:215], v[72:75]
	v_mfma_f32_16x16x32_bf16 v[96:99], v[132:135], v[148:151], v[96:99]
	v_mfma_f32_16x16x32_bf16 v[96:99], v[144:147], v[152:155], v[96:99]
	v_mfma_f32_16x16x32_bf16 v[84:87], v[132:135], v[176:179], v[84:87]
	v_mfma_f32_16x16x32_bf16 v[84:87], v[144:147], v[180:183], v[84:87]
	v_mfma_f32_16x16x32_bf16 v[76:79], v[132:135], v[184:187], v[76:79]
	v_mfma_f32_16x16x32_bf16 v[76:79], v[144:147], v[188:191], v[76:79]
	v_mfma_f32_16x16x32_bf16 v[68:71], v[132:135], v[192:195], v[68:71]
	v_mfma_f32_16x16x32_bf16 v[68:71], v[144:147], v[212:215], v[68:71]
	s_setprio 0
	s_barrier
	s_add_u32 s6, s6, 0x20080
	s_addc_u32 s7, s7, 0
	s_add_i32 s10, s10, s29
	v_lshl_add_u64 v[92:93], s[6:7], 0, v[158:159]
	s_mov_b32 m0, s10
	s_nop 0
	global_load_lds_dwordx4 v[92:93], off
	v_lshl_add_u64 v[92:93], s[6:7], 0, v[0:1]
	s_add_i32 m0, s10, 0x2000
	s_nop 0
	global_load_lds_dwordx4 v[92:93], off
	s_waitcnt vmcnt(6)
	s_barrier
	s_setprio 1
	v_mfma_f32_16x16x32_bf16 v[32:35], v[216:219], v[148:151], v[32:35]
	v_mfma_f32_16x16x32_bf16 v[32:35], v[220:223], v[152:155], v[32:35]
	v_mfma_f32_16x16x32_bf16 v[24:27], v[216:219], v[176:179], v[24:27]
	v_mfma_f32_16x16x32_bf16 v[24:27], v[220:223], v[180:183], v[24:27]
	v_mfma_f32_16x16x32_bf16 v[16:19], v[216:219], v[184:187], v[16:19]
	v_mfma_f32_16x16x32_bf16 v[16:19], v[220:223], v[188:191], v[16:19]
	v_mfma_f32_16x16x32_bf16 v[8:11], v[216:219], v[192:195], v[8:11]
	v_mfma_f32_16x16x32_bf16 v[8:11], v[220:223], v[212:215], v[8:11]
	v_mfma_f32_16x16x32_bf16 v[28:31], v[224:227], v[148:151], v[28:31]
	v_mfma_f32_16x16x32_bf16 v[28:31], v[228:231], v[152:155], v[28:31]
	v_mfma_f32_16x16x32_bf16 v[20:23], v[224:227], v[176:179], v[20:23]
	v_mfma_f32_16x16x32_bf16 v[20:23], v[228:231], v[180:183], v[20:23]
	v_mfma_f32_16x16x32_bf16 v[12:15], v[224:227], v[184:187], v[12:15]
	v_mfma_f32_16x16x32_bf16 v[12:15], v[228:231], v[188:191], v[12:15]
	v_mfma_f32_16x16x32_bf16 v[4:7], v[224:227], v[192:195], v[4:7]
	v_mfma_f32_16x16x32_bf16 v[4:7], v[228:231], v[212:215], v[4:7]
	s_setprio 0
	s_add_i32 s43, s43, 2
	s_add_u32 s41, s41, 0x100
	s_addc_u32 s42, s42, 0
	s_add_u32 s4, s4, 0x100
	s_addc_u32 s5, s5, 0
	s_cmp_gt_u32 s43, 5
	s_barrier
	s_cbranch_scc0 .LBB0_485
	s_ashr_i32 s3, s2, 31
	s_lshl_b64 s[2:3], s[2:3], 8
	v_lshl_add_u64 v[186:187], s[2:3], 0, v[162:163]
	s_lshl_b32 s2, s33, 8
	v_or_b32_e32 v196, s2, v168
	s_addk_i32 s2, 0x800
	s_ashr_i32 s2, s2, 8
	s_ashr_i32 s3, s2, 31
	s_lshl_b64 s[2:3], s[2:3], 23
	s_add_u32 s2, s0, s2
	s_addc_u32 s3, s1, s3
	v_lshlrev_b32_e32 v2, 1, v168
	v_or_b32_e32 v194, 16, v186
	v_mov_b32_e32 v195, v187
	v_ashrrev_i32_e32 v197, 31, v196
	v_lshl_add_u64 v[188:189], s[2:3], 0, v[2:3]
	v_lshlrev_b64 v[178:179], 9, v[186:187]
	v_lshlrev_b64 v[180:181], 9, v[194:195]
	v_or_b32_e32 v192, 32, v186
	v_mov_b32_e32 v193, v187
	v_or_b32_e32 v190, 48, v186
	v_mov_b32_e32 v191, v187
	v_lshl_add_u64 v[176:177], v[196:197], 2, s[12:13]
	v_lshl_add_u64 v[132:133], v[188:189], 0, v[178:179]
	v_lshl_add_u64 v[134:135], v[188:189], 0, v[180:181]
	v_lshlrev_b64 v[182:183], 9, v[192:193]
	v_lshlrev_b64 v[184:185], 9, v[190:191]
	global_load_dwordx4 v[92:95], v[176:177], off offset:16
	global_load_dwordx4 v[100:103], v[176:177], off
	flat_load_dwordx4 v[152:155], v[132:133]
	flat_load_dwordx4 v[148:151], v[134:135]
	v_lshl_add_u64 v[132:133], v[188:189], 0, v[182:183]
	v_lshl_add_u64 v[134:135], v[188:189], 0, v[184:185]
	flat_load_dwordx4 v[144:147], v[132:133]
	s_nop 0
	flat_load_dwordx4 v[132:135], v[134:135]
	s_waitcnt vmcnt(0) lgkmcnt(0)
	v_lshlrev_b32_e32 v213, 16, v152
	v_mul_f32_e32 v2, 0xbfb8aa3b, v213
	v_exp_f32_e32 v2, v2
	v_mov_b32_e32 v214, v140
	v_mov_b32_e32 v212, v100
	s_mov_b64 s[4:5], 0x90
	v_add_f32_e32 v2, 1.0, v2
	v_rcp_f32_e32 v215, v2
	s_nop 0
	v_pk_mul_f32 v[212:213], v[214:215], v[212:213]
	s_nop 0
	v_mul_f32_e32 v2, v212, v213
	v_and_b32_e32 v213, 0xffff0000, v152
	v_mul_f32_e32 v140, 0xbfb8aa3b, v213
	v_exp_f32_e32 v140, v140
	v_mov_b32_e32 v214, v141
	v_mov_b32_e32 v212, v101
	v_add_f32_e32 v140, 1.0, v140
	v_rcp_f32_e32 v215, v140
	s_nop 0
	v_pk_mul_f32 v[140:141], v[214:215], v[212:213]
	s_nop 0
	v_mul_f32_e32 v140, v140, v141
	v_lshlrev_b32_e32 v141, 16, v153
	v_cvt_pk_bf16_f32 v152, v2, v140
	v_mul_f32_e32 v2, 0xbfb8aa3b, v141
	v_exp_f32_e32 v2, v2
	v_mov_b32_e32 v212, v142
	v_mov_b32_e32 v140, v102
	v_mov_b32_e32 v142, v136
	v_add_f32_e32 v2, 1.0, v2
	v_rcp_f32_e32 v213, v2
	s_nop 0
	v_pk_mul_f32 v[140:141], v[212:213], v[140:141]
	s_nop 0
	v_mul_f32_e32 v2, v140, v141
	v_and_b32_e32 v141, 0xffff0000, v153
	v_mul_f32_e32 v140, 0xbfb8aa3b, v141
	v_exp_f32_e32 v140, v140
	v_mov_b32_e32 v212, v143
	v_add_f32_e32 v140, 1.0, v140
	v_rcp_f32_e32 v213, v140
	v_mov_b32_e32 v140, v103
	v_pk_mul_f32 v[140:141], v[212:213], v[140:141]
	s_nop 0
	v_mul_f32_e32 v140, v140, v141
	v_lshlrev_b32_e32 v141, 16, v154
	v_cvt_pk_bf16_f32 v153, v2, v140
	v_mul_f32_e32 v2, 0xbfb8aa3b, v141
	v_exp_f32_e32 v2, v2
	v_mov_b32_e32 v140, v92
	v_add_f32_e32 v2, 1.0, v2
	v_rcp_f32_e32 v143, v2
	s_nop 0
; __device__ __forceinline__ size_t pidx(size_t row, int col) { return ((size_t)(col >> 8) * MTOK + row) * PLD + (col & 255); }
; __device__ __forceinline__ float bflo(unsigned v) { return __uint_as_float(v << 16); }
; __device__ __forceinline__ float bfhi(unsigned v) { return __uint_as_float(v & 0xffff0000u); }
; __device__ __forceinline__ float siluf_(float x) { return x * __builtin_amdgcn_rcpf(1.0f + __expf(-x)); }
;   __device__ __forceinline__ void operator()(EPI_ARGS) const {
;     ...
;     for (int bj = 0; bj < 2; ++bj) {
;       const int c = col0 + bj * HALF;
;       const f32x4 s0 = *(const f32x4*)(psc + c), s1 = *(const f32x4*)(psc + c + 4);
; #pragma unroll
;       for (int ai = 0; ai < 2; ++ai) {
;         u32x4 z[4];
; #pragma unroll
;         for (int m = 0; m < 4; ++m) z[m] = *(const u32x4*)(proj + pidx(row0 + ai * HALF + m * 16, PZ + c));
;         __builtin_amdgcn_sched_barrier(0);
; #pragma unroll
;         for (int m = 0; m < 4; ++m) {
;           const size_t row = row0 + ai * HALF + m * 16;
;           const f32x4 v0 = acc[ai][bj][m][0], v1 = acc[ai][bj][m][1];
;           u32x4 o;
;           o.x = pack2(v0[0] * s0[0] * siluf_(bflo(z[m].x)), v0[1] * s0[1] * siluf_(bfhi(z[m].x)));
;           o.y = pack2(v0[2] * s0[2] * siluf_(bflo(z[m].y)), v0[3] * s0[3] * siluf_(bfhi(z[m].y)));
;           o.z = pack2(v1[0] * s1[0] * siluf_(bflo(z[m].z)), v1[1] * s1[1] * siluf_(bfhi(z[m].z)));
;           o.w = pack2(v1[2] * s1[2] * siluf_(bflo(z[m].w)), v1[3] * s1[3] * siluf_(bfhi(z[m].w)));
;           *(u32x4*)(y0 + row * DM + c) = o;
;         }
	v_pk_mul_f32 v[140:141], v[142:143], v[140:141]
	s_nop 0
	v_mul_f32_e32 v2, v140, v141
	v_and_b32_e32 v141, 0xffff0000, v154
	v_mul_f32_e32 v136, 0xbfb8aa3b, v141
	v_exp_f32_e32 v136, v136
	v_mov_b32_e32 v142, v137
	v_mov_b32_e32 v140, v93
	v_add_f32_e32 v136, 1.0, v136
	v_rcp_f32_e32 v143, v136
	s_nop 0
	v_pk_mul_f32 v[136:137], v[142:143], v[140:141]
	s_nop 0
	v_mul_f32_e32 v136, v136, v137
	v_lshlrev_b32_e32 v137, 16, v155
	v_cvt_pk_bf16_f32 v154, v2, v136
	v_mul_f32_e32 v2, 0xbfb8aa3b, v137
	v_exp_f32_e32 v2, v2
	v_mov_b32_e32 v140, v138
	v_mov_b32_e32 v136, v94
	v_mov_b32_e32 v142, v128
	v_add_f32_e32 v2, 1.0, v2
	v_rcp_f32_e32 v141, v2
	v_mov_b32_e32 v138, v100
	v_pk_mul_f32 v[136:137], v[140:141], v[136:137]
	s_nop 0
	v_mul_f32_e32 v2, v136, v137
	v_and_b32_e32 v137, 0xffff0000, v155
	v_mul_f32_e32 v136, 0xbfb8aa3b, v137
	v_exp_f32_e32 v136, v136
	v_mov_b32_e32 v140, v139
	v_lshlrev_b32_e32 v139, 16, v148
	v_add_f32_e32 v136, 1.0, v136
	v_rcp_f32_e32 v141, v136
	v_mov_b32_e32 v136, v95
	v_pk_mul_f32 v[136:137], v[140:141], v[136:137]
	s_nop 0
	v_mul_f32_e32 v136, v136, v137
	v_cvt_pk_bf16_f32 v155, v2, v136
	v_mul_f32_e32 v2, 0xbfb8aa3b, v139
	v_exp_f32_e32 v2, v2
	v_lshlrev_b64 v[140:141], 1, v[196:197]
	v_lshlrev_b64 v[136:137], 12, v[186:187]
	v_lshl_add_u64 v[136:137], s[8:9], 0, v[136:137]
	v_add_f32_e32 v2, 1.0, v2
	v_rcp_f32_e32 v143, v2
	v_lshl_add_u64 v[136:137], v[136:137], 0, v[140:141]
	flat_store_dwordx4 v[136:137], v[152:155]
	v_pk_mul_f32 v[138:139], v[142:143], v[138:139]
	s_nop 0
	v_mul_f32_e32 v2, v138, v139
	v_and_b32_e32 v139, 0xffff0000, v148
	v_mul_f32_e32 v128, 0xbfb8aa3b, v139
	v_exp_f32_e32 v128, v128
	v_mov_b32_e32 v142, v129
	v_mov_b32_e32 v138, v101
	v_add_f32_e32 v128, 1.0, v128
	v_rcp_f32_e32 v143, v128
	s_nop 0
	v_pk_mul_f32 v[128:129], v[142:143], v[138:139]
	s_nop 0
	v_mul_f32_e32 v128, v128, v129
	v_lshlrev_b32_e32 v139, 16, v149
	v_cvt_pk_bf16_f32 v128, v2, v128
	v_mul_f32_e32 v2, 0xbfb8aa3b, v139
	v_exp_f32_e32 v2, v2
	v_mov_b32_e32 v142, v130
	v_mov_b32_e32 v138, v102
	v_add_f32_e32 v2, 1.0, v2
	v_rcp_f32_e32 v143, v2
	s_nop 0
	v_pk_mul_f32 v[138:139], v[142:143], v[138:139]
	s_nop 0
	v_mul_f32_e32 v2, v138, v139
	v_and_b32_e32 v139, 0xffff0000, v149
	v_mul_f32_e32 v129, 0xbfb8aa3b, v139
	v_exp_f32_e32 v129, v129
	v_mov_b32_e32 v142, v131
	v_mov_b32_e32 v138, v103
	v_lshl_add_u64 v[148:149], v[186:187], 0, s[52:53]
	v_add_f32_e32 v129, 1.0, v129
	v_rcp_f32_e32 v143, v129
	s_nop 0
	v_pk_mul_f32 v[130:131], v[142:143], v[138:139]
	s_nop 0
	v_mul_f32_e32 v129, v130, v131
	v_lshlrev_b32_e32 v131, 16, v150
	v_cvt_pk_bf16_f32 v129, v2, v129
	v_mul_f32_e32 v2, 0xbfb8aa3b, v131
	v_exp_f32_e32 v2, v2
	v_mov_b32_e32 v138, v124
	v_mov_b32_e32 v130, v92
	v_add_f32_e32 v2, 1.0, v2
	v_rcp_f32_e32 v139, v2
	s_nop 0
	v_pk_mul_f32 v[130:131], v[138:139], v[130:131]
	s_nop 0
	v_mul_f32_e32 v2, v130, v131
	v_and_b32_e32 v131, 0xffff0000, v150
	v_mul_f32_e32 v124, 0xbfb8aa3b, v131
	v_exp_f32_e32 v124, v124
	v_mov_b32_e32 v138, v125
	v_mov_b32_e32 v130, v93
	v_add_f32_e32 v124, 1.0, v124
	v_rcp_f32_e32 v139, v124
	s_nop 0
	v_pk_mul_f32 v[124:125], v[138:139], v[130:131]
	s_nop 0
	v_mul_f32_e32 v124, v124, v125
	v_lshlrev_b32_e32 v125, 16, v151
	v_cvt_pk_bf16_f32 v130, v2, v124
	v_mul_f32_e32 v2, 0xbfb8aa3b, v125
	v_exp_f32_e32 v2, v2
	v_mov_b32_e32 v138, v126
	v_mov_b32_e32 v124, v94
	v_mov_b32_e32 v126, v100
	v_add_f32_e32 v2, 1.0, v2
	v_rcp_f32_e32 v139, v2
	s_nop 0
	v_pk_mul_f32 v[124:125], v[138:139], v[124:125]
	s_nop 0
	v_mul_f32_e32 v2, v124, v125
	v_and_b32_e32 v125, 0xffff0000, v151
	v_mul_f32_e32 v124, 0xbfb8aa3b, v125
	v_exp_f32_e32 v124, v124
	v_mov_b32_e32 v138, v127
	v_lshlrev_b32_e32 v127, 16, v144
	v_add_f32_e32 v124, 1.0, v124
	v_rcp_f32_e32 v139, v124
	v_mov_b32_e32 v124, v95
	v_pk_mul_f32 v[124:125], v[138:139], v[124:125]
	s_nop 0
	v_mul_f32_e32 v124, v124, v125
	v_cvt_pk_bf16_f32 v131, v2, v124
	v_mul_f32_e32 v2, 0xbfb8aa3b, v127
	v_exp_f32_e32 v2, v2
	v_lshlrev_b64 v[124:125], 12, v[194:195]
	v_lshl_add_u64 v[124:125], s[8:9], 0, v[124:125]
	v_lshl_add_u64 v[124:125], v[124:125], 0, v[140:141]
	v_add_f32_e32 v2, 1.0, v2
	flat_store_dwordx4 v[124:125], v[128:131]
	s_nop 1
	v_rcp_f32_e32 v129, v2
	v_mov_b32_e32 v128, v120
	v_lshlrev_b64 v[130:131], 9, v[148:149]
	v_pk_mul_f32 v[126:127], v[128:129], v[126:127]
	s_nop 0
	v_mul_f32_e32 v2, v126, v127
	v_and_b32_e32 v127, 0xffff0000, v144
	v_mul_f32_e32 v120, 0xbfb8aa3b, v127
	v_exp_f32_e32 v120, v120
	v_mov_b32_e32 v128, v121
	v_mov_b32_e32 v126, v101
	v_add_f32_e32 v120, 1.0, v120
	v_rcp_f32_e32 v129, v120
	s_nop 0
	v_pk_mul_f32 v[120:121], v[128:129], v[126:127]
	s_nop 0
	v_mul_f32_e32 v120, v120, v121
	v_lshlrev_b32_e32 v127, 16, v145
	v_cvt_pk_bf16_f32 v120, v2, v120
	v_mul_f32_e32 v2, 0xbfb8aa3b, v127
	v_exp_f32_e32 v2, v2
	v_mov_b32_e32 v128, v122
	v_mov_b32_e32 v126, v102
	v_add_f32_e32 v2, 1.0, v2
	v_rcp_f32_e32 v129, v2
	s_nop 0
	v_pk_mul_f32 v[126:127], v[128:129], v[126:127]
	s_nop 0
	v_mul_f32_e32 v2, v126, v127
	v_and_b32_e32 v127, 0xffff0000, v145
	v_mul_f32_e32 v121, 0xbfb8aa3b, v127
	v_exp_f32_e32 v121, v121
	v_mov_b32_e32 v128, v123
	v_mov_b32_e32 v126, v103
	v_add_f32_e32 v121, 1.0, v121
	v_rcp_f32_e32 v129, v121
	s_nop 0
	v_pk_mul_f32 v[122:123], v[128:129], v[126:127]
	s_nop 0
	v_mul_f32_e32 v121, v122, v123
	v_lshlrev_b32_e32 v123, 16, v146
	v_cvt_pk_bf16_f32 v121, v2, v121
	v_mul_f32_e32 v2, 0xbfb8aa3b, v123
	v_exp_f32_e32 v2, v2
	v_mov_b32_e32 v126, v116
	v_mov_b32_e32 v122, v92
	v_add_f32_e32 v2, 1.0, v2
	v_rcp_f32_e32 v127, v2
	s_nop 0
	v_pk_mul_f32 v[122:123], v[126:127], v[122:123]
	s_nop 0
	v_mul_f32_e32 v2, v122, v123
; __device__ __forceinline__ size_t pidx(size_t row, int col) { return ((size_t)(col >> 8) * MTOK + row) * PLD + (col & 255); }
; __device__ __forceinline__ float bflo(unsigned v) { return __uint_as_float(v << 16); }
; __device__ __forceinline__ float bfhi(unsigned v) { return __uint_as_float(v & 0xffff0000u); }
; __device__ __forceinline__ float siluf_(float x) { return x * __builtin_amdgcn_rcpf(1.0f + __expf(-x)); }
;   __device__ __forceinline__ void operator()(EPI_ARGS) const {
;     ...
;       for (int ai = 0; ai < 2; ++ai) {
;         u32x4 z[4];
; #pragma unroll
;         for (int m = 0; m < 4; ++m) z[m] = *(const u32x4*)(proj + pidx(row0 + ai * HALF + m * 16, PZ + c));
;         __builtin_amdgcn_sched_barrier(0);
; #pragma unroll
;         for (int m = 0; m < 4; ++m) {
;           const size_t row = row0 + ai * HALF + m * 16;
;           const f32x4 v0 = acc[ai][bj][m][0], v1 = acc[ai][bj][m][1];
;           u32x4 o;
;           o.x = pack2(v0[0] * s0[0] * siluf_(bflo(z[m].x)), v0[1] * s0[1] * siluf_(bfhi(z[m].x)));
;           o.y = pack2(v0[2] * s0[2] * siluf_(bflo(z[m].y)), v0[3] * s0[3] * siluf_(bfhi(z[m].y)));
;           o.z = pack2(v1[0] * s1[0] * siluf_(bflo(z[m].z)), v1[1] * s1[1] * siluf_(bfhi(z[m].z)));
;           o.w = pack2(v1[2] * s1[2] * siluf_(bflo(z[m].w)), v1[3] * s1[3] * siluf_(bfhi(z[m].w)));
;           *(u32x4*)(y0 + row * DM + c) = o;
;         }
	v_and_b32_e32 v123, 0xffff0000, v146
	v_mul_f32_e32 v116, 0xbfb8aa3b, v123
	v_exp_f32_e32 v116, v116
	v_mov_b32_e32 v126, v117
	v_mov_b32_e32 v122, v93
	v_add_f32_e32 v116, 1.0, v116
	v_rcp_f32_e32 v127, v116
	s_nop 0
	v_pk_mul_f32 v[116:117], v[126:127], v[122:123]
	s_nop 0
	v_mul_f32_e32 v116, v116, v117
	v_lshlrev_b32_e32 v117, 16, v147
	v_cvt_pk_bf16_f32 v122, v2, v116
	v_mul_f32_e32 v2, 0xbfb8aa3b, v117
	v_exp_f32_e32 v2, v2
	v_mov_b32_e32 v126, v118
	v_mov_b32_e32 v116, v94
	v_mov_b32_e32 v118, v112
	v_add_f32_e32 v2, 1.0, v2
	v_rcp_f32_e32 v127, v2
	s_nop 0
	v_pk_mul_f32 v[116:117], v[126:127], v[116:117]
	s_nop 0
	v_mul_f32_e32 v2, v116, v117
	v_and_b32_e32 v117, 0xffff0000, v147
	v_mul_f32_e32 v116, 0xbfb8aa3b, v117
	v_exp_f32_e32 v116, v116
	v_mov_b32_e32 v126, v119
	v_lshl_add_u64 v[146:147], v[186:187], 0, s[4:5]
	s_mov_b64 s[4:5], 0xa0
	v_add_f32_e32 v116, 1.0, v116
	v_rcp_f32_e32 v127, v116
	v_mov_b32_e32 v116, v95
	v_lshl_add_u64 v[144:145], v[186:187], 0, s[4:5]
	s_mov_b64 s[4:5], 0xb0
	v_pk_mul_f32 v[116:117], v[126:127], v[116:117]
	v_lshl_add_u64 v[142:143], v[186:187], 0, s[4:5]
	v_mul_f32_e32 v116, v116, v117
	v_cvt_pk_bf16_f32 v123, v2, v116
	v_lshlrev_b64 v[116:117], 12, v[192:193]
	v_lshl_add_u64 v[116:117], s[8:9], 0, v[116:117]
	v_lshl_add_u64 v[128:129], v[116:117], 0, v[140:141]
	v_lshlrev_b32_e32 v117, 16, v132
	v_mul_f32_e32 v2, 0xbfb8aa3b, v117
	v_exp_f32_e32 v2, v2
	v_mov_b32_e32 v116, v100
	flat_store_dwordx4 v[128:129], v[120:123]
	v_lshlrev_b64 v[138:139], 9, v[142:143]
	v_add_f32_e32 v2, 1.0, v2
	v_rcp_f32_e32 v119, v2
	s_nop 0
	v_pk_mul_f32 v[116:117], v[118:119], v[116:117]
	s_nop 0
	v_mul_f32_e32 v2, v116, v117
	v_and_b32_e32 v117, 0xffff0000, v132
	v_mul_f32_e32 v112, 0xbfb8aa3b, v117
	v_exp_f32_e32 v112, v112
	v_mov_b32_e32 v118, v113
	v_mov_b32_e32 v116, v101
	v_add_f32_e32 v112, 1.0, v112
	v_rcp_f32_e32 v119, v112
	s_nop 0
	v_pk_mul_f32 v[112:113], v[118:119], v[116:117]
	s_nop 0
	v_mul_f32_e32 v112, v112, v113
	v_lshlrev_b32_e32 v117, 16, v133
	v_cvt_pk_bf16_f32 v112, v2, v112
	v_mul_f32_e32 v2, 0xbfb8aa3b, v117
	v_exp_f32_e32 v2, v2
	v_mov_b32_e32 v118, v114
	v_mov_b32_e32 v116, v102
	v_add_f32_e32 v2, 1.0, v2
	v_rcp_f32_e32 v119, v2
	s_nop 0
	v_pk_mul_f32 v[116:117], v[118:119], v[116:117]
	s_nop 0
	v_mul_f32_e32 v2, v116, v117
	v_and_b32_e32 v117, 0xffff0000, v133
	v_mul_f32_e32 v113, 0xbfb8aa3b, v117
	v_exp_f32_e32 v113, v113
	v_mov_b32_e32 v118, v115
	v_mov_b32_e32 v116, v103
	v_lshlrev_b64 v[132:133], 9, v[146:147]
	v_add_f32_e32 v113, 1.0, v113
	v_rcp_f32_e32 v119, v113
	s_nop 0
	v_pk_mul_f32 v[114:115], v[118:119], v[116:117]
	s_nop 0
	v_mul_f32_e32 v113, v114, v115
	v_lshlrev_b32_e32 v115, 16, v134
	v_cvt_pk_bf16_f32 v113, v2, v113
	v_mul_f32_e32 v2, 0xbfb8aa3b, v115
	v_exp_f32_e32 v2, v2
	v_mov_b32_e32 v116, v108
	v_mov_b32_e32 v114, v92
	v_add_f32_e32 v2, 1.0, v2
	v_rcp_f32_e32 v117, v2
	s_nop 0
	v_pk_mul_f32 v[114:115], v[116:117], v[114:115]
	s_nop 0
	v_mul_f32_e32 v2, v114, v115
	v_and_b32_e32 v115, 0xffff0000, v134
	v_mul_f32_e32 v108, 0xbfb8aa3b, v115
	v_exp_f32_e32 v108, v108
	v_mov_b32_e32 v116, v109
	v_mov_b32_e32 v114, v93
	v_add_f32_e32 v108, 1.0, v108
	v_rcp_f32_e32 v117, v108
	s_nop 0
	v_pk_mul_f32 v[108:109], v[116:117], v[114:115]
	s_nop 0
	v_mul_f32_e32 v108, v108, v109
	v_lshlrev_b32_e32 v109, 16, v135
	v_cvt_pk_bf16_f32 v114, v2, v108
	v_mul_f32_e32 v2, 0xbfb8aa3b, v109
	v_exp_f32_e32 v2, v2
	v_mov_b32_e32 v116, v110
	v_mov_b32_e32 v108, v94
	v_add_f32_e32 v2, 1.0, v2
	v_rcp_f32_e32 v117, v2
	s_nop 0
	v_pk_mul_f32 v[108:109], v[116:117], v[108:109]
	s_nop 0
	v_mul_f32_e32 v2, v108, v109
	v_and_b32_e32 v109, 0xffff0000, v135
	v_mul_f32_e32 v108, 0xbfb8aa3b, v109
	v_exp_f32_e32 v108, v108
	v_mov_b32_e32 v116, v111
	v_lshlrev_b64 v[134:135], 9, v[144:145]
	v_add_f32_e32 v108, 1.0, v108
	v_rcp_f32_e32 v117, v108
	v_mov_b32_e32 v108, v95
	v_pk_mul_f32 v[108:109], v[116:117], v[108:109]
	s_nop 0
	v_mul_f32_e32 v108, v108, v109
	v_cvt_pk_bf16_f32 v115, v2, v108
	v_lshlrev_b64 v[108:109], 12, v[190:191]
	v_lshl_add_u64 v[108:109], s[8:9], 0, v[108:109]
	v_lshl_add_u64 v[126:127], v[108:109], 0, v[140:141]
	flat_store_dwordx4 v[126:127], v[112:115]
	v_lshl_add_u64 v[108:109], v[188:189], 0, v[130:131]
	flat_load_dwordx4 v[120:123], v[108:109]
	v_lshl_add_u64 v[108:109], v[188:189], 0, v[132:133]
	flat_load_dwordx4 v[116:119], v[108:109]
	v_lshl_add_u64 v[108:109], v[188:189], 0, v[134:135]
	flat_load_dwordx4 v[112:115], v[108:109]
	v_lshl_add_u64 v[108:109], v[188:189], 0, v[138:139]
	flat_load_dwordx4 v[108:111], v[108:109]
	s_waitcnt vmcnt(0) lgkmcnt(0)
; __device__ __forceinline__ size_t pidx(size_t row, int col) { return ((size_t)(col >> 8) * MTOK + row) * PLD + (col & 255); }
; __device__ __forceinline__ float bflo(unsigned v) { return __uint_as_float(v << 16); }
; __device__ __forceinline__ float bfhi(unsigned v) { return __uint_as_float(v & 0xffff0000u); }
; __device__ __forceinline__ float siluf_(float x) { return x * __builtin_amdgcn_rcpf(1.0f + __expf(-x)); }
;   __device__ __forceinline__ void operator()(EPI_ARGS) const {
;     ...
;       for (int ai = 0; ai < 2; ++ai) {
;         u32x4 z[4];
; #pragma unroll
;         for (int m = 0; m < 4; ++m) z[m] = *(const u32x4*)(proj + pidx(row0 + ai * HALF + m * 16, PZ + c));
;         __builtin_amdgcn_sched_barrier(0);
; #pragma unroll
;         for (int m = 0; m < 4; ++m) {
;           const size_t row = row0 + ai * HALF + m * 16;
;           const f32x4 v0 = acc[ai][bj][m][0], v1 = acc[ai][bj][m][1];
;           u32x4 o;
;           o.x = pack2(v0[0] * s0[0] * siluf_(bflo(z[m].x)), v0[1] * s0[1] * siluf_(bfhi(z[m].x)));
;           o.y = pack2(v0[2] * s0[2] * siluf_(bflo(z[m].y)), v0[3] * s0[3] * siluf_(bfhi(z[m].y)));
;           o.z = pack2(v1[0] * s1[0] * siluf_(bflo(z[m].z)), v1[1] * s1[1] * siluf_(bfhi(z[m].z)));
;           o.w = pack2(v1[2] * s1[2] * siluf_(bflo(z[m].w)), v1[3] * s1[3] * siluf_(bfhi(z[m].w)));
;           *(u32x4*)(y0 + row * DM + c) = o;
;         }
	v_lshlrev_b32_e32 v151, 16, v120
	v_mul_f32_e32 v2, 0xbfb8aa3b, v151
	v_exp_f32_e32 v2, v2
	v_mov_b32_e32 v152, v104
	v_mov_b32_e32 v150, v100
	v_mov_b32_e32 v175, v3
	v_add_f32_e32 v2, 1.0, v2
	v_rcp_f32_e32 v153, v2
	s_nop 0
	v_pk_mul_f32 v[150:151], v[152:153], v[150:151]
	s_nop 0
	v_mul_f32_e32 v2, v150, v151
	v_and_b32_e32 v151, 0xffff0000, v120
	v_mul_f32_e32 v104, 0xbfb8aa3b, v151
	v_exp_f32_e32 v104, v104
	v_mov_b32_e32 v152, v105
	v_mov_b32_e32 v150, v101
	v_mov_b32_e32 v120, v103
	v_add_f32_e32 v104, 1.0, v104
	v_rcp_f32_e32 v153, v104
	s_nop 0
	v_pk_mul_f32 v[104:105], v[152:153], v[150:151]
	s_nop 0
	v_mul_f32_e32 v104, v104, v105
	v_lshlrev_b32_e32 v151, 16, v121
	v_cvt_pk_bf16_f32 v104, v2, v104
	v_mul_f32_e32 v2, 0xbfb8aa3b, v151
	v_exp_f32_e32 v2, v2
	v_and_b32_e32 v121, 0xffff0000, v121
	v_mul_f32_e32 v105, 0xbfb8aa3b, v121
	v_exp_f32_e32 v105, v105
	v_add_f32_e32 v2, 1.0, v2
	v_rcp_f32_e32 v153, v2
	v_mov_b32_e32 v152, v106
	v_mov_b32_e32 v150, v102
	v_add_f32_e32 v105, 1.0, v105
	v_pk_mul_f32 v[150:151], v[152:153], v[150:151]
	s_nop 0
	v_mul_f32_e32 v2, v150, v151
	v_rcp_f32_e32 v151, v105
	v_mov_b32_e32 v150, v107
	v_pk_mul_f32 v[106:107], v[150:151], v[120:121]
	s_nop 0
	v_mul_f32_e32 v105, v106, v107
	v_lshlrev_b32_e32 v107, 16, v122
	v_cvt_pk_bf16_f32 v105, v2, v105
	v_mul_f32_e32 v2, 0xbfb8aa3b, v107
	v_exp_f32_e32 v2, v2
	v_mov_b32_e32 v120, v96
	v_mov_b32_e32 v106, v92
	v_add_f32_e32 v2, 1.0, v2
	v_rcp_f32_e32 v121, v2
	s_nop 0
	v_pk_mul_f32 v[106:107], v[120:121], v[106:107]
	s_nop 0
	v_mul_f32_e32 v2, v106, v107
	v_and_b32_e32 v107, 0xffff0000, v122
	v_mul_f32_e32 v96, 0xbfb8aa3b, v107
	v_exp_f32_e32 v96, v96
	v_mov_b32_e32 v120, v97
	v_mov_b32_e32 v106, v93
	v_add_f32_e32 v96, 1.0, v96
	v_rcp_f32_e32 v121, v96
	s_nop 0
	v_pk_mul_f32 v[96:97], v[120:121], v[106:107]
	s_nop 0
	v_mul_f32_e32 v96, v96, v97
	v_lshlrev_b32_e32 v97, 16, v123
	v_cvt_pk_bf16_f32 v106, v2, v96
	v_mul_f32_e32 v2, 0xbfb8aa3b, v97
	v_exp_f32_e32 v2, v2
	v_mov_b32_e32 v120, v98
	v_mov_b32_e32 v96, v94
	v_mov_b32_e32 v98, v100
	v_add_f32_e32 v2, 1.0, v2
	v_rcp_f32_e32 v121, v2
	s_nop 0
	v_pk_mul_f32 v[96:97], v[120:121], v[96:97]
	s_nop 0
	v_mul_f32_e32 v2, v96, v97
	v_and_b32_e32 v97, 0xffff0000, v123
	v_mul_f32_e32 v96, 0xbfb8aa3b, v97
	v_exp_f32_e32 v96, v96
	v_mov_b32_e32 v120, v99
	v_lshlrev_b32_e32 v99, 16, v116
	v_add_f32_e32 v96, 1.0, v96
	v_rcp_f32_e32 v121, v96
	v_mov_b32_e32 v96, v95
	v_pk_mul_f32 v[96:97], v[120:121], v[96:97]
	s_nop 0
	v_mul_f32_e32 v96, v96, v97
	v_cvt_pk_bf16_f32 v107, v2, v96
	v_mul_f32_e32 v2, 0xbfb8aa3b, v99
	v_exp_f32_e32 v2, v2
	v_lshlrev_b64 v[96:97], 12, v[148:149]
	v_lshl_add_u64 v[96:97], s[8:9], 0, v[96:97]
	v_lshl_add_u64 v[96:97], v[96:97], 0, v[140:141]
	v_add_f32_e32 v2, 1.0, v2
	flat_store_dwordx4 v[96:97], v[104:107]
	s_nop 1
	v_rcp_f32_e32 v105, v2
	v_mov_b32_e32 v104, v88
	v_pk_mul_f32 v[98:99], v[104:105], v[98:99]
	s_nop 0
	v_mul_f32_e32 v2, v98, v99
	v_and_b32_e32 v99, 0xffff0000, v116
	v_mul_f32_e32 v88, 0xbfb8aa3b, v99
	v_exp_f32_e32 v88, v88
	v_mov_b32_e32 v104, v89
	v_mov_b32_e32 v98, v101
	v_add_f32_e32 v88, 1.0, v88
	v_rcp_f32_e32 v105, v88
	s_nop 0
	v_pk_mul_f32 v[88:89], v[104:105], v[98:99]
	s_nop 0
	v_mul_f32_e32 v88, v88, v89
	v_lshlrev_b32_e32 v99, 16, v117
	v_cvt_pk_bf16_f32 v88, v2, v88
	v_mul_f32_e32 v2, 0xbfb8aa3b, v99
	v_exp_f32_e32 v2, v2
	v_mov_b32_e32 v104, v90
	v_mov_b32_e32 v98, v102
	v_add_f32_e32 v2, 1.0, v2
	v_rcp_f32_e32 v105, v2
	s_nop 0
	v_pk_mul_f32 v[98:99], v[104:105], v[98:99]
	s_nop 0
	v_mul_f32_e32 v2, v98, v99
	v_and_b32_e32 v99, 0xffff0000, v117
	v_mul_f32_e32 v89, 0xbfb8aa3b, v99
	v_exp_f32_e32 v89, v89
	v_mov_b32_e32 v104, v91
	v_mov_b32_e32 v98, v103
	v_add_f32_e32 v89, 1.0, v89
	v_rcp_f32_e32 v105, v89
	s_nop 0
	v_pk_mul_f32 v[90:91], v[104:105], v[98:99]
	s_nop 0
	v_mul_f32_e32 v89, v90, v91
	v_lshlrev_b32_e32 v91, 16, v118
	v_cvt_pk_bf16_f32 v89, v2, v89
	v_mul_f32_e32 v2, 0xbfb8aa3b, v91
	v_exp_f32_e32 v2, v2
	v_mov_b32_e32 v98, v84
	v_mov_b32_e32 v90, v92
	v_add_f32_e32 v2, 1.0, v2
	v_rcp_f32_e32 v99, v2
	s_nop 0
	v_pk_mul_f32 v[90:91], v[98:99], v[90:91]
	s_nop 0
	v_mul_f32_e32 v2, v90, v91
	v_and_b32_e32 v91, 0xffff0000, v118
	v_mul_f32_e32 v84, 0xbfb8aa3b, v91
	v_exp_f32_e32 v84, v84
	v_mov_b32_e32 v98, v85
	v_mov_b32_e32 v90, v93
	v_add_f32_e32 v84, 1.0, v84
	v_rcp_f32_e32 v99, v84
	s_nop 0
	v_pk_mul_f32 v[84:85], v[98:99], v[90:91]
	s_nop 0
	v_mul_f32_e32 v84, v84, v85
	v_lshlrev_b32_e32 v85, 16, v119
	v_cvt_pk_bf16_f32 v90, v2, v84
	v_mul_f32_e32 v2, 0xbfb8aa3b, v85
	v_exp_f32_e32 v2, v2
	v_mov_b32_e32 v98, v86
	v_mov_b32_e32 v84, v94
	v_mov_b32_e32 v86, v80
	v_add_f32_e32 v2, 1.0, v2
	v_rcp_f32_e32 v99, v2
	s_nop 0
	v_pk_mul_f32 v[84:85], v[98:99], v[84:85]
	s_nop 0
	v_mul_f32_e32 v2, v84, v85
	v_and_b32_e32 v85, 0xffff0000, v119
	v_mul_f32_e32 v84, 0xbfb8aa3b, v85
	v_exp_f32_e32 v84, v84
	v_mov_b32_e32 v98, v87
	v_add_f32_e32 v84, 1.0, v84
	v_rcp_f32_e32 v99, v84
	v_mov_b32_e32 v84, v95
	v_pk_mul_f32 v[84:85], v[98:99], v[84:85]
	s_nop 0
	v_mul_f32_e32 v84, v84, v85
	v_cvt_pk_bf16_f32 v91, v2, v84
	v_lshlrev_b64 v[84:85], 12, v[146:147]
	v_lshl_add_u64 v[84:85], s[8:9], 0, v[84:85]
	v_lshl_add_u64 v[98:99], v[84:85], 0, v[140:141]
	v_lshlrev_b32_e32 v85, 16, v112
	v_mul_f32_e32 v2, 0xbfb8aa3b, v85
	v_exp_f32_e32 v2, v2
	v_mov_b32_e32 v84, v100
	flat_store_dwordx4 v[98:99], v[88:91]
	v_add_f32_e32 v2, 1.0, v2
	v_rcp_f32_e32 v87, v2
	s_nop 0
	v_pk_mul_f32 v[84:85], v[86:87], v[84:85]
	s_nop 0
	v_mul_f32_e32 v2, v84, v85
	v_and_b32_e32 v85, 0xffff0000, v112
	v_mul_f32_e32 v80, 0xbfb8aa3b, v85
	v_exp_f32_e32 v80, v80
	v_mov_b32_e32 v86, v81
; __device__ __forceinline__ size_t pidx(size_t row, int col) { return ((size_t)(col >> 8) * MTOK + row) * PLD + (col & 255); }
; __device__ __forceinline__ float bflo(unsigned v) { return __uint_as_float(v << 16); }
; __device__ __forceinline__ float bfhi(unsigned v) { return __uint_as_float(v & 0xffff0000u); }
; __device__ __forceinline__ float siluf_(float x) { return x * __builtin_amdgcn_rcpf(1.0f + __expf(-x)); }
;   __device__ __forceinline__ void operator()(EPI_ARGS) const {
;     ...
;     for (int bj = 0; bj < 2; ++bj) {
;       const int c = col0 + bj * HALF;
;       const f32x4 s0 = *(const f32x4*)(psc + c), s1 = *(const f32x4*)(psc + c + 4);
; #pragma unroll
;       for (int ai = 0; ai < 2; ++ai) {
;         u32x4 z[4];
; #pragma unroll
;         for (int m = 0; m < 4; ++m) z[m] = *(const u32x4*)(proj + pidx(row0 + ai * HALF + m * 16, PZ + c));
;         __builtin_amdgcn_sched_barrier(0);
; #pragma unroll
;         for (int m = 0; m < 4; ++m) {
;           const size_t row = row0 + ai * HALF + m * 16;
;           const f32x4 v0 = acc[ai][bj][m][0], v1 = acc[ai][bj][m][1];
;           u32x4 o;
;           o.x = pack2(v0[0] * s0[0] * siluf_(bflo(z[m].x)), v0[1] * s0[1] * siluf_(bfhi(z[m].x)));
;           o.y = pack2(v0[2] * s0[2] * siluf_(bflo(z[m].y)), v0[3] * s0[3] * siluf_(bfhi(z[m].y)));
;           o.z = pack2(v1[0] * s1[0] * siluf_(bflo(z[m].z)), v1[1] * s1[1] * siluf_(bfhi(z[m].z)));
;           o.w = pack2(v1[2] * s1[2] * siluf_(bflo(z[m].w)), v1[3] * s1[3] * siluf_(bfhi(z[m].w)));
;           *(u32x4*)(y0 + row * DM + c) = o;
;         }
	v_mov_b32_e32 v84, v101
	v_add_f32_e32 v80, 1.0, v80
	v_rcp_f32_e32 v87, v80
	s_nop 0
	v_pk_mul_f32 v[80:81], v[86:87], v[84:85]
	s_nop 0
	v_mul_f32_e32 v80, v80, v81
	v_lshlrev_b32_e32 v85, 16, v113
	v_cvt_pk_bf16_f32 v80, v2, v80
	v_mul_f32_e32 v2, 0xbfb8aa3b, v85
	v_exp_f32_e32 v2, v2
	v_mov_b32_e32 v86, v82
	v_mov_b32_e32 v84, v102
	v_add_f32_e32 v2, 1.0, v2
	v_rcp_f32_e32 v87, v2
	s_nop 0
	v_pk_mul_f32 v[84:85], v[86:87], v[84:85]
	s_nop 0
	v_mul_f32_e32 v2, v84, v85
	v_and_b32_e32 v85, 0xffff0000, v113
	v_mul_f32_e32 v81, 0xbfb8aa3b, v85
	v_exp_f32_e32 v81, v81
	v_mov_b32_e32 v86, v83
	v_mov_b32_e32 v84, v103
	v_add_f32_e32 v81, 1.0, v81
	v_rcp_f32_e32 v87, v81
	s_nop 0
	v_pk_mul_f32 v[82:83], v[86:87], v[84:85]
	s_nop 0
	v_mul_f32_e32 v81, v82, v83
	v_lshlrev_b32_e32 v83, 16, v114
	v_cvt_pk_bf16_f32 v81, v2, v81
	v_mul_f32_e32 v2, 0xbfb8aa3b, v83
	v_exp_f32_e32 v2, v2
	v_mov_b32_e32 v84, v76
	v_mov_b32_e32 v82, v92
	v_add_f32_e32 v2, 1.0, v2
	v_rcp_f32_e32 v85, v2
	s_nop 0
	v_pk_mul_f32 v[82:83], v[84:85], v[82:83]
	s_nop 0
	v_mul_f32_e32 v2, v82, v83
	v_and_b32_e32 v83, 0xffff0000, v114
	v_mul_f32_e32 v76, 0xbfb8aa3b, v83
	v_exp_f32_e32 v76, v76
	v_mov_b32_e32 v84, v77
	v_mov_b32_e32 v82, v93
	v_add_f32_e32 v76, 1.0, v76
	v_rcp_f32_e32 v85, v76
	s_nop 0
	v_pk_mul_f32 v[76:77], v[84:85], v[82:83]
	s_nop 0
	v_mul_f32_e32 v76, v76, v77
	v_lshlrev_b32_e32 v77, 16, v115
	v_cvt_pk_bf16_f32 v82, v2, v76
	v_mul_f32_e32 v2, 0xbfb8aa3b, v77
	v_exp_f32_e32 v2, v2
	v_mov_b32_e32 v84, v78
	v_mov_b32_e32 v76, v94
	v_mov_b32_e32 v78, v72
	v_add_f32_e32 v2, 1.0, v2
	v_rcp_f32_e32 v85, v2
	s_nop 0
	v_pk_mul_f32 v[76:77], v[84:85], v[76:77]
	s_nop 0
	v_mul_f32_e32 v2, v76, v77
	v_and_b32_e32 v77, 0xffff0000, v115
	v_mul_f32_e32 v76, 0xbfb8aa3b, v77
	v_exp_f32_e32 v76, v76
	v_mov_b32_e32 v84, v79
	v_add_f32_e32 v76, 1.0, v76
	v_rcp_f32_e32 v85, v76
	v_mov_b32_e32 v76, v95
	v_pk_mul_f32 v[76:77], v[84:85], v[76:77]
	s_nop 0
	v_mul_f32_e32 v76, v76, v77
	v_cvt_pk_bf16_f32 v83, v2, v76
	v_lshlrev_b64 v[76:77], 12, v[144:145]
	v_lshl_add_u64 v[76:77], s[8:9], 0, v[76:77]
	v_lshl_add_u64 v[104:105], v[76:77], 0, v[140:141]
	v_lshlrev_b32_e32 v77, 16, v108
	v_mul_f32_e32 v2, 0xbfb8aa3b, v77
	v_exp_f32_e32 v2, v2
	v_mov_b32_e32 v76, v100
	flat_store_dwordx4 v[104:105], v[80:83]
	v_add_f32_e32 v2, 1.0, v2
	v_rcp_f32_e32 v79, v2
	s_nop 0
	v_pk_mul_f32 v[76:77], v[78:79], v[76:77]
	s_nop 0
	v_mul_f32_e32 v2, v76, v77
	v_and_b32_e32 v77, 0xffff0000, v108
	v_mul_f32_e32 v72, 0xbfb8aa3b, v77
	v_exp_f32_e32 v72, v72
	v_mov_b32_e32 v78, v73
	v_mov_b32_e32 v76, v101
	v_add_f32_e32 v72, 1.0, v72
	v_rcp_f32_e32 v79, v72
	s_nop 0
	v_pk_mul_f32 v[72:73], v[78:79], v[76:77]
	s_nop 0
	v_mul_f32_e32 v72, v72, v73
	v_lshlrev_b32_e32 v77, 16, v109
	v_cvt_pk_bf16_f32 v72, v2, v72
	v_mul_f32_e32 v2, 0xbfb8aa3b, v77
	v_exp_f32_e32 v2, v2
	v_mov_b32_e32 v78, v74
	v_mov_b32_e32 v76, v102
	v_add_f32_e32 v2, 1.0, v2
	v_rcp_f32_e32 v79, v2
	s_nop 0
	v_pk_mul_f32 v[76:77], v[78:79], v[76:77]
	s_nop 0
	v_mul_f32_e32 v2, v76, v77
	v_and_b32_e32 v77, 0xffff0000, v109
	v_mul_f32_e32 v73, 0xbfb8aa3b, v77
	v_exp_f32_e32 v73, v73
	v_mov_b32_e32 v78, v75
	v_mov_b32_e32 v76, v103
	v_add_f32_e32 v73, 1.0, v73
	v_rcp_f32_e32 v79, v73
	s_nop 0
	v_pk_mul_f32 v[74:75], v[78:79], v[76:77]
	s_nop 0
	v_mul_f32_e32 v73, v74, v75
	v_lshlrev_b32_e32 v75, 16, v110
	v_cvt_pk_bf16_f32 v73, v2, v73
	v_mul_f32_e32 v2, 0xbfb8aa3b, v75
	v_exp_f32_e32 v2, v2
	v_mov_b32_e32 v76, v68
	v_mov_b32_e32 v74, v92
	v_add_f32_e32 v2, 1.0, v2
	v_rcp_f32_e32 v77, v2
	s_nop 0
	v_pk_mul_f32 v[74:75], v[76:77], v[74:75]
	s_nop 0
	v_mul_f32_e32 v2, v74, v75
	v_and_b32_e32 v75, 0xffff0000, v110
	v_mul_f32_e32 v68, 0xbfb8aa3b, v75
	v_exp_f32_e32 v68, v68
	v_mov_b32_e32 v76, v69
	v_mov_b32_e32 v74, v93
	v_add_f32_e32 v68, 1.0, v68
	v_rcp_f32_e32 v77, v68
	s_nop 0
	v_pk_mul_f32 v[68:69], v[76:77], v[74:75]
	s_nop 0
	v_mul_f32_e32 v68, v68, v69
	v_lshlrev_b32_e32 v69, 16, v111
	v_cvt_pk_bf16_f32 v74, v2, v68
	v_mul_f32_e32 v2, 0xbfb8aa3b, v69
	v_exp_f32_e32 v2, v2
	v_mov_b32_e32 v76, v70
	v_mov_b32_e32 v68, v94
	v_add_f32_e32 v2, 1.0, v2
	v_rcp_f32_e32 v77, v2
	s_nop 0
	v_pk_mul_f32 v[68:69], v[76:77], v[68:69]
	s_nop 0
	v_mul_f32_e32 v2, v68, v69
	v_and_b32_e32 v69, 0xffff0000, v111
	v_mul_f32_e32 v68, 0xbfb8aa3b, v69
	v_exp_f32_e32 v68, v68
	v_mov_b32_e32 v76, v71
	v_add_f32_e32 v68, 1.0, v68
	v_rcp_f32_e32 v77, v68
	v_mov_b32_e32 v68, v95
	v_lshl_add_u64 v[94:95], s[2:3], 0, v[174:175]
	v_pk_mul_f32 v[68:69], v[76:77], v[68:69]
	s_nop 0
	v_mul_f32_e32 v68, v68, v69
	v_cvt_pk_bf16_f32 v75, v2, v68
	v_lshlrev_b64 v[68:69], 12, v[142:143]
	v_lshl_add_u64 v[68:69], s[8:9], 0, v[68:69]
	v_lshl_add_u64 v[92:93], v[68:69], 0, v[140:141]
	flat_store_dwordx4 v[92:93], v[72:75]
	v_lshl_add_u64 v[76:77], v[94:95], 0, v[178:179]
	global_load_dwordx4 v[68:71], v[176:177], off offset:528
	global_load_dwordx4 v[72:75], v[176:177], off offset:512
	flat_load_dwordx4 v[88:91], v[76:77]
	v_lshl_add_u64 v[76:77], v[94:95], 0, v[180:181]
	flat_load_dwordx4 v[84:87], v[76:77]
	v_lshl_add_u64 v[76:77], v[94:95], 0, v[182:183]
	flat_load_dwordx4 v[80:83], v[76:77]
	v_lshl_add_u64 v[76:77], v[94:95], 0, v[184:185]
	flat_load_dwordx4 v[76:79], v[76:77]
	s_waitcnt vmcnt(0) lgkmcnt(0)
; __device__ __forceinline__ size_t pidx(size_t row, int col) { return ((size_t)(col >> 8) * MTOK + row) * PLD + (col & 255); }
; __device__ __forceinline__ float bflo(unsigned v) { return __uint_as_float(v << 16); }
; __device__ __forceinline__ float bfhi(unsigned v) { return __uint_as_float(v & 0xffff0000u); }
; __device__ __forceinline__ float siluf_(float x) { return x * __builtin_amdgcn_rcpf(1.0f + __expf(-x)); }
;   __device__ __forceinline__ void operator()(EPI_ARGS) const {
;     ...
;         for (int m = 0; m < 4; ++m) z[m] = *(const u32x4*)(proj + pidx(row0 + ai * HALF + m * 16, PZ + c));
;         __builtin_amdgcn_sched_barrier(0);
; #pragma unroll
;         for (int m = 0; m < 4; ++m) {
;           const size_t row = row0 + ai * HALF + m * 16;
;           const f32x4 v0 = acc[ai][bj][m][0], v1 = acc[ai][bj][m][1];
;           u32x4 o;
;           o.x = pack2(v0[0] * s0[0] * siluf_(bflo(z[m].x)), v0[1] * s0[1] * siluf_(bfhi(z[m].x)));
;           o.y = pack2(v0[2] * s0[2] * siluf_(bflo(z[m].y)), v0[3] * s0[3] * siluf_(bfhi(z[m].y)));
;           o.z = pack2(v1[0] * s1[0] * siluf_(bflo(z[m].z)), v1[1] * s1[1] * siluf_(bfhi(z[m].z)));
;           o.w = pack2(v1[2] * s1[2] * siluf_(bflo(z[m].w)), v1[3] * s1[3] * siluf_(bfhi(z[m].w)));
;           *(u32x4*)(y0 + row * DM + c) = o;
;         }
	v_lshlrev_b32_e32 v101, 16, v88
	v_mul_f32_e32 v2, 0xbfb8aa3b, v101
	v_exp_f32_e32 v2, v2
	v_mov_b32_e32 v102, v64
	v_mov_b32_e32 v100, v72
	v_add_f32_e32 v2, 1.0, v2
	v_rcp_f32_e32 v103, v2
	s_nop 0
	v_pk_mul_f32 v[100:101], v[102:103], v[100:101]
	s_nop 0
	v_mul_f32_e32 v2, v100, v101
	v_and_b32_e32 v101, 0xffff0000, v88
	v_mul_f32_e32 v64, 0xbfb8aa3b, v101
	v_exp_f32_e32 v64, v64
	v_mov_b32_e32 v102, v65
	v_mov_b32_e32 v100, v73
	v_mov_b32_e32 v88, v75
	v_add_f32_e32 v64, 1.0, v64
	v_rcp_f32_e32 v103, v64
	s_nop 0
	v_pk_mul_f32 v[64:65], v[102:103], v[100:101]
	s_nop 0
	v_mul_f32_e32 v64, v64, v65
	v_lshlrev_b32_e32 v101, 16, v89
	v_cvt_pk_bf16_f32 v64, v2, v64
	v_mul_f32_e32 v2, 0xbfb8aa3b, v101
	v_exp_f32_e32 v2, v2
	v_and_b32_e32 v89, 0xffff0000, v89
	v_mul_f32_e32 v65, 0xbfb8aa3b, v89
	v_exp_f32_e32 v65, v65
	v_add_f32_e32 v2, 1.0, v2
	v_rcp_f32_e32 v103, v2
	v_mov_b32_e32 v102, v66
	v_mov_b32_e32 v100, v74
	v_add_f32_e32 v65, 1.0, v65
	v_pk_mul_f32 v[100:101], v[102:103], v[100:101]
	s_nop 0
	v_mul_f32_e32 v2, v100, v101
	v_rcp_f32_e32 v101, v65
	v_mov_b32_e32 v100, v67
	v_pk_mul_f32 v[66:67], v[100:101], v[88:89]
	s_nop 0
	v_mul_f32_e32 v65, v66, v67
	v_lshlrev_b32_e32 v67, 16, v90
	v_cvt_pk_bf16_f32 v65, v2, v65
	v_mul_f32_e32 v2, 0xbfb8aa3b, v67
	v_exp_f32_e32 v2, v2
	v_mov_b32_e32 v88, v60
	v_mov_b32_e32 v66, v68
	v_add_f32_e32 v2, 1.0, v2
	v_rcp_f32_e32 v89, v2
	s_nop 0
	v_pk_mul_f32 v[66:67], v[88:89], v[66:67]
	s_nop 0
	v_mul_f32_e32 v2, v66, v67
	v_and_b32_e32 v67, 0xffff0000, v90
	v_mul_f32_e32 v60, 0xbfb8aa3b, v67
	v_exp_f32_e32 v60, v60
	v_mov_b32_e32 v88, v61
	v_mov_b32_e32 v66, v69
	v_add_f32_e32 v60, 1.0, v60
	v_rcp_f32_e32 v89, v60
	s_nop 0
	v_pk_mul_f32 v[60:61], v[88:89], v[66:67]
	s_nop 0
	v_mul_f32_e32 v60, v60, v61
	v_lshlrev_b32_e32 v61, 16, v91
	v_cvt_pk_bf16_f32 v66, v2, v60
	v_mul_f32_e32 v2, 0xbfb8aa3b, v61
	v_exp_f32_e32 v2, v2
	v_mov_b32_e32 v88, v62
	v_mov_b32_e32 v60, v70
	v_mov_b32_e32 v62, v56
	v_add_f32_e32 v2, 1.0, v2
	v_rcp_f32_e32 v89, v2
	s_nop 0
	v_pk_mul_f32 v[60:61], v[88:89], v[60:61]
	s_nop 0
	v_mul_f32_e32 v2, v60, v61
	v_and_b32_e32 v61, 0xffff0000, v91
	v_mul_f32_e32 v60, 0xbfb8aa3b, v61
	v_exp_f32_e32 v60, v60
	v_mov_b32_e32 v88, v63
	v_add_f32_e32 v60, 1.0, v60
	v_rcp_f32_e32 v89, v60
	v_mov_b32_e32 v60, v71
	v_pk_mul_f32 v[60:61], v[88:89], v[60:61]
	s_nop 0
	v_mul_f32_e32 v60, v60, v61
	v_lshlrev_b32_e32 v61, 16, v84
	v_cvt_pk_bf16_f32 v67, v2, v60
	v_mul_f32_e32 v2, 0xbfb8aa3b, v61
	v_exp_f32_e32 v2, v2
	v_mov_b32_e32 v60, v72
	flat_store_dwordx4 v[136:137], v[64:67] offset:256
	v_add_f32_e32 v2, 1.0, v2
	v_rcp_f32_e32 v63, v2
	s_nop 0
	v_pk_mul_f32 v[60:61], v[62:63], v[60:61]
	s_nop 0
	v_mul_f32_e32 v2, v60, v61
	v_and_b32_e32 v61, 0xffff0000, v84
	v_mul_f32_e32 v56, 0xbfb8aa3b, v61
	v_exp_f32_e32 v56, v56
	v_mov_b32_e32 v62, v57
	v_mov_b32_e32 v60, v73
	v_add_f32_e32 v56, 1.0, v56
	v_rcp_f32_e32 v63, v56
	s_nop 0
	v_pk_mul_f32 v[56:57], v[62:63], v[60:61]
	s_nop 0
	v_mul_f32_e32 v56, v56, v57
	v_lshlrev_b32_e32 v61, 16, v85
	v_cvt_pk_bf16_f32 v56, v2, v56
	v_mul_f32_e32 v2, 0xbfb8aa3b, v61
	v_exp_f32_e32 v2, v2
	v_mov_b32_e32 v62, v58
	v_mov_b32_e32 v60, v74
	v_add_f32_e32 v2, 1.0, v2
	v_rcp_f32_e32 v63, v2
	s_nop 0
	v_pk_mul_f32 v[60:61], v[62:63], v[60:61]
	s_nop 0
	v_mul_f32_e32 v2, v60, v61
	v_and_b32_e32 v61, 0xffff0000, v85
	v_mul_f32_e32 v57, 0xbfb8aa3b, v61
	v_exp_f32_e32 v57, v57
	v_mov_b32_e32 v62, v59
	v_mov_b32_e32 v60, v75
	v_add_f32_e32 v57, 1.0, v57
	v_rcp_f32_e32 v63, v57
	s_nop 0
	v_pk_mul_f32 v[58:59], v[62:63], v[60:61]
	s_nop 0
	v_mul_f32_e32 v57, v58, v59
	v_lshlrev_b32_e32 v59, 16, v86
	v_cvt_pk_bf16_f32 v57, v2, v57
	v_mul_f32_e32 v2, 0xbfb8aa3b, v59
	v_exp_f32_e32 v2, v2
	v_mov_b32_e32 v60, v52
	v_mov_b32_e32 v58, v68
	v_add_f32_e32 v2, 1.0, v2
	v_rcp_f32_e32 v61, v2
	s_nop 0
	v_pk_mul_f32 v[58:59], v[60:61], v[58:59]
	s_nop 0
	v_mul_f32_e32 v2, v58, v59
	v_and_b32_e32 v59, 0xffff0000, v86
	v_mul_f32_e32 v52, 0xbfb8aa3b, v59
	v_exp_f32_e32 v52, v52
	v_mov_b32_e32 v60, v53
	v_mov_b32_e32 v58, v69
	v_add_f32_e32 v52, 1.0, v52
	v_rcp_f32_e32 v61, v52
	s_nop 0
	v_pk_mul_f32 v[52:53], v[60:61], v[58:59]
	s_nop 0
	v_mul_f32_e32 v52, v52, v53
	v_lshlrev_b32_e32 v53, 16, v87
	v_cvt_pk_bf16_f32 v58, v2, v52
	v_mul_f32_e32 v2, 0xbfb8aa3b, v53
	v_exp_f32_e32 v2, v2
	v_mov_b32_e32 v60, v54
	v_mov_b32_e32 v52, v70
	v_mov_b32_e32 v54, v48
	v_add_f32_e32 v2, 1.0, v2
	v_rcp_f32_e32 v61, v2
	s_nop 0
	v_pk_mul_f32 v[52:53], v[60:61], v[52:53]
	s_nop 0
	v_mul_f32_e32 v2, v52, v53
	v_and_b32_e32 v53, 0xffff0000, v87
	v_mul_f32_e32 v52, 0xbfb8aa3b, v53
	v_exp_f32_e32 v52, v52
	v_mov_b32_e32 v60, v55
	v_add_f32_e32 v52, 1.0, v52
	v_rcp_f32_e32 v61, v52
	v_mov_b32_e32 v52, v71
	v_pk_mul_f32 v[52:53], v[60:61], v[52:53]
	s_nop 0
	v_mul_f32_e32 v52, v52, v53
	v_lshlrev_b32_e32 v53, 16, v80
	v_cvt_pk_bf16_f32 v59, v2, v52
	v_mul_f32_e32 v2, 0xbfb8aa3b, v53
	v_exp_f32_e32 v2, v2
	v_mov_b32_e32 v52, v72
	flat_store_dwordx4 v[124:125], v[56:59] offset:256
	v_add_f32_e32 v2, 1.0, v2
	v_rcp_f32_e32 v55, v2
	s_nop 0
	v_pk_mul_f32 v[52:53], v[54:55], v[52:53]
	s_nop 0
	v_mul_f32_e32 v2, v52, v53
	v_and_b32_e32 v53, 0xffff0000, v80
	v_mul_f32_e32 v48, 0xbfb8aa3b, v53
	v_exp_f32_e32 v48, v48
	v_mov_b32_e32 v54, v49
	v_mov_b32_e32 v52, v73
	v_add_f32_e32 v48, 1.0, v48
	v_rcp_f32_e32 v55, v48
	s_nop 0
	v_pk_mul_f32 v[48:49], v[54:55], v[52:53]
	s_nop 0
	v_mul_f32_e32 v48, v48, v49
	v_lshlrev_b32_e32 v53, 16, v81
	v_cvt_pk_bf16_f32 v48, v2, v48
	v_mul_f32_e32 v2, 0xbfb8aa3b, v53
	v_exp_f32_e32 v2, v2
	v_mov_b32_e32 v54, v50
	v_mov_b32_e32 v52, v74
	v_add_f32_e32 v2, 1.0, v2
	v_rcp_f32_e32 v55, v2
; __device__ __forceinline__ size_t pidx(size_t row, int col) { return ((size_t)(col >> 8) * MTOK + row) * PLD + (col & 255); }
; __device__ __forceinline__ float bflo(unsigned v) { return __uint_as_float(v << 16); }
; __device__ __forceinline__ float bfhi(unsigned v) { return __uint_as_float(v & 0xffff0000u); }
; __device__ __forceinline__ float siluf_(float x) { return x * __builtin_amdgcn_rcpf(1.0f + __expf(-x)); }
;   __device__ __forceinline__ void operator()(EPI_ARGS) const {
;     ...
;         for (int m = 0; m < 4; ++m) z[m] = *(const u32x4*)(proj + pidx(row0 + ai * HALF + m * 16, PZ + c));
;         __builtin_amdgcn_sched_barrier(0);
; #pragma unroll
;         for (int m = 0; m < 4; ++m) {
;           const size_t row = row0 + ai * HALF + m * 16;
;           const f32x4 v0 = acc[ai][bj][m][0], v1 = acc[ai][bj][m][1];
;           u32x4 o;
;           o.x = pack2(v0[0] * s0[0] * siluf_(bflo(z[m].x)), v0[1] * s0[1] * siluf_(bfhi(z[m].x)));
;           o.y = pack2(v0[2] * s0[2] * siluf_(bflo(z[m].y)), v0[3] * s0[3] * siluf_(bfhi(z[m].y)));
;           o.z = pack2(v1[0] * s1[0] * siluf_(bflo(z[m].z)), v1[1] * s1[1] * siluf_(bfhi(z[m].z)));
;           o.w = pack2(v1[2] * s1[2] * siluf_(bflo(z[m].w)), v1[3] * s1[3] * siluf_(bfhi(z[m].w)));
;           *(u32x4*)(y0 + row * DM + c) = o;
;         }
	s_nop 0
	v_pk_mul_f32 v[52:53], v[54:55], v[52:53]
	s_nop 0
	v_mul_f32_e32 v2, v52, v53
	v_and_b32_e32 v53, 0xffff0000, v81
	v_mul_f32_e32 v49, 0xbfb8aa3b, v53
	v_exp_f32_e32 v49, v49
	v_mov_b32_e32 v54, v51
	v_mov_b32_e32 v52, v75
	v_add_f32_e32 v49, 1.0, v49
	v_rcp_f32_e32 v55, v49
	s_nop 0
	v_pk_mul_f32 v[50:51], v[54:55], v[52:53]
	s_nop 0
	v_mul_f32_e32 v49, v50, v51
	v_lshlrev_b32_e32 v51, 16, v82
	v_cvt_pk_bf16_f32 v49, v2, v49
	v_mul_f32_e32 v2, 0xbfb8aa3b, v51
	v_exp_f32_e32 v2, v2
	v_mov_b32_e32 v52, v44
	v_mov_b32_e32 v50, v68
	v_add_f32_e32 v2, 1.0, v2
	v_rcp_f32_e32 v53, v2
	s_nop 0
	v_pk_mul_f32 v[50:51], v[52:53], v[50:51]
	s_nop 0
	v_mul_f32_e32 v2, v50, v51
	v_and_b32_e32 v51, 0xffff0000, v82
	v_mul_f32_e32 v44, 0xbfb8aa3b, v51
	v_exp_f32_e32 v44, v44
	v_mov_b32_e32 v52, v45
	v_mov_b32_e32 v50, v69
	v_add_f32_e32 v44, 1.0, v44
	v_rcp_f32_e32 v53, v44
	s_nop 0
	v_pk_mul_f32 v[44:45], v[52:53], v[50:51]
	s_nop 0
	v_mul_f32_e32 v44, v44, v45
	v_lshlrev_b32_e32 v45, 16, v83
	v_cvt_pk_bf16_f32 v50, v2, v44
	v_mul_f32_e32 v2, 0xbfb8aa3b, v45
	v_exp_f32_e32 v2, v2
	v_mov_b32_e32 v52, v46
	v_mov_b32_e32 v44, v70
	v_mov_b32_e32 v46, v40
	v_add_f32_e32 v2, 1.0, v2
	v_rcp_f32_e32 v53, v2
	s_nop 0
	v_pk_mul_f32 v[44:45], v[52:53], v[44:45]
	s_nop 0
	v_mul_f32_e32 v2, v44, v45
	v_and_b32_e32 v45, 0xffff0000, v83
	v_mul_f32_e32 v44, 0xbfb8aa3b, v45
	v_exp_f32_e32 v44, v44
	v_mov_b32_e32 v52, v47
	v_add_f32_e32 v44, 1.0, v44
	v_rcp_f32_e32 v53, v44
	v_mov_b32_e32 v44, v71
	v_pk_mul_f32 v[44:45], v[52:53], v[44:45]
	s_nop 0
	v_mul_f32_e32 v44, v44, v45
	v_lshlrev_b32_e32 v45, 16, v76
	v_cvt_pk_bf16_f32 v51, v2, v44
	v_mul_f32_e32 v2, 0xbfb8aa3b, v45
	v_exp_f32_e32 v2, v2
	v_mov_b32_e32 v44, v72
	flat_store_dwordx4 v[128:129], v[48:51] offset:256
	v_add_f32_e32 v2, 1.0, v2
	v_rcp_f32_e32 v47, v2
	s_nop 0
	v_pk_mul_f32 v[44:45], v[46:47], v[44:45]
	s_nop 0
	v_mul_f32_e32 v2, v44, v45
	v_and_b32_e32 v45, 0xffff0000, v76
	v_mul_f32_e32 v40, 0xbfb8aa3b, v45
	v_exp_f32_e32 v40, v40
	v_mov_b32_e32 v46, v41
	v_mov_b32_e32 v44, v73
	v_add_f32_e32 v40, 1.0, v40
	v_rcp_f32_e32 v47, v40
	s_nop 0
	v_pk_mul_f32 v[40:41], v[46:47], v[44:45]
	s_nop 0
	v_mul_f32_e32 v40, v40, v41
	v_lshlrev_b32_e32 v45, 16, v77
	v_cvt_pk_bf16_f32 v40, v2, v40
	v_mul_f32_e32 v2, 0xbfb8aa3b, v45
	v_exp_f32_e32 v2, v2
	v_mov_b32_e32 v46, v42
	v_mov_b32_e32 v44, v74
	v_add_f32_e32 v2, 1.0, v2
	v_rcp_f32_e32 v47, v2
	s_nop 0
	v_pk_mul_f32 v[44:45], v[46:47], v[44:45]
	s_nop 0
	v_mul_f32_e32 v2, v44, v45
	v_and_b32_e32 v45, 0xffff0000, v77
	v_mul_f32_e32 v41, 0xbfb8aa3b, v45
	v_exp_f32_e32 v41, v41
	v_mov_b32_e32 v46, v43
	v_mov_b32_e32 v44, v75
	v_add_f32_e32 v41, 1.0, v41
	v_rcp_f32_e32 v47, v41
	s_nop 0
	v_pk_mul_f32 v[42:43], v[46:47], v[44:45]
	s_nop 0
	v_mul_f32_e32 v41, v42, v43
	v_lshlrev_b32_e32 v43, 16, v78
	v_cvt_pk_bf16_f32 v41, v2, v41
	v_mul_f32_e32 v2, 0xbfb8aa3b, v43
	v_exp_f32_e32 v2, v2
	v_mov_b32_e32 v44, v36
	v_mov_b32_e32 v42, v68
	v_add_f32_e32 v2, 1.0, v2
	v_rcp_f32_e32 v45, v2
	s_nop 0
	v_pk_mul_f32 v[42:43], v[44:45], v[42:43]
	s_nop 0
	v_mul_f32_e32 v2, v42, v43
	v_and_b32_e32 v43, 0xffff0000, v78
	v_mul_f32_e32 v36, 0xbfb8aa3b, v43
	v_exp_f32_e32 v36, v36
	v_mov_b32_e32 v44, v37
	v_mov_b32_e32 v42, v69
	v_add_f32_e32 v36, 1.0, v36
	v_rcp_f32_e32 v45, v36
	s_nop 0
	v_pk_mul_f32 v[36:37], v[44:45], v[42:43]
	s_nop 0
	v_mul_f32_e32 v36, v36, v37
	v_lshlrev_b32_e32 v37, 16, v79
	v_cvt_pk_bf16_f32 v42, v2, v36
	v_mul_f32_e32 v2, 0xbfb8aa3b, v37
	v_exp_f32_e32 v2, v2
	v_mov_b32_e32 v44, v38
	v_mov_b32_e32 v36, v70
	v_add_f32_e32 v2, 1.0, v2
	v_rcp_f32_e32 v45, v2
	s_nop 0
	v_pk_mul_f32 v[36:37], v[44:45], v[36:37]
	s_nop 0
	v_mul_f32_e32 v2, v36, v37
	v_and_b32_e32 v37, 0xffff0000, v79
	v_mul_f32_e32 v36, 0xbfb8aa3b, v37
	v_exp_f32_e32 v36, v36
	v_mov_b32_e32 v44, v39
	v_add_f32_e32 v36, 1.0, v36
	v_rcp_f32_e32 v45, v36
	v_mov_b32_e32 v36, v71
	v_pk_mul_f32 v[36:37], v[44:45], v[36:37]
	s_nop 0
	v_mul_f32_e32 v36, v36, v37
	v_cvt_pk_bf16_f32 v43, v2, v36
	flat_store_dwordx4 v[126:127], v[40:43] offset:256
	v_lshl_add_u64 v[36:37], v[94:95], 0, v[130:131]
	flat_load_dwordx4 v[48:51], v[36:37]
	v_lshl_add_u64 v[36:37], v[94:95], 0, v[132:133]
	flat_load_dwordx4 v[44:47], v[36:37]
	v_lshl_add_u64 v[36:37], v[94:95], 0, v[134:135]
	flat_load_dwordx4 v[40:43], v[36:37]
	v_lshl_add_u64 v[36:37], v[94:95], 0, v[138:139]
	flat_load_dwordx4 v[36:39], v[36:37]
	s_waitcnt vmcnt(0) lgkmcnt(0)
; __device__ __forceinline__ size_t pidx(size_t row, int col) { return ((size_t)(col >> 8) * MTOK + row) * PLD + (col & 255); }
; __device__ __forceinline__ float bflo(unsigned v) { return __uint_as_float(v << 16); }
; __device__ __forceinline__ float bfhi(unsigned v) { return __uint_as_float(v & 0xffff0000u); }
; __device__ __forceinline__ float siluf_(float x) { return x * __builtin_amdgcn_rcpf(1.0f + __expf(-x)); }
;   __device__ __forceinline__ void operator()(EPI_ARGS) const {
;     ...
;         for (int m = 0; m < 4; ++m) z[m] = *(const u32x4*)(proj + pidx(row0 + ai * HALF + m * 16, PZ + c));
;         __builtin_amdgcn_sched_barrier(0);
; #pragma unroll
;         for (int m = 0; m < 4; ++m) {
;           const size_t row = row0 + ai * HALF + m * 16;
;           const f32x4 v0 = acc[ai][bj][m][0], v1 = acc[ai][bj][m][1];
;           u32x4 o;
;           o.x = pack2(v0[0] * s0[0] * siluf_(bflo(z[m].x)), v0[1] * s0[1] * siluf_(bfhi(z[m].x)));
;           o.y = pack2(v0[2] * s0[2] * siluf_(bflo(z[m].y)), v0[3] * s0[3] * siluf_(bfhi(z[m].y)));
;           o.z = pack2(v1[0] * s1[0] * siluf_(bflo(z[m].z)), v1[1] * s1[1] * siluf_(bfhi(z[m].z)));
;           o.w = pack2(v1[2] * s1[2] * siluf_(bflo(z[m].w)), v1[3] * s1[3] * siluf_(bfhi(z[m].w)));
;           *(u32x4*)(y0 + row * DM + c) = o;
;         }
	v_lshlrev_b32_e32 v53, 16, v48
	v_mul_f32_e32 v2, 0xbfb8aa3b, v53
	v_exp_f32_e32 v2, v2
	v_mov_b32_e32 v54, v32
	v_mov_b32_e32 v52, v72
	s_and_b64 vcc, exec, s[18:19]
	v_add_f32_e32 v2, 1.0, v2
	v_rcp_f32_e32 v55, v2
	s_mov_b32 s33, s16
	s_mov_b32 s2, s14
	s_mov_b64 s[4:5], s[22:23]
	v_pk_mul_f32 v[52:53], v[54:55], v[52:53]
	v_mov_b32_e32 v54, v33
	v_mul_f32_e32 v2, v52, v53
	v_and_b32_e32 v53, 0xffff0000, v48
	v_mul_f32_e32 v32, 0xbfb8aa3b, v53
	v_exp_f32_e32 v32, v32
	v_mov_b32_e32 v52, v73
	v_mov_b32_e32 v48, v75
	s_mov_b64 s[6:7], s[20:21]
	v_add_f32_e32 v32, 1.0, v32
	v_rcp_f32_e32 v55, v32
	s_nop 0
	v_pk_mul_f32 v[32:33], v[54:55], v[52:53]
	s_nop 0
	v_mul_f32_e32 v32, v32, v33
	v_lshlrev_b32_e32 v53, 16, v49
	v_cvt_pk_bf16_f32 v32, v2, v32
	v_mul_f32_e32 v2, 0xbfb8aa3b, v53
	v_exp_f32_e32 v2, v2
	v_and_b32_e32 v49, 0xffff0000, v49
	v_mul_f32_e32 v33, 0xbfb8aa3b, v49
	v_exp_f32_e32 v33, v33
	v_add_f32_e32 v2, 1.0, v2
	v_rcp_f32_e32 v55, v2
	v_mov_b32_e32 v54, v34
	v_mov_b32_e32 v52, v74
	v_add_f32_e32 v33, 1.0, v33
	v_pk_mul_f32 v[52:53], v[54:55], v[52:53]
	s_nop 0
	v_mul_f32_e32 v2, v52, v53
	v_rcp_f32_e32 v53, v33
	v_mov_b32_e32 v52, v35
	v_pk_mul_f32 v[34:35], v[52:53], v[48:49]
	s_nop 0
	v_mul_f32_e32 v33, v34, v35
	v_lshlrev_b32_e32 v35, 16, v50
	v_cvt_pk_bf16_f32 v33, v2, v33
	v_mul_f32_e32 v2, 0xbfb8aa3b, v35
	v_exp_f32_e32 v2, v2
	v_mov_b32_e32 v48, v28
	v_mov_b32_e32 v34, v68
	v_add_f32_e32 v2, 1.0, v2
	v_rcp_f32_e32 v49, v2
	s_nop 0
	v_pk_mul_f32 v[34:35], v[48:49], v[34:35]
	s_nop 0
	v_mul_f32_e32 v2, v34, v35
	v_and_b32_e32 v35, 0xffff0000, v50
	v_mul_f32_e32 v28, 0xbfb8aa3b, v35
	v_exp_f32_e32 v28, v28
	v_mov_b32_e32 v48, v29
	v_mov_b32_e32 v34, v69
	v_add_f32_e32 v28, 1.0, v28
	v_rcp_f32_e32 v49, v28
	s_nop 0
	v_pk_mul_f32 v[28:29], v[48:49], v[34:35]
	s_nop 0
	v_mul_f32_e32 v28, v28, v29
	v_lshlrev_b32_e32 v29, 16, v51
	v_cvt_pk_bf16_f32 v34, v2, v28
	v_mul_f32_e32 v2, 0xbfb8aa3b, v29
	v_exp_f32_e32 v2, v2
	v_mov_b32_e32 v48, v30
	v_mov_b32_e32 v28, v70
	v_mov_b32_e32 v30, v24
	v_add_f32_e32 v2, 1.0, v2
	v_rcp_f32_e32 v49, v2
	s_nop 0
	v_pk_mul_f32 v[28:29], v[48:49], v[28:29]
	s_nop 0
	v_mul_f32_e32 v2, v28, v29
	v_and_b32_e32 v29, 0xffff0000, v51
	v_mul_f32_e32 v28, 0xbfb8aa3b, v29
	v_exp_f32_e32 v28, v28
	v_mov_b32_e32 v48, v31
	v_add_f32_e32 v28, 1.0, v28
	v_rcp_f32_e32 v49, v28
	v_mov_b32_e32 v28, v71
	v_pk_mul_f32 v[28:29], v[48:49], v[28:29]
	s_nop 0
	v_mul_f32_e32 v28, v28, v29
	v_lshlrev_b32_e32 v29, 16, v44
	v_cvt_pk_bf16_f32 v35, v2, v28
	v_mul_f32_e32 v2, 0xbfb8aa3b, v29
	v_exp_f32_e32 v2, v2
	v_mov_b32_e32 v28, v72
	flat_store_dwordx4 v[96:97], v[32:35] offset:256
	v_add_f32_e32 v2, 1.0, v2
	v_rcp_f32_e32 v31, v2
	s_nop 0
	v_pk_mul_f32 v[28:29], v[30:31], v[28:29]
	s_nop 0
	v_mul_f32_e32 v2, v28, v29
	v_and_b32_e32 v29, 0xffff0000, v44
	v_mul_f32_e32 v24, 0xbfb8aa3b, v29
	v_exp_f32_e32 v24, v24
	v_mov_b32_e32 v30, v25
	v_mov_b32_e32 v28, v73
	v_add_f32_e32 v24, 1.0, v24
	v_rcp_f32_e32 v31, v24
	s_nop 0
	v_pk_mul_f32 v[24:25], v[30:31], v[28:29]
	s_nop 0
	v_mul_f32_e32 v24, v24, v25
	v_lshlrev_b32_e32 v29, 16, v45
	v_cvt_pk_bf16_f32 v24, v2, v24
	v_mul_f32_e32 v2, 0xbfb8aa3b, v29
	v_exp_f32_e32 v2, v2
	v_mov_b32_e32 v30, v26
	v_mov_b32_e32 v28, v74
	v_add_f32_e32 v2, 1.0, v2
	v_rcp_f32_e32 v31, v2
	s_nop 0
	v_pk_mul_f32 v[28:29], v[30:31], v[28:29]
	s_nop 0
	v_mul_f32_e32 v2, v28, v29
	v_and_b32_e32 v29, 0xffff0000, v45
	v_mul_f32_e32 v25, 0xbfb8aa3b, v29
	v_exp_f32_e32 v25, v25
	v_mov_b32_e32 v30, v27
	v_mov_b32_e32 v28, v75
	v_add_f32_e32 v25, 1.0, v25
	v_rcp_f32_e32 v31, v25
	s_nop 0
	v_pk_mul_f32 v[26:27], v[30:31], v[28:29]
	s_nop 0
	v_mul_f32_e32 v25, v26, v27
	v_lshlrev_b32_e32 v27, 16, v46
	v_cvt_pk_bf16_f32 v25, v2, v25
	v_mul_f32_e32 v2, 0xbfb8aa3b, v27
	v_exp_f32_e32 v2, v2
	v_mov_b32_e32 v28, v20
	v_mov_b32_e32 v26, v68
	v_add_f32_e32 v2, 1.0, v2
	v_rcp_f32_e32 v29, v2
	s_nop 0
	v_pk_mul_f32 v[26:27], v[28:29], v[26:27]
	s_nop 0
	v_mul_f32_e32 v2, v26, v27
	v_and_b32_e32 v27, 0xffff0000, v46
	v_mul_f32_e32 v20, 0xbfb8aa3b, v27
	v_exp_f32_e32 v20, v20
	v_mov_b32_e32 v28, v21
	v_mov_b32_e32 v26, v69
	v_add_f32_e32 v20, 1.0, v20
	v_rcp_f32_e32 v29, v20
	s_nop 0
	v_pk_mul_f32 v[20:21], v[28:29], v[26:27]
	s_nop 0
	v_mul_f32_e32 v20, v20, v21
	v_lshlrev_b32_e32 v21, 16, v47
	v_cvt_pk_bf16_f32 v26, v2, v20
	v_mul_f32_e32 v2, 0xbfb8aa3b, v21
	v_exp_f32_e32 v2, v2
	v_mov_b32_e32 v28, v22
	v_mov_b32_e32 v20, v70
	v_mov_b32_e32 v22, v16
	v_add_f32_e32 v2, 1.0, v2
	v_rcp_f32_e32 v29, v2
	s_nop 0
	v_pk_mul_f32 v[20:21], v[28:29], v[20:21]
	s_nop 0
	v_mul_f32_e32 v2, v20, v21
	v_and_b32_e32 v21, 0xffff0000, v47
	v_mul_f32_e32 v20, 0xbfb8aa3b, v21
	v_exp_f32_e32 v20, v20
	v_mov_b32_e32 v28, v23
	v_add_f32_e32 v20, 1.0, v20
	v_rcp_f32_e32 v29, v20
	v_mov_b32_e32 v20, v71
	v_pk_mul_f32 v[20:21], v[28:29], v[20:21]
	s_nop 0
	v_mul_f32_e32 v20, v20, v21
	v_lshlrev_b32_e32 v21, 16, v40
	v_cvt_pk_bf16_f32 v27, v2, v20
	v_mul_f32_e32 v2, 0xbfb8aa3b, v21
	v_exp_f32_e32 v2, v2
	v_mov_b32_e32 v20, v72
	flat_store_dwordx4 v[98:99], v[24:27] offset:256
; __device__ __forceinline__ float bflo(unsigned v) { return __uint_as_float(v << 16); }
; __device__ __forceinline__ float bfhi(unsigned v) { return __uint_as_float(v & 0xffff0000u); }
; __device__ __forceinline__ float siluf_(float x) { return x * __builtin_amdgcn_rcpf(1.0f + __expf(-x)); }
; #define PG8_WAIT_V(n) asm volatile("s_waitcnt vmcnt(" #n ")" ::: "memory")
; #define PG8_BAR __builtin_amdgcn_s_barrier()
; template <class Epi, class AddrA, class AddrB>
; __device__ __forceinline__ void gemm_phase(const Sched S, const int lda, const int ldb, const int K, const AddrA addrA,
;                                            const AddrB addrB, const Epi E) {
;     ...
;   PG8_WAIT_V(0);
;   if (wr == 0) PG8_BAR;
;   PG8_BAR;
;   __device__ __forceinline__ void operator()(EPI_ARGS) const {
;     ...
;         for (int m = 0; m < 4; ++m) {
;           const size_t row = row0 + ai * HALF + m * 16;
;           const f32x4 v0 = acc[ai][bj][m][0], v1 = acc[ai][bj][m][1];
;           u32x4 o;
;           o.x = pack2(v0[0] * s0[0] * siluf_(bflo(z[m].x)), v0[1] * s0[1] * siluf_(bfhi(z[m].x)));
;           o.y = pack2(v0[2] * s0[2] * siluf_(bflo(z[m].y)), v0[3] * s0[3] * siluf_(bfhi(z[m].y)));
;           o.z = pack2(v1[0] * s1[0] * siluf_(bflo(z[m].z)), v1[1] * s1[1] * siluf_(bfhi(z[m].z)));
;           o.w = pack2(v1[2] * s1[2] * siluf_(bflo(z[m].w)), v1[3] * s1[3] * siluf_(bfhi(z[m].w)));
;           *(u32x4*)(y0 + row * DM + c) = o;
;         }
	v_add_f32_e32 v2, 1.0, v2
	v_rcp_f32_e32 v23, v2
	s_nop 0
	v_pk_mul_f32 v[20:21], v[22:23], v[20:21]
	s_nop 0
	v_mul_f32_e32 v2, v20, v21
	v_and_b32_e32 v21, 0xffff0000, v40
	v_mul_f32_e32 v16, 0xbfb8aa3b, v21
	v_exp_f32_e32 v16, v16
	v_mov_b32_e32 v22, v17
	v_mov_b32_e32 v20, v73
	v_add_f32_e32 v16, 1.0, v16
	v_rcp_f32_e32 v23, v16
	s_nop 0
	v_pk_mul_f32 v[16:17], v[22:23], v[20:21]
	s_nop 0
	v_mul_f32_e32 v16, v16, v17
	v_lshlrev_b32_e32 v21, 16, v41
	v_cvt_pk_bf16_f32 v16, v2, v16
	v_mul_f32_e32 v2, 0xbfb8aa3b, v21
	v_exp_f32_e32 v2, v2
	v_mov_b32_e32 v22, v18
	v_mov_b32_e32 v20, v74
	v_add_f32_e32 v2, 1.0, v2
	v_rcp_f32_e32 v23, v2
	s_nop 0
	v_pk_mul_f32 v[20:21], v[22:23], v[20:21]
	s_nop 0
	v_mul_f32_e32 v2, v20, v21
	v_and_b32_e32 v21, 0xffff0000, v41
	v_mul_f32_e32 v17, 0xbfb8aa3b, v21
	v_exp_f32_e32 v17, v17
	v_mov_b32_e32 v22, v19
	v_mov_b32_e32 v20, v75
	v_add_f32_e32 v17, 1.0, v17
	v_rcp_f32_e32 v23, v17
	s_nop 0
	v_pk_mul_f32 v[18:19], v[22:23], v[20:21]
	s_nop 0
	v_mul_f32_e32 v17, v18, v19
	v_lshlrev_b32_e32 v19, 16, v42
	v_cvt_pk_bf16_f32 v17, v2, v17
	v_mul_f32_e32 v2, 0xbfb8aa3b, v19
	v_exp_f32_e32 v2, v2
	v_mov_b32_e32 v20, v12
	v_mov_b32_e32 v18, v68
	v_add_f32_e32 v2, 1.0, v2
	v_rcp_f32_e32 v21, v2
	s_nop 0
	v_pk_mul_f32 v[18:19], v[20:21], v[18:19]
	s_nop 0
	v_mul_f32_e32 v2, v18, v19
	v_and_b32_e32 v19, 0xffff0000, v42
	v_mul_f32_e32 v12, 0xbfb8aa3b, v19
	v_exp_f32_e32 v12, v12
	v_mov_b32_e32 v20, v13
	v_mov_b32_e32 v18, v69
	v_add_f32_e32 v12, 1.0, v12
	v_rcp_f32_e32 v21, v12
	s_nop 0
	v_pk_mul_f32 v[12:13], v[20:21], v[18:19]
	s_nop 0
	v_mul_f32_e32 v12, v12, v13
	v_lshlrev_b32_e32 v13, 16, v43
	v_cvt_pk_bf16_f32 v18, v2, v12
	v_mul_f32_e32 v2, 0xbfb8aa3b, v13
	v_exp_f32_e32 v2, v2
	v_mov_b32_e32 v20, v14
	v_mov_b32_e32 v12, v70
	v_mov_b32_e32 v14, v8
	v_add_f32_e32 v2, 1.0, v2
	v_rcp_f32_e32 v21, v2
	s_nop 0
	v_pk_mul_f32 v[12:13], v[20:21], v[12:13]
	s_nop 0
	v_mul_f32_e32 v2, v12, v13
	v_and_b32_e32 v13, 0xffff0000, v43
	v_mul_f32_e32 v12, 0xbfb8aa3b, v13
	v_exp_f32_e32 v12, v12
	v_mov_b32_e32 v20, v15
	v_add_f32_e32 v12, 1.0, v12
	v_rcp_f32_e32 v21, v12
	v_mov_b32_e32 v12, v71
	v_pk_mul_f32 v[12:13], v[20:21], v[12:13]
	s_nop 0
	v_mul_f32_e32 v12, v12, v13
	v_lshlrev_b32_e32 v13, 16, v36
	v_cvt_pk_bf16_f32 v19, v2, v12
	v_mul_f32_e32 v2, 0xbfb8aa3b, v13
	v_exp_f32_e32 v2, v2
	v_mov_b32_e32 v12, v72
	flat_store_dwordx4 v[104:105], v[16:19] offset:256
	v_add_f32_e32 v2, 1.0, v2
	v_rcp_f32_e32 v15, v2
	s_nop 0
	v_pk_mul_f32 v[12:13], v[14:15], v[12:13]
	s_nop 0
	v_mul_f32_e32 v2, v12, v13
	v_and_b32_e32 v13, 0xffff0000, v36
	v_mul_f32_e32 v8, 0xbfb8aa3b, v13
	v_exp_f32_e32 v8, v8
	v_mov_b32_e32 v14, v9
	v_mov_b32_e32 v12, v73
	v_add_f32_e32 v8, 1.0, v8
	v_rcp_f32_e32 v15, v8
	s_nop 0
	v_pk_mul_f32 v[8:9], v[14:15], v[12:13]
	s_nop 0
	v_mul_f32_e32 v8, v8, v9
	v_lshlrev_b32_e32 v13, 16, v37
	v_cvt_pk_bf16_f32 v8, v2, v8
	v_mul_f32_e32 v2, 0xbfb8aa3b, v13
	v_exp_f32_e32 v2, v2
	v_mov_b32_e32 v14, v10
	v_mov_b32_e32 v12, v74
	v_add_f32_e32 v2, 1.0, v2
	v_rcp_f32_e32 v15, v2
	s_nop 0
	v_pk_mul_f32 v[12:13], v[14:15], v[12:13]
	s_nop 0
	v_mul_f32_e32 v2, v12, v13
	v_and_b32_e32 v13, 0xffff0000, v37
	v_mul_f32_e32 v9, 0xbfb8aa3b, v13
	v_exp_f32_e32 v9, v9
	v_mov_b32_e32 v14, v11
	v_mov_b32_e32 v12, v75
	v_add_f32_e32 v9, 1.0, v9
	v_rcp_f32_e32 v15, v9
	s_nop 0
	v_pk_mul_f32 v[10:11], v[14:15], v[12:13]
	s_nop 0
	v_mul_f32_e32 v9, v10, v11
	v_lshlrev_b32_e32 v11, 16, v38
	v_cvt_pk_bf16_f32 v9, v2, v9
	v_mul_f32_e32 v2, 0xbfb8aa3b, v11
	v_exp_f32_e32 v2, v2
	v_mov_b32_e32 v12, v4
	v_mov_b32_e32 v10, v68
	v_add_f32_e32 v2, 1.0, v2
	v_rcp_f32_e32 v13, v2
	s_nop 0
	v_pk_mul_f32 v[10:11], v[12:13], v[10:11]
	s_nop 0
	v_mul_f32_e32 v2, v10, v11
	v_and_b32_e32 v11, 0xffff0000, v38
	v_mul_f32_e32 v4, 0xbfb8aa3b, v11
	v_exp_f32_e32 v4, v4
	v_mov_b32_e32 v12, v5
	v_mov_b32_e32 v10, v69
	v_add_f32_e32 v4, 1.0, v4
	v_rcp_f32_e32 v13, v4
	s_nop 0
	v_pk_mul_f32 v[4:5], v[12:13], v[10:11]
	s_nop 0
	v_mul_f32_e32 v4, v4, v5
	v_lshlrev_b32_e32 v5, 16, v39
	v_cvt_pk_bf16_f32 v10, v2, v4
	v_mul_f32_e32 v2, 0xbfb8aa3b, v5
	v_exp_f32_e32 v2, v2
	v_mov_b32_e32 v12, v6
	v_mov_b32_e32 v4, v70
	v_add_f32_e32 v2, 1.0, v2
	v_rcp_f32_e32 v13, v2
	s_nop 0
	v_pk_mul_f32 v[4:5], v[12:13], v[4:5]
	s_nop 0
	v_mul_f32_e32 v2, v4, v5
	v_and_b32_e32 v5, 0xffff0000, v39
	v_mul_f32_e32 v4, 0xbfb8aa3b, v5
	v_exp_f32_e32 v4, v4
	v_mov_b32_e32 v12, v7
	v_add_f32_e32 v4, 1.0, v4
	v_rcp_f32_e32 v13, v4
	v_mov_b32_e32 v4, v71
	v_pk_mul_f32 v[4:5], v[12:13], v[4:5]
	s_nop 0
	v_mul_f32_e32 v4, v4, v5
	v_cvt_pk_bf16_f32 v11, v2, v4
	flat_store_dwordx4 v[92:93], v[8:11] offset:256
	s_cbranch_vccz .LBB0_482
	s_waitcnt vmcnt(0)
	v_readlane_b32 s44, v244, 59
	v_readlane_b32 s40, v243, 18
	s_cmpk_gt_u32 s24, 0xff
	s_mov_b32 s43, 0x800000
	v_readlane_b32 s45, v244, 60
	v_readlane_b32 s46, v244, 61
	v_readlane_b32 s47, v244, 62
	v_readlane_b32 s48, v244, 63
	v_readlane_b32 s49, v243, 0
	v_readlane_b32 s50, v243, 1
	v_readlane_b32 s51, v243, 2
	v_readlane_b32 s41, v243, 19
	s_cbranch_scc1 .LBB0_489
	s_barrier

; #define PG8_WAIT_L(n) asm volatile("s_waitcnt lgkmcnt(" #n ")" ::: "memory")
; #define PG8_BAR __builtin_amdgcn_s_barrier()
; #define PG8_SCHED __builtin_amdgcn_sched_barrier(0)
; template <class Epi, class AddrA, class AddrB>
; __device__ __forceinline__ void gemm_phase(const Sched S, const int lda, const int ldb, const int K, const AddrA addrA,
;                                            const AddrB addrB, const Epi E) {
;     ...
;       PG8_LDB(B0, 0, 0); PG8_SCHED; PG8_LDA(At, 0, 0); PG8_STAGE(PG8_SA(1, 1), a1 + hstepA, voffA);
;       PG8_WAIT_L(8); PG8_BAR; PG8_WAIT_L(0); PG8_MMA(0, 0, At, B0); PG8_BAR; PG8_SCHED;
;       PG8_LDB(B1, 0, 1); PG8_STAGE(PG8_SB(0, 0), b2, voffB);
;       PG8_BAR; PG8_WAIT_L(0); PG8_MMA(0, 1, At, B1); PG8_BAR;
;       PG8_LDA(At, 0, 1); PG8_STAGE(PG8_SA(0, 0), a2, voffA);
;       PG8_BAR; PG8_WAIT_L(0); PG8_MMA(1, 0, At, B0); PG8_BAR; PG8_SCHED;
.LBB0_543:
	s_add_u32 s4, s2, 0xfff80080
	s_addc_u32 s5, s3, -1
	s_add_i32 s43, 0, 0x10000
	v_add_u32_e32 v0, s43, v167
	ds_read_b128 v[132:135], v0
	ds_read_b128 v[136:139], v0 offset:1024
	ds_read_b128 v[140:143], v0 offset:2048
	ds_read_b128 v[144:147], v0 offset:3072
	s_cmp_eq_u32 s42, 28
	s_cselect_b32 s7, s1, s5
	s_cselect_b32 s6, s9, s4
	s_cselect_b32 s5, s13, s41
	s_cselect_b32 s4, s15, s33
	v_lshl_add_u64 v[0:1], s[2:3], 0, v[180:181]
	s_add_i32 m0, s28, 0xc000
	ds_read_b128 v[148:151], v188
	ds_read_b128 v[152:155], v188 offset:1024
	ds_read_b128 v[156:159], v188 offset:2048
	ds_read_b128 v[160:163], v188 offset:3072
	ds_read_b128 v[182:185], v188 offset:4096
	ds_read_b128 v[190:193], v188 offset:5120
	ds_read_b128 v[194:197], v188 offset:6144
	ds_read_b128 v[212:215], v188 offset:7168
	global_load_lds_dwordx4 v[0:1], off
	v_lshl_add_u64 v[0:1], s[2:3], 0, v[178:179]
	s_add_i32 m0, s28, 0xe000
	s_nop 0
	global_load_lds_dwordx4 v[0:1], off
	s_waitcnt lgkmcnt(8)
	s_barrier
	s_waitcnt lgkmcnt(0)
	s_setprio 1
	s_waitcnt lgkmcnt(0)
	v_mfma_f32_16x16x32_bf16 v[128:131], v[132:135], v[148:151], v[128:131]
	v_mfma_f32_16x16x32_bf16 v[128:131], v[136:139], v[152:155], v[128:131]
	v_mfma_f32_16x16x32_bf16 v[120:123], v[132:135], v[156:159], v[120:123]
	v_mfma_f32_16x16x32_bf16 v[120:123], v[136:139], v[160:163], v[120:123]
	v_mfma_f32_16x16x32_bf16 v[112:115], v[132:135], v[182:185], v[112:115]
	v_mfma_f32_16x16x32_bf16 v[112:115], v[136:139], v[190:193], v[112:115]
	v_mfma_f32_16x16x32_bf16 v[104:107], v[132:135], v[194:197], v[104:107]
	v_mfma_f32_16x16x32_bf16 v[104:107], v[136:139], v[212:215], v[104:107]
	v_mfma_f32_16x16x32_bf16 v[124:127], v[140:143], v[148:151], v[124:127]
	v_mfma_f32_16x16x32_bf16 v[124:127], v[144:147], v[152:155], v[124:127]
	v_mfma_f32_16x16x32_bf16 v[116:119], v[140:143], v[156:159], v[116:119]
	v_mfma_f32_16x16x32_bf16 v[116:119], v[144:147], v[160:163], v[116:119]
	v_mfma_f32_16x16x32_bf16 v[108:111], v[140:143], v[182:185], v[108:111]
	v_mfma_f32_16x16x32_bf16 v[108:111], v[144:147], v[190:193], v[108:111]
	v_mfma_f32_16x16x32_bf16 v[100:103], v[140:143], v[194:197], v[100:103]
	v_mfma_f32_16x16x32_bf16 v[100:103], v[144:147], v[212:215], v[100:103]
	s_setprio 0
	s_barrier
	s_add_i32 s46, 0, 0x14000
	v_add_u32_e32 v0, s46, v167
	s_add_i32 s43, s43, s27
	ds_read_b128 v[216:219], v0
	ds_read_b128 v[220:223], v0 offset:1024
	ds_read_b128 v[224:227], v0 offset:2048
	ds_read_b128 v[228:231], v0 offset:3072
	v_lshl_add_u64 v[0:1], s[4:5], 0, v[172:173]
	s_mov_b32 m0, s43
	v_lshl_add_u64 v[232:233], s[4:5], 0, v[168:169]
	global_load_lds_dwordx4 v[0:1], off
	s_add_i32 m0, s43, 0x2000
	s_nop 0
	global_load_lds_dwordx4 v[232:233], off
	s_barrier
	s_waitcnt lgkmcnt(0)
	s_setprio 1
	s_waitcnt lgkmcnt(0)
	v_mfma_f32_16x16x32_bf16 v[96:99], v[216:219], v[148:151], v[96:99]
	v_mfma_f32_16x16x32_bf16 v[96:99], v[220:223], v[152:155], v[96:99]
	v_mfma_f32_16x16x32_bf16 v[88:91], v[216:219], v[156:159], v[88:91]
	v_mfma_f32_16x16x32_bf16 v[88:91], v[220:223], v[160:163], v[88:91]
	v_mfma_f32_16x16x32_bf16 v[80:83], v[216:219], v[182:185], v[80:83]
	v_mfma_f32_16x16x32_bf16 v[80:83], v[220:223], v[190:193], v[80:83]
	v_mfma_f32_16x16x32_bf16 v[72:75], v[216:219], v[194:197], v[72:75]
	v_mfma_f32_16x16x32_bf16 v[72:75], v[220:223], v[212:215], v[72:75]
	v_mfma_f32_16x16x32_bf16 v[92:95], v[224:227], v[148:151], v[92:95]
	v_mfma_f32_16x16x32_bf16 v[92:95], v[228:231], v[152:155], v[92:95]
	v_mfma_f32_16x16x32_bf16 v[84:87], v[224:227], v[156:159], v[84:87]
	v_mfma_f32_16x16x32_bf16 v[84:87], v[228:231], v[160:163], v[84:87]
	v_mfma_f32_16x16x32_bf16 v[76:79], v[224:227], v[182:185], v[76:79]
	v_mfma_f32_16x16x32_bf16 v[76:79], v[228:231], v[190:193], v[76:79]
	v_mfma_f32_16x16x32_bf16 v[68:71], v[224:227], v[194:197], v[68:71]
	v_mfma_f32_16x16x32_bf16 v[68:71], v[228:231], v[212:215], v[68:71]
	s_setprio 0
	s_mov_b32 m0, s28
	v_lshl_add_u64 v[234:235], s[6:7], 0, v[174:175]
	s_barrier
	ds_read_b128 v[148:151], v188 offset:16384
	ds_read_b128 v[152:155], v188 offset:17408
	ds_read_b128 v[156:159], v188 offset:18432
	ds_read_b128 v[160:163], v188 offset:19456
	ds_read_b128 v[182:185], v188 offset:20480
	ds_read_b128 v[190:193], v188 offset:21504
	ds_read_b128 v[194:197], v188 offset:22528
	ds_read_b128 v[212:215], v188 offset:23552
	global_load_lds_dwordx4 v[234:235], off
	v_lshl_add_u64 v[236:237], s[6:7], 0, v[170:171]
	s_mov_b32 m0, s29
	s_nop 0
	global_load_lds_dwordx4 v[236:237], off
	s_barrier
	s_waitcnt lgkmcnt(0)
	s_setprio 1
	s_waitcnt lgkmcnt(0)
	v_mfma_f32_16x16x32_bf16 v[64:67], v[132:135], v[148:151], v[64:67]
	v_mfma_f32_16x16x32_bf16 v[64:67], v[136:139], v[152:155], v[64:67]
	v_mfma_f32_16x16x32_bf16 v[56:59], v[132:135], v[156:159], v[56:59]
	v_mfma_f32_16x16x32_bf16 v[56:59], v[136:139], v[160:163], v[56:59]
	v_mfma_f32_16x16x32_bf16 v[48:51], v[132:135], v[182:185], v[48:51]
	v_mfma_f32_16x16x32_bf16 v[48:51], v[136:139], v[190:193], v[48:51]
	v_mfma_f32_16x16x32_bf16 v[40:43], v[132:135], v[194:197], v[40:43]
	v_mfma_f32_16x16x32_bf16 v[40:43], v[136:139], v[212:215], v[40:43]
	v_mfma_f32_16x16x32_bf16 v[60:63], v[140:143], v[148:151], v[60:63]
	v_mfma_f32_16x16x32_bf16 v[60:63], v[144:147], v[152:155], v[60:63]
	v_mfma_f32_16x16x32_bf16 v[52:55], v[140:143], v[156:159], v[52:55]
	v_mfma_f32_16x16x32_bf16 v[52:55], v[144:147], v[160:163], v[52:55]
	v_mfma_f32_16x16x32_bf16 v[44:47], v[140:143], v[182:185], v[44:47]
	v_mfma_f32_16x16x32_bf16 v[44:47], v[144:147], v[190:193], v[44:47]
	v_mfma_f32_16x16x32_bf16 v[36:39], v[140:143], v[194:197], v[36:39]
	v_mfma_f32_16x16x32_bf16 v[36:39], v[144:147], v[212:215], v[36:39]
	s_setprio 0
	s_barrier
; #define PG8_WAIT_V(n) asm volatile("s_waitcnt vmcnt(" #n ")" ::: "memory")
; #define PG8_WAIT_L(n) asm volatile("s_waitcnt lgkmcnt(" #n ")" ::: "memory")
; #define PG8_BAR __builtin_amdgcn_s_barrier()
; #define PG8_SCHED __builtin_amdgcn_sched_barrier(0)
; template <class Epi, class AddrA, class AddrB>
; __device__ __forceinline__ void gemm_phase(const Sched S, const int lda, const int ldb, const int K, const AddrA addrA,
;                                            const AddrB addrB, const Epi E) {
;     ...
;       PG8_STAGE(PG8_SB(0, 1), b2 + hstepB, voffB);
;       PG8_WAIT_V(6); PG8_BAR; PG8_MMA(1, 1, At, B1); PG8_BAR;
;       PG8_LDB(B0, 1, 0); PG8_SCHED; PG8_LDA(At, 1, 0); PG8_STAGE(PG8_SA(0, 1), a2 + hstepA, voffA);
;       PG8_WAIT_L(8); PG8_BAR; PG8_WAIT_L(0); PG8_MMA(0, 0, At, B0); PG8_BAR; PG8_SCHED;
;       PG8_LDB(B1, 1, 1); PG8_STAGE(PG8_SB(1, 0), b3, voffB);
;       PG8_BAR; PG8_WAIT_L(0); PG8_MMA(0, 1, At, B1); PG8_BAR;
;       PG8_LDA(At, 1, 1); PG8_STAGE(PG8_SA(1, 0), a3, voffA);
	s_add_u32 s44, s4, 0x80000
	s_addc_u32 s45, s5, 0
	s_add_i32 s43, s46, s27
	v_lshl_add_u64 v[132:133], s[44:45], 0, v[172:173]
	s_mov_b32 m0, s43
	s_nop 0
	global_load_lds_dwordx4 v[132:133], off
	v_lshl_add_u64 v[132:133], s[44:45], 0, v[168:169]
	s_add_i32 m0, s43, 0x2000
	s_nop 0
	global_load_lds_dwordx4 v[132:133], off
	s_waitcnt vmcnt(6)
	s_barrier
	s_setprio 1
	v_mfma_f32_16x16x32_bf16 v[32:35], v[216:219], v[148:151], v[32:35]
	v_mfma_f32_16x16x32_bf16 v[32:35], v[220:223], v[152:155], v[32:35]
	v_mfma_f32_16x16x32_bf16 v[24:27], v[216:219], v[156:159], v[24:27]
	v_mfma_f32_16x16x32_bf16 v[24:27], v[220:223], v[160:163], v[24:27]
	v_mfma_f32_16x16x32_bf16 v[16:19], v[216:219], v[182:185], v[16:19]
	v_mfma_f32_16x16x32_bf16 v[16:19], v[220:223], v[190:193], v[16:19]
	v_mfma_f32_16x16x32_bf16 v[8:11], v[216:219], v[194:197], v[8:11]
	v_mfma_f32_16x16x32_bf16 v[8:11], v[220:223], v[212:215], v[8:11]
	v_mfma_f32_16x16x32_bf16 v[28:31], v[224:227], v[148:151], v[28:31]
	v_mfma_f32_16x16x32_bf16 v[28:31], v[228:231], v[152:155], v[28:31]
	v_mfma_f32_16x16x32_bf16 v[20:23], v[224:227], v[156:159], v[20:23]
	v_mfma_f32_16x16x32_bf16 v[20:23], v[228:231], v[160:163], v[20:23]
	v_mfma_f32_16x16x32_bf16 v[12:15], v[224:227], v[182:185], v[12:15]
	v_mfma_f32_16x16x32_bf16 v[12:15], v[228:231], v[190:193], v[12:15]
	v_mfma_f32_16x16x32_bf16 v[4:7], v[224:227], v[194:197], v[4:7]
	v_mfma_f32_16x16x32_bf16 v[4:7], v[228:231], v[212:215], v[4:7]
	s_setprio 0
	s_add_i32 s43, 0, 0x18000
	v_add_u32_e32 v2, s43, v167
	s_barrier
	ds_read_b128 v[132:135], v2
	ds_read_b128 v[136:139], v2 offset:1024
	ds_read_b128 v[140:143], v2 offset:2048
	ds_read_b128 v[144:147], v2 offset:3072
	s_add_u32 s6, s6, 0x80000
	s_addc_u32 s7, s7, 0
	s_mov_b32 m0, s30
	v_lshl_add_u64 v[216:217], s[6:7], 0, v[174:175]
	ds_read_b128 v[148:151], v188 offset:32768
	ds_read_b128 v[152:155], v188 offset:33792
	ds_read_b128 v[156:159], v188 offset:34816
	ds_read_b128 v[160:163], v188 offset:35840
	ds_read_b128 v[182:185], v188 offset:36864
	ds_read_b128 v[190:193], v188 offset:37888
	ds_read_b128 v[194:197], v188 offset:38912
	ds_read_b128 v[212:215], v188 offset:39936
	global_load_lds_dwordx4 v[216:217], off
	v_lshl_add_u64 v[216:217], s[6:7], 0, v[170:171]
	s_mov_b32 m0, s31
	s_nop 0
	global_load_lds_dwordx4 v[216:217], off
	s_waitcnt lgkmcnt(8)
	s_barrier
	s_waitcnt lgkmcnt(0)
	s_setprio 1
	s_waitcnt lgkmcnt(0)
	v_mfma_f32_16x16x32_bf16 v[128:131], v[132:135], v[148:151], v[128:131]
	v_mfma_f32_16x16x32_bf16 v[128:131], v[136:139], v[152:155], v[128:131]
	v_mfma_f32_16x16x32_bf16 v[120:123], v[132:135], v[156:159], v[120:123]
	v_mfma_f32_16x16x32_bf16 v[120:123], v[136:139], v[160:163], v[120:123]
	v_mfma_f32_16x16x32_bf16 v[112:115], v[132:135], v[182:185], v[112:115]
	v_mfma_f32_16x16x32_bf16 v[112:115], v[136:139], v[190:193], v[112:115]
	v_mfma_f32_16x16x32_bf16 v[104:107], v[132:135], v[194:197], v[104:107]
	v_mfma_f32_16x16x32_bf16 v[104:107], v[136:139], v[212:215], v[104:107]
	v_mfma_f32_16x16x32_bf16 v[124:127], v[140:143], v[148:151], v[124:127]
	v_mfma_f32_16x16x32_bf16 v[124:127], v[144:147], v[152:155], v[124:127]
	v_mfma_f32_16x16x32_bf16 v[116:119], v[140:143], v[156:159], v[116:119]
	v_mfma_f32_16x16x32_bf16 v[116:119], v[144:147], v[160:163], v[116:119]
	v_mfma_f32_16x16x32_bf16 v[108:111], v[140:143], v[182:185], v[108:111]
	v_mfma_f32_16x16x32_bf16 v[108:111], v[144:147], v[190:193], v[108:111]
	v_mfma_f32_16x16x32_bf16 v[100:103], v[140:143], v[194:197], v[100:103]
	v_mfma_f32_16x16x32_bf16 v[100:103], v[144:147], v[212:215], v[100:103]
	s_setprio 0
	s_barrier
	s_add_i32 s6, 0, 0x1c000
	s_add_i32 s7, s43, s27
	v_add_u32_e32 v2, s6, v167
	v_lshl_add_u64 v[0:1], v[0:1], 0, s[52:53]
	s_mov_b32 m0, s7
	ds_read_b128 v[216:219], v2
	ds_read_b128 v[220:223], v2 offset:1024
	ds_read_b128 v[224:227], v2 offset:2048
	ds_read_b128 v[228:231], v2 offset:3072
	global_load_lds_dwordx4 v[0:1], off
	v_lshl_add_u64 v[0:1], v[232:233], 0, s[52:53]
	s_add_i32 m0, s7, 0x2000
	s_nop 0
	global_load_lds_dwordx4 v[0:1], off
	s_barrier
	s_waitcnt lgkmcnt(0)
	s_setprio 1
	s_waitcnt lgkmcnt(0)
	v_mfma_f32_16x16x32_bf16 v[96:99], v[216:219], v[148:151], v[96:99]
	v_mfma_f32_16x16x32_bf16 v[96:99], v[220:223], v[152:155], v[96:99]
	v_mfma_f32_16x16x32_bf16 v[88:91], v[216:219], v[156:159], v[88:91]
	v_mfma_f32_16x16x32_bf16 v[88:91], v[220:223], v[160:163], v[88:91]
	v_mfma_f32_16x16x32_bf16 v[80:83], v[216:219], v[182:185], v[80:83]
	v_mfma_f32_16x16x32_bf16 v[80:83], v[220:223], v[190:193], v[80:83]
	v_mfma_f32_16x16x32_bf16 v[72:75], v[216:219], v[194:197], v[72:75]
	v_mfma_f32_16x16x32_bf16 v[72:75], v[220:223], v[212:215], v[72:75]
	v_mfma_f32_16x16x32_bf16 v[92:95], v[224:227], v[148:151], v[92:95]
	v_mfma_f32_16x16x32_bf16 v[92:95], v[228:231], v[152:155], v[92:95]
	v_mfma_f32_16x16x32_bf16 v[84:87], v[224:227], v[156:159], v[84:87]
	v_mfma_f32_16x16x32_bf16 v[84:87], v[228:231], v[160:163], v[84:87]
	v_mfma_f32_16x16x32_bf16 v[76:79], v[224:227], v[182:185], v[76:79]
	v_mfma_f32_16x16x32_bf16 v[76:79], v[228:231], v[190:193], v[76:79]
	v_mfma_f32_16x16x32_bf16 v[68:71], v[224:227], v[194:197], v[68:71]
	v_mfma_f32_16x16x32_bf16 v[68:71], v[228:231], v[212:215], v[68:71]
	s_setprio 0
	s_mov_b32 m0, s38
	v_lshl_add_u64 v[0:1], v[234:235], 0, s[52:53]
	s_barrier
	ds_read_b128 v[148:151], v188 offset:49152
	ds_read_b128 v[152:155], v188 offset:50176
	ds_read_b128 v[156:159], v188 offset:51200
	ds_read_b128 v[160:163], v188 offset:52224
	ds_read_b128 v[182:185], v188 offset:53248
	ds_read_b128 v[190:193], v188 offset:54272
	ds_read_b128 v[194:197], v188 offset:55296
	ds_read_b128 v[212:215], v188 offset:56320
	global_load_lds_dwordx4 v[0:1], off
	v_lshl_add_u64 v[0:1], v[236:237], 0, s[52:53]
	s_mov_b32 m0, s39
	s_nop 0
	global_load_lds_dwordx4 v[0:1], off
	s_barrier
; #define PG8_WAIT_V(n) asm volatile("s_waitcnt vmcnt(" #n ")" ::: "memory")
; #define PG8_WAIT_L(n) asm volatile("s_waitcnt lgkmcnt(" #n ")" ::: "memory")
; #define PG8_BAR __builtin_amdgcn_s_barrier()
; #define PG8_SCHED __builtin_amdgcn_sched_barrier(0)
; template <class Epi, class AddrA, class AddrB>
; __device__ __forceinline__ void gemm_phase(const Sched S, const int lda, const int ldb, const int K, const AddrA addrA,
;                                            const AddrB addrB, const Epi E) {
;     ...
;       PG8_BAR; PG8_WAIT_L(0); PG8_MMA(1, 0, At, B0); PG8_BAR; PG8_SCHED;
;       PG8_STAGE(PG8_SB(1, 1), b3 + hstepB, voffB);
;       PG8_WAIT_V(6); PG8_BAR; PG8_MMA(1, 1, At, B1); PG8_BAR;
;   __device__ __forceinline__ void operator()(EPI_ARGS) const {
;     const int col0 = u.pn * 256 + wc * 32 + 8 * fq;
;     const int br = u.br, brn = br < 2 ? br + 1 : 2;
;     const unsigned loff0 = (unsigned)((wr * 64 + fr) * PLD + wc * 32 + 8 * fq);
;     const bf16_t* pc = proj + ((size_t)((GT + br * DM) / 256 + u.pn) * MTOK + (size_t)u.pm * 256) * PLD;
;     const bf16_t* pn_ = proj + ((size_t)((GT + brn * DM) / 256 + u.pn) * MTOK + (size_t)u.pm * 256) * PLD;
;     bf16_t* mrow = merged + ((size_t)u.pm * 256 + wr * 64 + fr) * DM + col0;
; #pragma unroll
;     for (int bj = 0; bj < 2; ++bj) {
;       const int c = col0 + bj * HALF;
;       float gc[8], gn[8];
;       {
;         const f32x4 a0 = *(const f32x4*)(bg + br * DM + c), a1 = *(const f32x4*)(bg + br * DM + c + 4);
;         const f32x4 b0 = *(const f32x4*)(bg + brn * DM + c), b1 = *(const f32x4*)(bg + brn * DM + c + 4);
; #pragma unroll
;         for (int k = 0; k < 4; ++k) { gc[k] = a0[k]; gc[4 + k] = a1[k]; gn[k] = b0[k]; gn[4 + k] = b1[k]; }
;       }
; #pragma unroll
;       for (int ai = 0; ai < 2; ++ai) {
;         unsigned loff = loff0;
;         asm volatile("" : "+v"(loff));
;         u32x4 zc[4], zn[4];
; #pragma unroll
;         for (int m = 0; m < 4; ++m) {
;           const unsigned o = loff + (unsigned)((ai * HALF + m * 16) * PLD + bj * HALF);
;           zc[m] = *(const u32x4*)(pc + o);
;           zn[m] = *(const u32x4*)(pn_ + o);
;         }
	s_waitcnt lgkmcnt(0)
	s_setprio 1
	s_waitcnt lgkmcnt(0)
	v_mfma_f32_16x16x32_bf16 v[64:67], v[132:135], v[148:151], v[64:67]
	v_mfma_f32_16x16x32_bf16 v[64:67], v[136:139], v[152:155], v[64:67]
	v_mfma_f32_16x16x32_bf16 v[56:59], v[132:135], v[156:159], v[56:59]
	v_mfma_f32_16x16x32_bf16 v[56:59], v[136:139], v[160:163], v[56:59]
	v_mfma_f32_16x16x32_bf16 v[48:51], v[132:135], v[182:185], v[48:51]
	v_mfma_f32_16x16x32_bf16 v[48:51], v[136:139], v[190:193], v[48:51]
	v_mfma_f32_16x16x32_bf16 v[40:43], v[132:135], v[194:197], v[40:43]
	v_mfma_f32_16x16x32_bf16 v[40:43], v[136:139], v[212:215], v[40:43]
	v_mfma_f32_16x16x32_bf16 v[60:63], v[140:143], v[148:151], v[60:63]
	v_mfma_f32_16x16x32_bf16 v[60:63], v[144:147], v[152:155], v[60:63]
	v_mfma_f32_16x16x32_bf16 v[52:55], v[140:143], v[156:159], v[52:55]
	v_mfma_f32_16x16x32_bf16 v[52:55], v[144:147], v[160:163], v[52:55]
	v_mfma_f32_16x16x32_bf16 v[44:47], v[140:143], v[182:185], v[44:47]
	v_mfma_f32_16x16x32_bf16 v[44:47], v[144:147], v[190:193], v[44:47]
	v_mfma_f32_16x16x32_bf16 v[36:39], v[140:143], v[194:197], v[36:39]
	v_mfma_f32_16x16x32_bf16 v[36:39], v[144:147], v[212:215], v[36:39]
	s_setprio 0
	s_barrier
	s_add_u32 s4, s4, 0x80080
	s_addc_u32 s5, s5, 0
	s_add_i32 s6, s6, s27
	v_lshl_add_u64 v[0:1], s[4:5], 0, v[172:173]
	s_mov_b32 m0, s6
	s_nop 0
	global_load_lds_dwordx4 v[0:1], off
	v_lshl_add_u64 v[0:1], s[4:5], 0, v[168:169]
	s_add_i32 m0, s6, 0x2000
	s_nop 0
	global_load_lds_dwordx4 v[0:1], off
	s_waitcnt vmcnt(6)
	s_barrier
	s_setprio 1
	v_mfma_f32_16x16x32_bf16 v[32:35], v[216:219], v[148:151], v[32:35]
	v_mfma_f32_16x16x32_bf16 v[32:35], v[220:223], v[152:155], v[32:35]
	v_mfma_f32_16x16x32_bf16 v[24:27], v[216:219], v[156:159], v[24:27]
	v_mfma_f32_16x16x32_bf16 v[24:27], v[220:223], v[160:163], v[24:27]
	v_mfma_f32_16x16x32_bf16 v[16:19], v[216:219], v[182:185], v[16:19]
	v_mfma_f32_16x16x32_bf16 v[16:19], v[220:223], v[190:193], v[16:19]
	v_mfma_f32_16x16x32_bf16 v[8:11], v[216:219], v[194:197], v[8:11]
	v_mfma_f32_16x16x32_bf16 v[8:11], v[220:223], v[212:215], v[8:11]
	v_mfma_f32_16x16x32_bf16 v[28:31], v[224:227], v[148:151], v[28:31]
	v_mfma_f32_16x16x32_bf16 v[28:31], v[228:231], v[152:155], v[28:31]
	v_mfma_f32_16x16x32_bf16 v[20:23], v[224:227], v[156:159], v[20:23]
	v_mfma_f32_16x16x32_bf16 v[20:23], v[228:231], v[160:163], v[20:23]
	v_mfma_f32_16x16x32_bf16 v[12:15], v[224:227], v[182:185], v[12:15]
	v_mfma_f32_16x16x32_bf16 v[12:15], v[228:231], v[190:193], v[12:15]
	v_mfma_f32_16x16x32_bf16 v[4:7], v[224:227], v[194:197], v[4:7]
	v_mfma_f32_16x16x32_bf16 v[4:7], v[228:231], v[212:215], v[4:7]
	s_setprio 0
	s_add_i32 s42, s42, 2
	s_add_u32 s33, s33, 0x100
	s_addc_u32 s41, s41, 0
	s_add_u32 s2, s2, 0x100
	s_addc_u32 s3, s3, 0
	s_cmp_gt_u32 s42, 29
	s_barrier
	s_cbranch_scc0 .LBB0_543
	s_cmp_gt_i32 s10, 1
	s_cselect_b64 s[6:7], -1, 0
	s_lshl_b32 s42, s10, 11
	s_add_i32 s2, s42, 0x4c00
	s_ashr_i32 s2, s2, 8
	s_add_i32 s2, s2, s11
	s_ashr_i32 s3, s2, 31
	s_min_i32 s1, s10, 1
	s_ashr_i32 s9, s8, 31
	s_lshl_b64 s[2:3], s[2:3], 23
	s_add_u32 s2, s34, s2
	s_addc_u32 s3, s35, s3
	s_lshl_b64 s[4:5], s[8:9], 17
	s_add_u32 s2, s2, s4
	s_addc_u32 s3, s3, s5
	s_lshl_b32 s1, s1, 11
	s_add_i32 s44, s1, 0x800
	s_addk_i32 s1, 0x5400
	s_ashr_i32 s1, s1, 8
	s_add_i32 s46, s1, s11
	s_ashr_i32 s47, s46, 31
	s_lshl_b64 s[46:47], s[46:47], 23
	s_add_u32 s1, s34, s46
	v_lshl_or_b32 v132, s11, 8, v187
	s_addc_u32 s11, s35, s47
	s_add_u32 s4, s1, s4
	s_addc_u32 s5, s11, s5
	s_ashr_i32 s43, s42, 31
	s_lshl_b64 s[8:9], s[8:9], 20
	s_ashr_i32 s45, s44, 31
	s_lshl_b64 s[42:43], s[42:43], 2
	s_add_u32 s42, s36, s42
	s_addc_u32 s43, s37, s43
	s_lshl_b64 s[44:45], s[44:45], 2
	s_add_u32 s44, s36, s44
	v_lshl_add_u64 v[0:1], v[176:177], 0, s[8:9]
	v_ashrrev_i32_e32 v133, 31, v132
	s_addc_u32 s45, s37, s45
	v_lshl_add_u64 v[0:1], v[132:133], 1, v[0:1]
	v_lshlrev_b64 v[132:133], 2, v[132:133]
	v_lshl_add_u64 v[182:183], s[42:43], 0, v[132:133]
	v_lshl_add_u64 v[184:185], s[44:45], 0, v[132:133]
	v_mov_b32_e32 v2, v186
	global_load_dwordx4 v[144:147], v[182:183], off
	global_load_dwordx4 v[136:139], v[182:183], off offset:16
	global_load_dwordx4 v[140:143], v[184:185], off
	global_load_dwordx4 v[132:135], v[184:185], off offset:16
	s_cmp_lt_i32 s10, 2
	v_lshlrev_b64 v[148:149], 1, v[2:3]
	v_lshl_add_u64 v[150:151], s[2:3], 0, v[148:149]
	v_lshl_add_u64 v[148:149], s[4:5], 0, v[148:149]
	flat_load_dwordx4 v[190:193], v[150:151]
	flat_load_dwordx4 v[160:163], v[148:149]
	v_add_u32_e32 v148, 0x1000, v2
	v_mov_b32_e32 v149, v3
	v_lshlrev_b64 v[148:149], 1, v[148:149]
	v_lshl_add_u64 v[150:151], s[2:3], 0, v[148:149]
	v_lshl_add_u64 v[148:149], s[4:5], 0, v[148:149]
	flat_load_dwordx4 v[194:197], v[150:151]
	flat_load_dwordx4 v[156:159], v[148:149]
	v_add_u32_e32 v148, 0x2000, v2
	v_mov_b32_e32 v149, v3
	v_lshlrev_b64 v[148:149], 1, v[148:149]
	v_lshl_add_u64 v[150:151], s[2:3], 0, v[148:149]
	v_lshl_add_u64 v[148:149], s[4:5], 0, v[148:149]
	v_add_u32_e32 v2, 0x3000, v2
	flat_load_dwordx4 v[234:237], v[150:151]
	flat_load_dwordx4 v[152:155], v[148:149]
	v_lshlrev_b64 v[148:149], 1, v[2:3]
	v_lshl_add_u64 v[150:151], s[2:3], 0, v[148:149]
	v_lshl_add_u64 v[148:149], s[4:5], 0, v[148:149]
	flat_load_dwordx4 v[238:241], v[150:151]
	s_nop 0
	flat_load_dwordx4 v[148:151], v[148:149]
	s_waitcnt vmcnt(0) lgkmcnt(0)
; __device__ __forceinline__ float sigmoidf_(float x) { return __builtin_amdgcn_rcpf(1.0f + __expf(-x)); }
;   __device__ __forceinline__ void operator()(EPI_ARGS) const {
;     ...
;         if (br < 2) {
; #pragma unroll
;           for (int m = 0; m < 4; ++m) {
;             float xc[8], xn[8];
;             unpack8(zc[m], xc);
;             unpack8(zn[m], xn);
; #pragma unroll
;             for (int k = 0; k < 8; ++k) {
;               const float ec = __expf(-fmaxf(xc[k] + gc[k], -40.f)), en = __expf(-fmaxf(xn[k] + gn[k], -40.f));
;               const float f = (1.0f + en) * __builtin_amdgcn_rcpf(1.0f + ec);
;               acc[ai][bj][m][k >> 2][k & 3] *= f;
;             }
;           }
;         } else {
; #pragma unroll
;           for (int m = 0; m < 4; ++m) {
;             float xc[8], y[8];
;             unpack8(zc[m], xc);
; #pragma unroll
;             for (int k = 0; k < 8; ++k) y[k] = acc[ai][bj][m][k >> 2][k & 3] * sigmoidf_(fmaxf(xc[k] + gc[k], -40.f));
;             u32x4 o;
;             o.x = pack2(y[0], y[1]); o.y = pack2(y[2], y[3]); o.z = pack2(y[4], y[5]); o.w = pack2(y[6], y[7]);
;             *(u32x4*)(mrow + (size_t)(ai * HALF + m * 16) * DM + bj * HALF) = o;
;           }
	v_lshlrev_b32_e32 v2, 16, v190
	v_and_b32_e32 v189, 0xffff0000, v190
	v_lshlrev_b32_e32 v190, 16, v191
	v_and_b32_e32 v191, 0xffff0000, v191
	v_lshlrev_b32_e32 v212, 16, v192
	v_and_b32_e32 v192, 0xffff0000, v192
	v_lshlrev_b32_e32 v213, 16, v193
	v_and_b32_e32 v193, 0xffff0000, v193
	v_add_f32_e32 v2, v144, v2
	v_add_f32_e32 v189, v145, v189
	v_add_f32_e32 v190, v146, v190
	v_add_f32_e32 v191, v147, v191
	v_add_f32_e32 v212, v136, v212
	v_add_f32_e32 v192, v137, v192
	v_add_f32_e32 v213, v138, v213
	v_add_f32_e32 v193, v139, v193
	s_mov_b64 s[8:9], -1
	v_max_f32_e32 v233, 0xc2200000, v2
	v_max_f32_e32 v232, 0xc2200000, v189
	v_max_f32_e32 v231, 0xc2200000, v190
	v_max_f32_e32 v230, 0xc2200000, v191
	v_max_f32_e32 v229, 0xc2200000, v212
	v_max_f32_e32 v228, 0xc2200000, v192
	v_max_f32_e32 v227, 0xc2200000, v213
	v_max_f32_e32 v226, 0xc2200000, v193
	v_lshlrev_b32_e32 v225, 16, v194
	v_and_b32_e32 v224, 0xffff0000, v194
	v_lshlrev_b32_e32 v223, 16, v195
	v_and_b32_e32 v222, 0xffff0000, v195
	v_lshlrev_b32_e32 v221, 16, v196
	v_and_b32_e32 v220, 0xffff0000, v196
	v_lshlrev_b32_e32 v219, 16, v197
	v_and_b32_e32 v218, 0xffff0000, v197
	v_lshlrev_b32_e32 v217, 16, v234
	v_and_b32_e32 v216, 0xffff0000, v234
	v_lshlrev_b32_e32 v215, 16, v235
	v_and_b32_e32 v214, 0xffff0000, v235
	v_lshlrev_b32_e32 v213, 16, v236
	v_and_b32_e32 v212, 0xffff0000, v236
	v_lshlrev_b32_e32 v197, 16, v237
	v_and_b32_e32 v196, 0xffff0000, v237
	v_lshlrev_b32_e32 v195, 16, v238
	v_and_b32_e32 v194, 0xffff0000, v238
	v_lshlrev_b32_e32 v193, 16, v239
	v_and_b32_e32 v192, 0xffff0000, v239
	v_lshlrev_b32_e32 v191, 16, v240
	v_and_b32_e32 v190, 0xffff0000, v240
	v_lshlrev_b32_e32 v189, 16, v241
	v_and_b32_e32 v2, 0xffff0000, v241
	s_cbranch_scc1 .LBB0_546
	v_mul_f32_e32 v234, 0xbfb8aa3b, v233
	v_mul_f32_e32 v235, 0xbfb8aa3b, v232
	v_mul_f32_e32 v236, 0xbfb8aa3b, v231
	v_exp_f32_e32 v234, v234
	v_exp_f32_e32 v235, v235
	v_exp_f32_e32 v236, v236
	v_mul_f32_e32 v237, 0xbfb8aa3b, v230
	v_exp_f32_e32 v237, v237
	v_mul_f32_e32 v238, 0xbfb8aa3b, v229
	v_mul_f32_e32 v239, 0xbfb8aa3b, v228
	v_add_f32_e32 v234, 1.0, v234
	v_add_f32_e32 v235, 1.0, v235
	v_add_f32_e32 v236, 1.0, v236
	v_exp_f32_e32 v238, v238
	v_exp_f32_e32 v239, v239
	v_mul_f32_e32 v240, 0xbfb8aa3b, v227
	v_mul_f32_e32 v241, 0xbfb8aa3b, v226
	v_rcp_f32_e32 v234, v234
	v_rcp_f32_e32 v235, v235
	v_rcp_f32_e32 v236, v236
	v_add_f32_e32 v237, 1.0, v237
	v_exp_f32_e32 v240, v240
	v_exp_f32_e32 v241, v241
	v_rcp_f32_e32 v237, v237
	v_add_f32_e32 v238, 1.0, v238
	v_add_f32_e32 v239, 1.0, v239
	v_mul_f32_e32 v234, v128, v234
	v_mul_f32_e32 v235, v129, v235
	v_mul_f32_e32 v236, v130, v236
	v_rcp_f32_e32 v238, v238
	v_rcp_f32_e32 v239, v239
	v_add_f32_e32 v240, 1.0, v240
	v_add_f32_e32 v241, 1.0, v241
	v_mul_f32_e32 v237, v131, v237
	v_rcp_f32_e32 v240, v240
	v_rcp_f32_e32 v241, v241
	v_cvt_pk_bf16_f32 v234, v234, v235
	v_cvt_pk_bf16_f32 v235, v236, v237
	v_add_f32_e32 v236, v144, v225
	v_max_f32_e32 v236, 0xc2200000, v236
	v_mul_f32_e32 v236, 0xbfb8aa3b, v236
	v_mul_f32_e32 v238, v124, v238
	v_mul_f32_e32 v239, v125, v239
	v_exp_f32_e32 v242, v236
	v_cvt_pk_bf16_f32 v236, v238, v239
	v_mul_f32_e32 v240, v126, v240
	v_mul_f32_e32 v241, v127, v241
	v_cvt_pk_bf16_f32 v237, v240, v241
	flat_store_dwordx4 v[0:1], v[234:237]
	v_add_f32_e32 v238, v136, v221
	v_max_f32_e32 v238, 0xc2200000, v238
	v_add_f32_e32 v235, v145, v224
	v_add_f32_e32 v236, v146, v223
	v_max_f32_e32 v235, 0xc2200000, v235
	v_max_f32_e32 v236, 0xc2200000, v236
	v_add_f32_e32 v237, v147, v222
	v_add_f32_e32 v239, v137, v220
	v_mul_f32_e32 v235, 0xbfb8aa3b, v235
	v_mul_f32_e32 v236, 0xbfb8aa3b, v236
	v_max_f32_e32 v237, 0xc2200000, v237
	v_mul_f32_e32 v238, 0xbfb8aa3b, v238
	v_max_f32_e32 v239, 0xc2200000, v239
	v_exp_f32_e32 v235, v235
	v_exp_f32_e32 v236, v236
	v_mul_f32_e32 v237, 0xbfb8aa3b, v237
	v_exp_f32_e32 v238, v238
	v_mul_f32_e32 v239, 0xbfb8aa3b, v239
	v_add_f32_e32 v240, v138, v219
	v_exp_f32_e32 v237, v237
	v_exp_f32_e32 v239, v239
	v_max_f32_e32 v240, 0xc2200000, v240
	v_add_f32_e32 v241, v139, v218
	v_mul_f32_e32 v240, 0xbfb8aa3b, v240
	v_max_f32_e32 v241, 0xc2200000, v241
	v_exp_f32_e32 v240, v240
	v_mul_f32_e32 v241, 0xbfb8aa3b, v241
	v_add_f32_e32 v234, 1.0, v242
	v_add_f32_e32 v235, 1.0, v235
	v_add_f32_e32 v236, 1.0, v236
	v_add_f32_e32 v238, 1.0, v238
	v_exp_f32_e32 v241, v241
	v_rcp_f32_e32 v234, v234
	v_rcp_f32_e32 v235, v235
	v_rcp_f32_e32 v236, v236
	v_add_f32_e32 v237, 1.0, v237
	v_rcp_f32_e32 v238, v238
	v_add_f32_e32 v239, 1.0, v239
	v_rcp_f32_e32 v237, v237
	v_rcp_f32_e32 v239, v239
	v_add_f32_e32 v240, 1.0, v240
	v_rcp_f32_e32 v240, v240
	v_add_f32_e32 v241, 1.0, v241
	v_mul_f32_e32 v234, v120, v234
; __device__ __forceinline__ float sigmoidf_(float x) { return __builtin_amdgcn_rcpf(1.0f + __expf(-x)); }
;   __device__ __forceinline__ void operator()(EPI_ARGS) const {
;     ...
; #pragma unroll
;           for (int m = 0; m < 4; ++m) {
;             float xc[8], y[8];
;             unpack8(zc[m], xc);
; #pragma unroll
;             for (int k = 0; k < 8; ++k) y[k] = acc[ai][bj][m][k >> 2][k & 3] * sigmoidf_(fmaxf(xc[k] + gc[k], -40.f));
;             u32x4 o;
;             o.x = pack2(y[0], y[1]); o.y = pack2(y[2], y[3]); o.z = pack2(y[4], y[5]); o.w = pack2(y[6], y[7]);
;             *(u32x4*)(mrow + (size_t)(ai * HALF + m * 16) * DM + bj * HALF) = o;
;           }
	v_mul_f32_e32 v235, v121, v235
	v_mul_f32_e32 v236, v122, v236
	v_rcp_f32_e32 v241, v241
	v_mul_f32_e32 v238, v116, v238
	v_mul_f32_e32 v237, v123, v237
	v_mul_f32_e32 v239, v117, v239
	v_cvt_pk_bf16_f32 v234, v234, v235
	v_cvt_pk_bf16_f32 v235, v236, v237
	v_cvt_pk_bf16_f32 v236, v238, v239
	v_add_f32_e32 v238, v144, v217
	v_max_f32_e32 v238, 0xc2200000, v238
	v_mul_f32_e32 v240, v118, v240
	v_mul_f32_e32 v238, 0xbfb8aa3b, v238
	v_mul_f32_e32 v241, v119, v241
	v_cvt_pk_bf16_f32 v237, v240, v241
	v_exp_f32_e32 v240, v238
	v_add_co_u32_e32 v238, vcc, s67, v0
	v_add_f32_e32 v241, v139, v196
	s_nop 0
	v_addc_co_u32_e32 v239, vcc, 0, v1, vcc
	flat_store_dwordx4 v[238:239], v[234:237]
	v_add_f32_e32 v238, v136, v213
	v_max_f32_e32 v238, 0xc2200000, v238
	v_add_f32_e32 v235, v145, v216
	v_add_f32_e32 v236, v146, v215
	v_max_f32_e32 v235, 0xc2200000, v235
	v_max_f32_e32 v236, 0xc2200000, v236
	v_add_f32_e32 v237, v147, v214
	v_add_f32_e32 v239, v137, v212
	v_mul_f32_e32 v235, 0xbfb8aa3b, v235
	v_mul_f32_e32 v236, 0xbfb8aa3b, v236
	v_max_f32_e32 v237, 0xc2200000, v237
	v_mul_f32_e32 v238, 0xbfb8aa3b, v238
	v_max_f32_e32 v239, 0xc2200000, v239
	v_add_f32_e32 v234, 1.0, v240
	v_exp_f32_e32 v235, v235
	v_exp_f32_e32 v236, v236
	v_mul_f32_e32 v237, 0xbfb8aa3b, v237
	v_exp_f32_e32 v238, v238
	v_mul_f32_e32 v239, 0xbfb8aa3b, v239
	v_add_f32_e32 v240, v138, v197
	v_exp_f32_e32 v237, v237
	v_exp_f32_e32 v239, v239
	v_max_f32_e32 v240, 0xc2200000, v240
	v_mul_f32_e32 v240, 0xbfb8aa3b, v240
	v_max_f32_e32 v241, 0xc2200000, v241
	v_exp_f32_e32 v240, v240
	v_mul_f32_e32 v241, 0xbfb8aa3b, v241
	v_add_f32_e32 v235, 1.0, v235
	v_add_f32_e32 v236, 1.0, v236
	v_add_f32_e32 v238, 1.0, v238
	v_exp_f32_e32 v241, v241
	v_rcp_f32_e32 v234, v234
	v_rcp_f32_e32 v235, v235
	v_rcp_f32_e32 v236, v236
	v_add_f32_e32 v237, 1.0, v237
	v_rcp_f32_e32 v238, v238
	v_add_f32_e32 v239, 1.0, v239
	v_rcp_f32_e32 v237, v237
	v_rcp_f32_e32 v239, v239
	v_add_f32_e32 v240, 1.0, v240
	v_rcp_f32_e32 v240, v240
	v_add_f32_e32 v241, 1.0, v241
	v_mul_f32_e32 v234, v112, v234
	v_mul_f32_e32 v235, v113, v235
	v_mul_f32_e32 v236, v114, v236
	v_rcp_f32_e32 v241, v241
	v_mul_f32_e32 v238, v108, v238
	v_mul_f32_e32 v237, v115, v237
	v_mul_f32_e32 v239, v109, v239
	v_cvt_pk_bf16_f32 v234, v234, v235
	v_cvt_pk_bf16_f32 v235, v236, v237
	v_cvt_pk_bf16_f32 v236, v238, v239
	v_add_f32_e32 v238, v144, v195
	v_max_f32_e32 v238, 0xc2200000, v238
	v_mul_f32_e32 v240, v110, v240
	v_mul_f32_e32 v238, 0xbfb8aa3b, v238
	s_mov_b32 s1, 0x20000
	v_mul_f32_e32 v241, v111, v241
	v_cvt_pk_bf16_f32 v237, v240, v241
	v_exp_f32_e32 v240, v238
	v_add_co_u32_e32 v238, vcc, s1, v0
	v_add_f32_e32 v241, v139, v2
	s_nop 0
	v_addc_co_u32_e32 v239, vcc, 0, v1, vcc
	flat_store_dwordx4 v[238:239], v[234:237]
	v_add_f32_e32 v238, v136, v191
	v_max_f32_e32 v238, 0xc2200000, v238
	v_add_f32_e32 v235, v145, v194
	v_add_f32_e32 v236, v146, v193
	v_max_f32_e32 v235, 0xc2200000, v235
	v_max_f32_e32 v236, 0xc2200000, v236
	v_add_f32_e32 v237, v147, v192
	v_add_f32_e32 v239, v137, v190
	v_mul_f32_e32 v235, 0xbfb8aa3b, v235
	v_mul_f32_e32 v236, 0xbfb8aa3b, v236
	v_max_f32_e32 v237, 0xc2200000, v237
	v_mul_f32_e32 v238, 0xbfb8aa3b, v238
	v_max_f32_e32 v239, 0xc2200000, v239
	v_add_f32_e32 v234, 1.0, v240
	v_exp_f32_e32 v235, v235
	v_exp_f32_e32 v236, v236
	v_mul_f32_e32 v237, 0xbfb8aa3b, v237
	v_exp_f32_e32 v238, v238
	v_mul_f32_e32 v239, 0xbfb8aa3b, v239
	v_add_f32_e32 v240, v138, v189
	v_exp_f32_e32 v237, v237
	v_exp_f32_e32 v239, v239
	v_max_f32_e32 v240, 0xc2200000, v240
	v_max_f32_e32 v241, 0xc2200000, v241
	v_mul_f32_e32 v240, 0xbfb8aa3b, v240
	v_mul_f32_e32 v241, 0xbfb8aa3b, v241
	v_exp_f32_e32 v240, v240
	v_exp_f32_e32 v241, v241
	v_add_f32_e32 v235, 1.0, v235
	v_add_f32_e32 v236, 1.0, v236
	v_add_f32_e32 v238, 1.0, v238
	v_rcp_f32_e32 v234, v234
	v_rcp_f32_e32 v235, v235
	v_rcp_f32_e32 v236, v236
	v_add_f32_e32 v237, 1.0, v237
	v_rcp_f32_e32 v238, v238
	v_add_f32_e32 v239, 1.0, v239
	v_rcp_f32_e32 v237, v237
	v_rcp_f32_e32 v239, v239
	v_add_f32_e32 v240, 1.0, v240
	v_add_f32_e32 v241, 1.0, v241
	v_rcp_f32_e32 v240, v240
	v_rcp_f32_e32 v241, v241
	v_mul_f32_e32 v234, v104, v234
	v_mul_f32_e32 v235, v105, v235
	v_mul_f32_e32 v236, v106, v236
	v_mul_f32_e32 v238, v100, v238
	v_mul_f32_e32 v237, v107, v237
	v_mul_f32_e32 v239, v101, v239
	v_cvt_pk_bf16_f32 v234, v234, v235
	v_cvt_pk_bf16_f32 v235, v236, v237
	v_cvt_pk_bf16_f32 v236, v238, v239
	v_add_co_u32_e32 v238, vcc, 0x30000, v0
	s_mov_b64 s[8:9], 0
	s_nop 0
	v_addc_co_u32_e32 v239, vcc, 0, v1, vcc
	v_mul_f32_e32 v240, v102, v240
	v_mul_f32_e32 v241, v103, v241
	v_cvt_pk_bf16_f32 v237, v240, v241
	flat_store_dwordx4 v[238:239], v[234:237]

; #define PG8_WAIT_L(n) asm volatile("s_waitcnt lgkmcnt(" #n ")" ::: "memory")
; #define PG8_BAR __builtin_amdgcn_s_barrier()
; #define PG8_SCHED __builtin_amdgcn_sched_barrier(0)
; template <class Epi, class AddrA, class AddrB>
; __device__ __forceinline__ void gemm_phase(const Sched S, const int lda, const int ldb, const int K, const AddrA addrA,
;                                            const AddrB addrB, const Epi E) {
;     ...
;       PG8_LDB(B0, 0, 0); PG8_SCHED; PG8_LDA(At, 0, 0); PG8_STAGE(PG8_SA(1, 1), a1 + hstepA, voffA);
;       PG8_WAIT_L(8); PG8_BAR; PG8_WAIT_L(0); PG8_MMA(0, 0, At, B0); PG8_BAR; PG8_SCHED;
;       PG8_LDB(B1, 0, 1); PG8_STAGE(PG8_SB(0, 0), b2, voffB);
;       PG8_BAR; PG8_WAIT_L(0); PG8_MMA(0, 1, At, B1); PG8_BAR;
;       PG8_LDA(At, 0, 1); PG8_STAGE(PG8_SA(0, 0), a2, voffA);
;       PG8_BAR; PG8_WAIT_L(0); PG8_MMA(1, 0, At, B0); PG8_BAR; PG8_SCHED;
.LBB0_619:
	s_add_u32 s16, s14, 0xfff80080
	s_addc_u32 s17, s15, -1
	s_add_i32 s39, 0, 0x10000
	v_add_u32_e32 v142, s39, v144
	ds_read_b128 v[148:151], v142
	ds_read_b128 v[152:155], v142 offset:1024
	ds_read_b128 v[156:159], v142 offset:2048
	ds_read_b128 v[160:163], v142 offset:3072
	s_cmp_eq_u32 s38, 28
	s_cselect_b32 s19, s3, s17
	s_cselect_b32 s18, s13, s16
	s_cselect_b32 s17, s5, s37
	s_cselect_b32 s16, s35, s36
	v_lshl_add_u64 v[142:143], s[14:15], 0, v[140:141]
	s_add_i32 m0, s26, 0xc000
	ds_read_b128 v[168:171], v146
	ds_read_b128 v[172:175], v146 offset:1024
	ds_read_b128 v[176:179], v146 offset:2048
	ds_read_b128 v[180:183], v146 offset:3072
	ds_read_b128 v[184:187], v146 offset:4096
	ds_read_b128 v[188:191], v146 offset:5120
	ds_read_b128 v[192:195], v146 offset:6144
	ds_read_b128 v[212:215], v146 offset:7168
	global_load_lds_dwordx4 v[142:143], off
	v_lshl_add_u64 v[142:143], s[14:15], 0, v[138:139]
	s_add_i32 m0, s26, 0xe000
	s_nop 0
	global_load_lds_dwordx4 v[142:143], off
	s_waitcnt lgkmcnt(8)
	s_barrier
	s_waitcnt lgkmcnt(0)
	s_setprio 1
	s_waitcnt lgkmcnt(0)
	v_mfma_f32_16x16x32_bf16 v[128:131], v[148:151], v[168:171], v[128:131]
	v_mfma_f32_16x16x32_bf16 v[128:131], v[152:155], v[172:175], v[128:131]
	v_mfma_f32_16x16x32_bf16 v[120:123], v[148:151], v[176:179], v[120:123]
	v_mfma_f32_16x16x32_bf16 v[120:123], v[152:155], v[180:183], v[120:123]
	v_mfma_f32_16x16x32_bf16 v[112:115], v[148:151], v[184:187], v[112:115]
	v_mfma_f32_16x16x32_bf16 v[112:115], v[152:155], v[188:191], v[112:115]
	v_mfma_f32_16x16x32_bf16 v[104:107], v[148:151], v[192:195], v[104:107]
	v_mfma_f32_16x16x32_bf16 v[104:107], v[152:155], v[212:215], v[104:107]
	v_mfma_f32_16x16x32_bf16 v[124:127], v[156:159], v[168:171], v[124:127]
	v_mfma_f32_16x16x32_bf16 v[124:127], v[160:163], v[172:175], v[124:127]
	v_mfma_f32_16x16x32_bf16 v[116:119], v[156:159], v[176:179], v[116:119]
	v_mfma_f32_16x16x32_bf16 v[116:119], v[160:163], v[180:183], v[116:119]
	v_mfma_f32_16x16x32_bf16 v[108:111], v[156:159], v[184:187], v[108:111]
	v_mfma_f32_16x16x32_bf16 v[108:111], v[160:163], v[188:191], v[108:111]
	v_mfma_f32_16x16x32_bf16 v[100:103], v[156:159], v[192:195], v[100:103]
	v_mfma_f32_16x16x32_bf16 v[100:103], v[160:163], v[212:215], v[100:103]
	s_setprio 0
	s_barrier
	s_add_i32 s42, 0, 0x14000
	v_add_u32_e32 v142, s42, v144
	s_add_i32 s39, s39, s25
	ds_read_b128 v[216:219], v142
	ds_read_b128 v[220:223], v142 offset:1024
	ds_read_b128 v[224:227], v142 offset:2048
	ds_read_b128 v[228:231], v142 offset:3072
	v_lshl_add_u64 v[142:143], s[16:17], 0, v[2:3]
	s_mov_b32 m0, s39
	v_lshl_add_u64 v[196:197], s[16:17], 0, v[0:1]
	global_load_lds_dwordx4 v[142:143], off
	s_add_i32 m0, s39, 0x2000
	s_nop 0
	global_load_lds_dwordx4 v[196:197], off
	s_barrier
	s_waitcnt lgkmcnt(0)
	s_setprio 1
	s_waitcnt lgkmcnt(0)
	v_mfma_f32_16x16x32_bf16 v[96:99], v[216:219], v[168:171], v[96:99]
	v_mfma_f32_16x16x32_bf16 v[96:99], v[220:223], v[172:175], v[96:99]
	v_mfma_f32_16x16x32_bf16 v[88:91], v[216:219], v[176:179], v[88:91]
	v_mfma_f32_16x16x32_bf16 v[88:91], v[220:223], v[180:183], v[88:91]
	v_mfma_f32_16x16x32_bf16 v[80:83], v[216:219], v[184:187], v[80:83]
	v_mfma_f32_16x16x32_bf16 v[80:83], v[220:223], v[188:191], v[80:83]
	v_mfma_f32_16x16x32_bf16 v[72:75], v[216:219], v[192:195], v[72:75]
	v_mfma_f32_16x16x32_bf16 v[72:75], v[220:223], v[212:215], v[72:75]
	v_mfma_f32_16x16x32_bf16 v[92:95], v[224:227], v[168:171], v[92:95]
	v_mfma_f32_16x16x32_bf16 v[92:95], v[228:231], v[172:175], v[92:95]
	v_mfma_f32_16x16x32_bf16 v[84:87], v[224:227], v[176:179], v[84:87]
	v_mfma_f32_16x16x32_bf16 v[84:87], v[228:231], v[180:183], v[84:87]
	v_mfma_f32_16x16x32_bf16 v[76:79], v[224:227], v[184:187], v[76:79]
	v_mfma_f32_16x16x32_bf16 v[76:79], v[228:231], v[188:191], v[76:79]
	v_mfma_f32_16x16x32_bf16 v[68:71], v[224:227], v[192:195], v[68:71]
	v_mfma_f32_16x16x32_bf16 v[68:71], v[228:231], v[212:215], v[68:71]
	s_setprio 0
	s_mov_b32 m0, s26
	v_lshl_add_u64 v[232:233], s[18:19], 0, v[134:135]
	s_barrier
	ds_read_b128 v[168:171], v146 offset:16384
	ds_read_b128 v[172:175], v146 offset:17408
	ds_read_b128 v[176:179], v146 offset:18432
	ds_read_b128 v[180:183], v146 offset:19456
	ds_read_b128 v[184:187], v146 offset:20480
	ds_read_b128 v[188:191], v146 offset:21504
	ds_read_b128 v[192:195], v146 offset:22528
	ds_read_b128 v[212:215], v146 offset:23552
	global_load_lds_dwordx4 v[232:233], off
	v_lshl_add_u64 v[234:235], s[18:19], 0, v[132:133]
	s_mov_b32 m0, s27
	s_nop 0
	global_load_lds_dwordx4 v[234:235], off
	s_barrier
	s_waitcnt lgkmcnt(0)
	s_setprio 1
	s_waitcnt lgkmcnt(0)
	v_mfma_f32_16x16x32_bf16 v[64:67], v[148:151], v[168:171], v[64:67]
	v_mfma_f32_16x16x32_bf16 v[64:67], v[152:155], v[172:175], v[64:67]
	v_mfma_f32_16x16x32_bf16 v[56:59], v[148:151], v[176:179], v[56:59]
	v_mfma_f32_16x16x32_bf16 v[56:59], v[152:155], v[180:183], v[56:59]
	v_mfma_f32_16x16x32_bf16 v[48:51], v[148:151], v[184:187], v[48:51]
	v_mfma_f32_16x16x32_bf16 v[48:51], v[152:155], v[188:191], v[48:51]
	v_mfma_f32_16x16x32_bf16 v[40:43], v[148:151], v[192:195], v[40:43]
	v_mfma_f32_16x16x32_bf16 v[40:43], v[152:155], v[212:215], v[40:43]
	v_mfma_f32_16x16x32_bf16 v[60:63], v[156:159], v[168:171], v[60:63]
	v_mfma_f32_16x16x32_bf16 v[60:63], v[160:163], v[172:175], v[60:63]
	v_mfma_f32_16x16x32_bf16 v[52:55], v[156:159], v[176:179], v[52:55]
	v_mfma_f32_16x16x32_bf16 v[52:55], v[160:163], v[180:183], v[52:55]
	v_mfma_f32_16x16x32_bf16 v[44:47], v[156:159], v[184:187], v[44:47]
	v_mfma_f32_16x16x32_bf16 v[44:47], v[160:163], v[188:191], v[44:47]
	v_mfma_f32_16x16x32_bf16 v[36:39], v[156:159], v[192:195], v[36:39]
	v_mfma_f32_16x16x32_bf16 v[36:39], v[160:163], v[212:215], v[36:39]
	s_setprio 0
	s_barrier
; #define PG8_WAIT_V(n) asm volatile("s_waitcnt vmcnt(" #n ")" ::: "memory")
; #define PG8_WAIT_L(n) asm volatile("s_waitcnt lgkmcnt(" #n ")" ::: "memory")
; #define PG8_BAR __builtin_amdgcn_s_barrier()
; #define PG8_SCHED __builtin_amdgcn_sched_barrier(0)
; template <class Epi, class AddrA, class AddrB>
; __device__ __forceinline__ void gemm_phase(const Sched S, const int lda, const int ldb, const int K, const AddrA addrA,
;                                            const AddrB addrB, const Epi E) {
;     ...
;       PG8_STAGE(PG8_SB(0, 1), b2 + hstepB, voffB);
;       PG8_WAIT_V(6); PG8_BAR; PG8_MMA(1, 1, At, B1); PG8_BAR;
;       PG8_LDB(B0, 1, 0); PG8_SCHED; PG8_LDA(At, 1, 0); PG8_STAGE(PG8_SA(0, 1), a2 + hstepA, voffA);
;       PG8_WAIT_L(8); PG8_BAR; PG8_WAIT_L(0); PG8_MMA(0, 0, At, B0); PG8_BAR; PG8_SCHED;
;       PG8_LDB(B1, 1, 1); PG8_STAGE(PG8_SB(1, 0), b3, voffB);
;       PG8_BAR; PG8_WAIT_L(0); PG8_MMA(0, 1, At, B1); PG8_BAR;
;       PG8_LDA(At, 1, 1); PG8_STAGE(PG8_SA(1, 0), a3, voffA);
	s_add_u32 s40, s16, 0x80000
	s_addc_u32 s41, s17, 0
	s_add_i32 s39, s42, s25
	v_lshl_add_u64 v[148:149], s[40:41], 0, v[2:3]
	s_mov_b32 m0, s39
	s_nop 0
	global_load_lds_dwordx4 v[148:149], off
	v_lshl_add_u64 v[148:149], s[40:41], 0, v[0:1]
	s_add_i32 m0, s39, 0x2000
	s_nop 0
	global_load_lds_dwordx4 v[148:149], off
	s_waitcnt vmcnt(6)
	s_barrier
	s_setprio 1
	v_mfma_f32_16x16x32_bf16 v[32:35], v[216:219], v[168:171], v[32:35]
	v_mfma_f32_16x16x32_bf16 v[32:35], v[220:223], v[172:175], v[32:35]
	v_mfma_f32_16x16x32_bf16 v[24:27], v[216:219], v[176:179], v[24:27]
	v_mfma_f32_16x16x32_bf16 v[24:27], v[220:223], v[180:183], v[24:27]
	v_mfma_f32_16x16x32_bf16 v[16:19], v[216:219], v[184:187], v[16:19]
	v_mfma_f32_16x16x32_bf16 v[16:19], v[220:223], v[188:191], v[16:19]
	v_mfma_f32_16x16x32_bf16 v[8:11], v[216:219], v[192:195], v[8:11]
	v_mfma_f32_16x16x32_bf16 v[8:11], v[220:223], v[212:215], v[8:11]
	v_mfma_f32_16x16x32_bf16 v[28:31], v[224:227], v[168:171], v[28:31]
	v_mfma_f32_16x16x32_bf16 v[28:31], v[228:231], v[172:175], v[28:31]
	v_mfma_f32_16x16x32_bf16 v[20:23], v[224:227], v[176:179], v[20:23]
	v_mfma_f32_16x16x32_bf16 v[20:23], v[228:231], v[180:183], v[20:23]
	v_mfma_f32_16x16x32_bf16 v[12:15], v[224:227], v[184:187], v[12:15]
	v_mfma_f32_16x16x32_bf16 v[12:15], v[228:231], v[188:191], v[12:15]
	v_mfma_f32_16x16x32_bf16 v[4:7], v[224:227], v[192:195], v[4:7]
	v_mfma_f32_16x16x32_bf16 v[4:7], v[228:231], v[212:215], v[4:7]
	s_setprio 0
	s_add_i32 s39, 0, 0x18000
	v_add_u32_e32 v147, s39, v144
	s_barrier
	ds_read_b128 v[148:151], v147
	ds_read_b128 v[152:155], v147 offset:1024
	ds_read_b128 v[156:159], v147 offset:2048
	ds_read_b128 v[160:163], v147 offset:3072
	s_add_u32 s18, s18, 0x80000
	s_addc_u32 s19, s19, 0
	s_mov_b32 m0, s28
	v_lshl_add_u64 v[216:217], s[18:19], 0, v[134:135]
	ds_read_b128 v[168:171], v146 offset:32768
	ds_read_b128 v[172:175], v146 offset:33792
	ds_read_b128 v[176:179], v146 offset:34816
	ds_read_b128 v[180:183], v146 offset:35840
	ds_read_b128 v[184:187], v146 offset:36864
	ds_read_b128 v[188:191], v146 offset:37888
	ds_read_b128 v[192:195], v146 offset:38912
	ds_read_b128 v[212:215], v146 offset:39936
	global_load_lds_dwordx4 v[216:217], off
	v_lshl_add_u64 v[216:217], s[18:19], 0, v[132:133]
	s_mov_b32 m0, s29
	s_nop 0
	global_load_lds_dwordx4 v[216:217], off
	s_waitcnt lgkmcnt(8)
	s_barrier
	s_waitcnt lgkmcnt(0)
	s_setprio 1
	s_waitcnt lgkmcnt(0)
	v_mfma_f32_16x16x32_bf16 v[128:131], v[148:151], v[168:171], v[128:131]
	v_mfma_f32_16x16x32_bf16 v[128:131], v[152:155], v[172:175], v[128:131]
	v_mfma_f32_16x16x32_bf16 v[120:123], v[148:151], v[176:179], v[120:123]
	v_mfma_f32_16x16x32_bf16 v[120:123], v[152:155], v[180:183], v[120:123]
	v_mfma_f32_16x16x32_bf16 v[112:115], v[148:151], v[184:187], v[112:115]
	v_mfma_f32_16x16x32_bf16 v[112:115], v[152:155], v[188:191], v[112:115]
	v_mfma_f32_16x16x32_bf16 v[104:107], v[148:151], v[192:195], v[104:107]
	v_mfma_f32_16x16x32_bf16 v[104:107], v[152:155], v[212:215], v[104:107]
	v_mfma_f32_16x16x32_bf16 v[124:127], v[156:159], v[168:171], v[124:127]
	v_mfma_f32_16x16x32_bf16 v[124:127], v[160:163], v[172:175], v[124:127]
	v_mfma_f32_16x16x32_bf16 v[116:119], v[156:159], v[176:179], v[116:119]
	v_mfma_f32_16x16x32_bf16 v[116:119], v[160:163], v[180:183], v[116:119]
	v_mfma_f32_16x16x32_bf16 v[108:111], v[156:159], v[184:187], v[108:111]
	v_mfma_f32_16x16x32_bf16 v[108:111], v[160:163], v[188:191], v[108:111]
	v_mfma_f32_16x16x32_bf16 v[100:103], v[156:159], v[192:195], v[100:103]
	v_mfma_f32_16x16x32_bf16 v[100:103], v[160:163], v[212:215], v[100:103]
	s_setprio 0
	s_barrier
	s_add_i32 s18, 0, 0x1c000
	s_add_i32 s19, s39, s25
	v_add_u32_e32 v147, s18, v144
	v_lshl_add_u64 v[142:143], v[142:143], 0, s[52:53]
	s_mov_b32 m0, s19
	ds_read_b128 v[216:219], v147
	ds_read_b128 v[220:223], v147 offset:1024
	ds_read_b128 v[224:227], v147 offset:2048
	ds_read_b128 v[228:231], v147 offset:3072
	global_load_lds_dwordx4 v[142:143], off
	v_lshl_add_u64 v[142:143], v[196:197], 0, s[52:53]
	s_add_i32 m0, s19, 0x2000
	s_nop 0
	global_load_lds_dwordx4 v[142:143], off
	s_barrier
	s_waitcnt lgkmcnt(0)
	s_setprio 1
	s_waitcnt lgkmcnt(0)
	v_mfma_f32_16x16x32_bf16 v[96:99], v[216:219], v[168:171], v[96:99]
	v_mfma_f32_16x16x32_bf16 v[96:99], v[220:223], v[172:175], v[96:99]
	v_mfma_f32_16x16x32_bf16 v[88:91], v[216:219], v[176:179], v[88:91]
	v_mfma_f32_16x16x32_bf16 v[88:91], v[220:223], v[180:183], v[88:91]
	v_mfma_f32_16x16x32_bf16 v[80:83], v[216:219], v[184:187], v[80:83]
	v_mfma_f32_16x16x32_bf16 v[80:83], v[220:223], v[188:191], v[80:83]
	v_mfma_f32_16x16x32_bf16 v[72:75], v[216:219], v[192:195], v[72:75]
	v_mfma_f32_16x16x32_bf16 v[72:75], v[220:223], v[212:215], v[72:75]
	v_mfma_f32_16x16x32_bf16 v[92:95], v[224:227], v[168:171], v[92:95]
	v_mfma_f32_16x16x32_bf16 v[92:95], v[228:231], v[172:175], v[92:95]
	v_mfma_f32_16x16x32_bf16 v[84:87], v[224:227], v[176:179], v[84:87]
	v_mfma_f32_16x16x32_bf16 v[84:87], v[228:231], v[180:183], v[84:87]
	v_mfma_f32_16x16x32_bf16 v[76:79], v[224:227], v[184:187], v[76:79]
	v_mfma_f32_16x16x32_bf16 v[76:79], v[228:231], v[188:191], v[76:79]
	v_mfma_f32_16x16x32_bf16 v[68:71], v[224:227], v[192:195], v[68:71]
	v_mfma_f32_16x16x32_bf16 v[68:71], v[228:231], v[212:215], v[68:71]
	s_setprio 0
	s_mov_b32 m0, s30
	v_lshl_add_u64 v[142:143], v[232:233], 0, s[52:53]
	s_barrier
	ds_read_b128 v[168:171], v146 offset:49152
	ds_read_b128 v[172:175], v146 offset:50176
	ds_read_b128 v[176:179], v146 offset:51200
	ds_read_b128 v[180:183], v146 offset:52224
	ds_read_b128 v[184:187], v146 offset:53248
	ds_read_b128 v[188:191], v146 offset:54272
	ds_read_b128 v[192:195], v146 offset:55296
	ds_read_b128 v[212:215], v146 offset:56320
	global_load_lds_dwordx4 v[142:143], off
	v_lshl_add_u64 v[142:143], v[234:235], 0, s[52:53]
	s_mov_b32 m0, s31
	s_nop 0
	global_load_lds_dwordx4 v[142:143], off
	s_barrier
; #define PG8_WAIT_V(n) asm volatile("s_waitcnt vmcnt(" #n ")" ::: "memory")
; #define PG8_WAIT_L(n) asm volatile("s_waitcnt lgkmcnt(" #n ")" ::: "memory")
; #define PG8_BAR __builtin_amdgcn_s_barrier()
; #define PG8_SCHED __builtin_amdgcn_sched_barrier(0)
; template <class Epi, class AddrA, class AddrB>
; __device__ __forceinline__ void gemm_phase(const Sched S, const int lda, const int ldb, const int K, const AddrA addrA,
;                                            const AddrB addrB, const Epi E) {
;     ...
;       PG8_BAR; PG8_WAIT_L(0); PG8_MMA(1, 0, At, B0); PG8_BAR; PG8_SCHED;
;       PG8_STAGE(PG8_SB(1, 1), b3 + hstepB, voffB);
;       PG8_WAIT_V(6); PG8_BAR; PG8_MMA(1, 1, At, B1); PG8_BAR;
;   __device__ __forceinline__ void operator()(EPI_ARGS) const {
;     ...
; #pragma unroll
;         for (int m = 0; m < 4; ++m) {
;           const size_t o = (row0 + ai * HALF + m * 16) * DM + col0 + bj * HALF;
;           x0[m] = *(const f32x4*)(xres + o);
;           x1[m] = *(const f32x4*)(xres + o + 4);
;         }
;         __builtin_amdgcn_sched_barrier(0);
; #pragma unroll
;         for (int m = 0; m < 4; ++m) {
;           const size_t o = (row0 + ai * HALF + m * 16) * DM + col0 + bj * HALF;
;           *(f32x4*)(hbuf + o) = acc[ai][bj][m][0] + x0[m] * ALPHA;
;           *(f32x4*)(hbuf + o + 4) = acc[ai][bj][m][1] + x1[m] * ALPHA;
;         }
	s_waitcnt lgkmcnt(0)
	s_setprio 1
	s_waitcnt lgkmcnt(0)
	v_mfma_f32_16x16x32_bf16 v[64:67], v[148:151], v[168:171], v[64:67]
	v_mfma_f32_16x16x32_bf16 v[64:67], v[152:155], v[172:175], v[64:67]
	v_mfma_f32_16x16x32_bf16 v[56:59], v[148:151], v[176:179], v[56:59]
	v_mfma_f32_16x16x32_bf16 v[56:59], v[152:155], v[180:183], v[56:59]
	v_mfma_f32_16x16x32_bf16 v[48:51], v[148:151], v[184:187], v[48:51]
	v_mfma_f32_16x16x32_bf16 v[48:51], v[152:155], v[188:191], v[48:51]
	v_mfma_f32_16x16x32_bf16 v[40:43], v[148:151], v[192:195], v[40:43]
	v_mfma_f32_16x16x32_bf16 v[40:43], v[152:155], v[212:215], v[40:43]
	v_mfma_f32_16x16x32_bf16 v[60:63], v[156:159], v[168:171], v[60:63]
	v_mfma_f32_16x16x32_bf16 v[60:63], v[160:163], v[172:175], v[60:63]
	v_mfma_f32_16x16x32_bf16 v[52:55], v[156:159], v[176:179], v[52:55]
	v_mfma_f32_16x16x32_bf16 v[52:55], v[160:163], v[180:183], v[52:55]
	v_mfma_f32_16x16x32_bf16 v[44:47], v[156:159], v[184:187], v[44:47]
	v_mfma_f32_16x16x32_bf16 v[44:47], v[160:163], v[188:191], v[44:47]
	v_mfma_f32_16x16x32_bf16 v[36:39], v[156:159], v[192:195], v[36:39]
	v_mfma_f32_16x16x32_bf16 v[36:39], v[160:163], v[212:215], v[36:39]
	s_setprio 0
	s_barrier
	s_add_u32 s16, s16, 0x80080
	s_addc_u32 s17, s17, 0
	s_add_i32 s18, s18, s25
	v_lshl_add_u64 v[142:143], s[16:17], 0, v[2:3]
	s_mov_b32 m0, s18
	s_nop 0
	global_load_lds_dwordx4 v[142:143], off
	v_lshl_add_u64 v[142:143], s[16:17], 0, v[0:1]
	s_add_i32 m0, s18, 0x2000
	s_nop 0
	global_load_lds_dwordx4 v[142:143], off
	s_waitcnt vmcnt(6)
	s_barrier
	s_setprio 1
	v_mfma_f32_16x16x32_bf16 v[32:35], v[216:219], v[168:171], v[32:35]
	v_mfma_f32_16x16x32_bf16 v[32:35], v[220:223], v[172:175], v[32:35]
	v_mfma_f32_16x16x32_bf16 v[24:27], v[216:219], v[176:179], v[24:27]
	v_mfma_f32_16x16x32_bf16 v[24:27], v[220:223], v[180:183], v[24:27]
	v_mfma_f32_16x16x32_bf16 v[16:19], v[216:219], v[184:187], v[16:19]
	v_mfma_f32_16x16x32_bf16 v[16:19], v[220:223], v[188:191], v[16:19]
	v_mfma_f32_16x16x32_bf16 v[8:11], v[216:219], v[192:195], v[8:11]
	v_mfma_f32_16x16x32_bf16 v[8:11], v[220:223], v[212:215], v[8:11]
	v_mfma_f32_16x16x32_bf16 v[28:31], v[224:227], v[168:171], v[28:31]
	v_mfma_f32_16x16x32_bf16 v[28:31], v[228:231], v[172:175], v[28:31]
	v_mfma_f32_16x16x32_bf16 v[20:23], v[224:227], v[176:179], v[20:23]
	v_mfma_f32_16x16x32_bf16 v[20:23], v[228:231], v[180:183], v[20:23]
	v_mfma_f32_16x16x32_bf16 v[12:15], v[224:227], v[184:187], v[12:15]
	v_mfma_f32_16x16x32_bf16 v[12:15], v[228:231], v[188:191], v[12:15]
	v_mfma_f32_16x16x32_bf16 v[4:7], v[224:227], v[192:195], v[4:7]
	v_mfma_f32_16x16x32_bf16 v[4:7], v[228:231], v[212:215], v[4:7]
	s_setprio 0
	s_add_i32 s38, s38, 2
	s_add_u32 s36, s36, 0x100
	s_addc_u32 s37, s37, 0
	s_add_u32 s14, s14, 0x100
	s_addc_u32 s15, s15, 0
	s_cmp_gt_u32 s38, 29
	s_barrier
	s_cbranch_scc0 .LBB0_619
	s_ashr_i32 s13, s12, 31
	v_lshl_or_b32 v142, s34, 8, v145
	v_ashrrev_i32_e32 v143, 31, v142
	s_lshl_b64 s[12:13], s[12:13], 21
	v_lshlrev_b64 v[184:185], 2, v[142:143]
	v_lshl_add_u64 v[188:189], s[12:13], 0, v[136:137]
	v_lshl_add_u64 v[186:187], s[0:1], 0, v[184:185]
	v_or_b32_e32 v190, 0x20000, v188
	v_mov_b32_e32 v191, v189
	v_or_b32_e32 v192, 0x40000, v188
	v_mov_b32_e32 v193, v189
	v_or_b32_e32 v194, 0x60000, v188
	v_mov_b32_e32 v195, v189
	v_lshl_add_u64 v[142:143], v[186:187], 0, v[188:189]
	v_lshl_add_u64 v[160:161], v[186:187], 0, v[190:191]
	v_lshl_add_u64 v[172:173], v[186:187], 0, v[192:193]
	v_lshl_add_u64 v[180:181], v[186:187], 0, v[194:195]
	flat_load_dwordx4 v[148:151], v[142:143]
	flat_load_dwordx4 v[152:155], v[142:143] offset:16
	flat_load_dwordx4 v[156:159], v[160:161]
	s_nop 0
	flat_load_dwordx4 v[160:163], v[160:161] offset:16
	s_nop 0
	flat_load_dwordx4 v[168:171], v[172:173]
	s_nop 0
	flat_load_dwordx4 v[172:175], v[172:173] offset:16
	s_nop 0
	flat_load_dwordx4 v[176:179], v[180:181]
	s_nop 0
	flat_load_dwordx4 v[180:183], v[180:181] offset:16
	v_lshl_add_u64 v[184:185], s[48:49], 0, v[184:185]
	s_mov_b32 s14, 0x3fb504f3
	s_waitcnt vmcnt(0) lgkmcnt(0)
	v_pk_fma_f32 v[148:149], v[148:149], s[14:15], v[128:129] op_sel_hi:[1,0,1]
	v_lshl_add_u64 v[128:129], v[184:185], 0, v[188:189]
	v_pk_fma_f32 v[126:127], v[154:155], s[14:15], v[126:127] op_sel_hi:[1,0,1]
	v_pk_fma_f32 v[124:125], v[152:153], s[14:15], v[124:125] op_sel_hi:[1,0,1]
	global_store_dwordx4 v[128:129], v[124:127], off offset:16
	v_pk_fma_f32 v[118:119], v[162:163], s[14:15], v[118:119] op_sel_hi:[1,0,1]
	v_pk_fma_f32 v[116:117], v[160:161], s[14:15], v[116:117] op_sel_hi:[1,0,1]
	v_lshl_add_u64 v[124:125], v[184:185], 0, v[190:191]
	v_pk_fma_f32 v[122:123], v[158:159], s[14:15], v[122:123] op_sel_hi:[1,0,1]
	v_pk_fma_f32 v[120:121], v[156:157], s[14:15], v[120:121] op_sel_hi:[1,0,1]
	global_store_dwordx4 v[124:125], v[116:119], off offset:16
	v_pk_fma_f32 v[110:111], v[174:175], s[14:15], v[110:111] op_sel_hi:[1,0,1]
	v_pk_fma_f32 v[108:109], v[172:173], s[14:15], v[108:109] op_sel_hi:[1,0,1]
	v_lshl_add_u64 v[116:117], v[184:185], 0, v[192:193]
	s_mov_b64 s[12:13], 0x200
	v_pk_fma_f32 v[150:151], v[150:151], s[14:15], v[130:131] op_sel_hi:[1,0,1]
	global_store_dwordx4 v[124:125], v[120:123], off
	v_pk_fma_f32 v[114:115], v[170:171], s[14:15], v[114:115] op_sel_hi:[1,0,1]
	v_pk_fma_f32 v[112:113], v[168:169], s[14:15], v[112:113] op_sel_hi:[1,0,1]
	global_store_dwordx4 v[116:117], v[108:111], off offset:16
	v_pk_fma_f32 v[106:107], v[178:179], s[14:15], v[106:107] op_sel_hi:[1,0,1]
	v_pk_fma_f32 v[104:105], v[176:177], s[14:15], v[104:105] op_sel_hi:[1,0,1]
	v_lshl_add_u64 v[108:109], v[184:185], 0, v[194:195]
	v_pk_fma_f32 v[102:103], v[182:183], s[14:15], v[102:103] op_sel_hi:[1,0,1]
	v_pk_fma_f32 v[100:101], v[180:181], s[14:15], v[100:101] op_sel_hi:[1,0,1]
	v_lshl_add_u64 v[124:125], v[186:187], 0, s[12:13]
	global_store_dwordx4 v[128:129], v[148:151], off
	global_store_dwordx4 v[116:117], v[112:115], off
	global_store_dwordx4 v[108:109], v[104:107], off
	global_store_dwordx4 v[108:109], v[100:103], off offset:16
	v_lshl_add_u64 v[112:113], v[124:125], 0, v[190:191]
	v_lshl_add_u64 v[120:121], v[124:125], 0, v[192:193]
	v_lshl_add_u64 v[130:131], v[124:125], 0, v[194:195]
	flat_load_dwordx4 v[100:103], v[142:143] offset:512
	flat_load_dwordx4 v[104:107], v[142:143] offset:528
	flat_load_dwordx4 v[108:111], v[112:113]
	s_nop 0
	flat_load_dwordx4 v[112:115], v[112:113] offset:16
	s_nop 0
	flat_load_dwordx4 v[116:119], v[120:121]
	s_nop 0
	flat_load_dwordx4 v[120:123], v[120:121] offset:16
	s_nop 0
	flat_load_dwordx4 v[124:127], v[130:131]
	flat_load_dwordx4 v[148:151], v[130:131] offset:16
	s_mov_b32 s3, 0x100000
	s_waitcnt vmcnt(0) lgkmcnt(0)
;   __device__ __forceinline__ void operator()(EPI_ARGS) const {
;     ...
; #pragma unroll
;         for (int m = 0; m < 4; ++m) {
;           const size_t o = (row0 + ai * HALF + m * 16) * DM + col0 + bj * HALF;
;           x0[m] = *(const f32x4*)(xres + o);
;           x1[m] = *(const f32x4*)(xres + o + 4);
;         }
;         __builtin_amdgcn_sched_barrier(0);
; #pragma unroll
;         for (int m = 0; m < 4; ++m) {
;           const size_t o = (row0 + ai * HALF + m * 16) * DM + col0 + bj * HALF;
;           *(f32x4*)(hbuf + o) = acc[ai][bj][m][0] + x0[m] * ALPHA;
;           *(f32x4*)(hbuf + o + 4) = acc[ai][bj][m][1] + x1[m] * ALPHA;
;         }
	v_pk_fma_f32 v[96:97], v[100:101], s[14:15], v[96:97] op_sel_hi:[1,0,1]
	v_add_co_u32_e32 v100, vcc, s3, v142
	s_mov_b32 s5, 0x120000
	s_nop 0
	v_addc_co_u32_e32 v101, vcc, 0, v143, vcc
	v_pk_fma_f32 v[98:99], v[102:103], s[14:15], v[98:99] op_sel_hi:[1,0,1]
	v_add_co_u32_e32 v102, vcc, s5, v142
	v_lshl_add_u64 v[130:131], v[184:185], 0, s[12:13]
	v_pk_fma_f32 v[94:95], v[106:107], s[14:15], v[94:95] op_sel_hi:[1,0,1]
	v_pk_fma_f32 v[92:93], v[104:105], s[14:15], v[92:93] op_sel_hi:[1,0,1]
	v_addc_co_u32_e32 v103, vcc, 0, v143, vcc
	s_mov_b32 s12, 0x140000
	global_store_dwordx4 v[128:129], v[92:95], off offset:528
	v_pk_fma_f32 v[86:87], v[114:115], s[14:15], v[86:87] op_sel_hi:[1,0,1]
	v_pk_fma_f32 v[84:85], v[112:113], s[14:15], v[84:85] op_sel_hi:[1,0,1]
	v_lshl_add_u64 v[92:93], v[130:131], 0, v[190:191]
	v_add_co_u32_e32 v104, vcc, s12, v142
	global_store_dwordx4 v[92:93], v[84:87], off offset:16
	v_pk_fma_f32 v[78:79], v[122:123], s[14:15], v[78:79] op_sel_hi:[1,0,1]
	v_pk_fma_f32 v[76:77], v[120:121], s[14:15], v[76:77] op_sel_hi:[1,0,1]
	v_lshl_add_u64 v[84:85], v[130:131], 0, v[192:193]
	v_addc_co_u32_e32 v105, vcc, 0, v143, vcc
	s_mov_b32 s13, 0x160000
	v_pk_fma_f32 v[90:91], v[110:111], s[14:15], v[90:91] op_sel_hi:[1,0,1]
	v_pk_fma_f32 v[88:89], v[108:109], s[14:15], v[88:89] op_sel_hi:[1,0,1]
	v_pk_fma_f32 v[82:83], v[118:119], s[14:15], v[82:83] op_sel_hi:[1,0,1]
	v_pk_fma_f32 v[80:81], v[116:117], s[14:15], v[80:81] op_sel_hi:[1,0,1]
	global_store_dwordx4 v[84:85], v[76:79], off offset:16
	v_pk_fma_f32 v[74:75], v[126:127], s[14:15], v[74:75] op_sel_hi:[1,0,1]
	v_pk_fma_f32 v[72:73], v[124:125], s[14:15], v[72:73] op_sel_hi:[1,0,1]
	v_lshl_add_u64 v[76:77], v[130:131], 0, v[194:195]
	v_pk_fma_f32 v[70:71], v[150:151], s[14:15], v[70:71] op_sel_hi:[1,0,1]
	v_pk_fma_f32 v[68:69], v[148:149], s[14:15], v[68:69] op_sel_hi:[1,0,1]
	s_mov_b64 s[16:17], 0x100000
	s_mov_b64 s[18:19], 0x120000
	s_mov_b64 s[34:35], 0x140000
	s_mov_b64 s[36:37], 0x160000
	v_add_co_u32_e32 v106, vcc, s13, v142
	global_store_dwordx4 v[128:129], v[96:99], off offset:512
	global_store_dwordx4 v[92:93], v[88:91], off
	global_store_dwordx4 v[84:85], v[80:83], off
	global_store_dwordx4 v[76:77], v[72:75], off
	global_store_dwordx4 v[76:77], v[68:71], off offset:16
	v_lshl_add_u64 v[80:81], v[142:143], 0, s[18:19]
	v_lshl_add_u64 v[72:73], v[142:143], 0, s[16:17]
	v_lshl_add_u64 v[88:89], v[142:143], 0, s[34:35]
	v_lshl_add_u64 v[96:97], v[142:143], 0, s[36:37]
	v_addc_co_u32_e32 v107, vcc, 0, v143, vcc
	flat_load_dwordx4 v[68:71], v[100:101]
	s_nop 0
	flat_load_dwordx4 v[72:75], v[72:73] offset:16
	s_nop 0
	flat_load_dwordx4 v[76:79], v[102:103]
	s_nop 0
	flat_load_dwordx4 v[80:83], v[80:81] offset:16
	s_nop 0
	flat_load_dwordx4 v[84:87], v[104:105]
	s_nop 0
	flat_load_dwordx4 v[88:91], v[88:89] offset:16
	s_nop 0
	flat_load_dwordx4 v[92:95], v[106:107]
	s_nop 0
	flat_load_dwordx4 v[96:99], v[96:97] offset:16
	s_waitcnt vmcnt(0) lgkmcnt(0)
; #define PG8_WAIT_V(n) asm volatile("s_waitcnt vmcnt(" #n ")" ::: "memory")
; #define PG8_BAR __builtin_amdgcn_s_barrier()
; template <class Epi, class AddrA, class AddrB>
; __device__ __forceinline__ void gemm_phase(const Sched S, const int lda, const int ldb, const int K, const AddrA addrA,
;                                            const AddrB addrB, const Epi E) {
;     ...
;     cur = nxt; cA = nA; cB = nB; ++ui;
;   }
;   PG8_WAIT_V(0);
;   if (wr == 0) PG8_BAR;
;   PG8_BAR;
;   __device__ __forceinline__ void operator()(EPI_ARGS) const {
;     ...
; #pragma unroll
;         for (int m = 0; m < 4; ++m) {
;           const size_t o = (row0 + ai * HALF + m * 16) * DM + col0 + bj * HALF;
;           x0[m] = *(const f32x4*)(xres + o);
;           x1[m] = *(const f32x4*)(xres + o + 4);
;         }
;         __builtin_amdgcn_sched_barrier(0);
; #pragma unroll
;         for (int m = 0; m < 4; ++m) {
;           const size_t o = (row0 + ai * HALF + m * 16) * DM + col0 + bj * HALF;
;           *(f32x4*)(hbuf + o) = acc[ai][bj][m][0] + x0[m] * ALPHA;
;           *(f32x4*)(hbuf + o + 4) = acc[ai][bj][m][1] + x1[m] * ALPHA;
;         }
	v_pk_fma_f32 v[66:67], v[70:71], s[14:15], v[66:67] op_sel_hi:[1,0,1]
	v_add_co_u32_e32 v70, vcc, s3, v128
	v_pk_fma_f32 v[64:65], v[68:69], s[14:15], v[64:65] op_sel_hi:[1,0,1]
	v_lshl_add_u64 v[68:69], v[128:129], 0, s[16:17]
	v_addc_co_u32_e32 v71, vcc, 0, v129, vcc
	v_pk_fma_f32 v[62:63], v[74:75], s[14:15], v[62:63] op_sel_hi:[1,0,1]
	v_pk_fma_f32 v[60:61], v[72:73], s[14:15], v[60:61] op_sel_hi:[1,0,1]
	global_store_dwordx4 v[68:69], v[60:63], off offset:16
	v_add_co_u32_e32 v68, vcc, s5, v128
	s_nop 0
	v_lshl_add_u64 v[60:61], v[128:129], 0, s[18:19]
	v_addc_co_u32_e32 v69, vcc, 0, v129, vcc
	v_add_co_u32_e32 v72, vcc, s12, v128
	v_pk_fma_f32 v[54:55], v[82:83], s[14:15], v[54:55] op_sel_hi:[1,0,1]
	v_pk_fma_f32 v[52:53], v[80:81], s[14:15], v[52:53] op_sel_hi:[1,0,1]
	v_addc_co_u32_e32 v73, vcc, 0, v129, vcc
	global_store_dwordx4 v[60:61], v[52:55], off offset:16
	v_pk_fma_f32 v[46:47], v[90:91], s[14:15], v[46:47] op_sel_hi:[1,0,1]
	v_pk_fma_f32 v[44:45], v[88:89], s[14:15], v[44:45] op_sel_hi:[1,0,1]
	v_lshl_add_u64 v[52:53], v[128:129], 0, s[34:35]
	v_add_co_u32_e32 v74, vcc, s13, v128
	v_pk_fma_f32 v[58:59], v[78:79], s[14:15], v[58:59] op_sel_hi:[1,0,1]
	v_pk_fma_f32 v[56:57], v[76:77], s[14:15], v[56:57] op_sel_hi:[1,0,1]
	v_pk_fma_f32 v[50:51], v[86:87], s[14:15], v[50:51] op_sel_hi:[1,0,1]
	v_pk_fma_f32 v[48:49], v[84:85], s[14:15], v[48:49] op_sel_hi:[1,0,1]
	global_store_dwordx4 v[52:53], v[44:47], off offset:16
	v_pk_fma_f32 v[42:43], v[94:95], s[14:15], v[42:43] op_sel_hi:[1,0,1]
	v_pk_fma_f32 v[40:41], v[92:93], s[14:15], v[40:41] op_sel_hi:[1,0,1]
	v_lshl_add_u64 v[44:45], v[128:129], 0, s[36:37]
	v_addc_co_u32_e32 v75, vcc, 0, v129, vcc
	v_pk_fma_f32 v[38:39], v[98:99], s[14:15], v[38:39] op_sel_hi:[1,0,1]
	v_pk_fma_f32 v[36:37], v[96:97], s[14:15], v[36:37] op_sel_hi:[1,0,1]
	s_mov_b64 s[12:13], 0x100200
	s_mov_b64 s[16:17], 0x120200
	s_mov_b64 s[18:19], 0x140200
	s_mov_b64 s[34:35], 0x160200
	global_store_dwordx4 v[70:71], v[64:67], off
	global_store_dwordx4 v[68:69], v[56:59], off
	global_store_dwordx4 v[72:73], v[48:51], off
	global_store_dwordx4 v[74:75], v[40:43], off
	global_store_dwordx4 v[44:45], v[36:39], off offset:16
	v_lshl_add_u64 v[44:45], v[142:143], 0, s[12:13]
	v_lshl_add_u64 v[48:49], v[142:143], 0, s[16:17]
	v_lshl_add_u64 v[60:61], v[142:143], 0, s[18:19]
	v_lshl_add_u64 v[64:65], v[142:143], 0, s[34:35]
	flat_load_dwordx4 v[36:39], v[100:101] offset:512
	flat_load_dwordx4 v[40:43], v[102:103] offset:512
	s_nop 0
	flat_load_dwordx4 v[44:47], v[44:45] offset:16
	s_nop 0
	flat_load_dwordx4 v[48:51], v[48:49] offset:16
	s_nop 0
	flat_load_dwordx4 v[52:55], v[104:105] offset:512
	flat_load_dwordx4 v[56:59], v[106:107] offset:512
	s_nop 0
	flat_load_dwordx4 v[60:63], v[60:61] offset:16
	s_nop 0
	flat_load_dwordx4 v[64:67], v[64:65] offset:16
	s_waitcnt vmcnt(0) lgkmcnt(0)
	v_pk_fma_f32 v[32:33], v[36:37], s[14:15], v[32:33] op_sel_hi:[1,0,1]
	v_lshl_add_u64 v[36:37], v[128:129], 0, s[12:13]
	v_pk_fma_f32 v[30:31], v[46:47], s[14:15], v[30:31] op_sel_hi:[1,0,1]
	v_pk_fma_f32 v[28:29], v[44:45], s[14:15], v[28:29] op_sel_hi:[1,0,1]
	global_store_dwordx4 v[36:37], v[28:31], off offset:16
	v_pk_fma_f32 v[22:23], v[50:51], s[14:15], v[22:23] op_sel_hi:[1,0,1]
	v_pk_fma_f32 v[20:21], v[48:49], s[14:15], v[20:21] op_sel_hi:[1,0,1]
	v_lshl_add_u64 v[28:29], v[128:129], 0, s[16:17]
	global_store_dwordx4 v[28:29], v[20:23], off offset:16
	v_pk_fma_f32 v[14:15], v[62:63], s[14:15], v[14:15] op_sel_hi:[1,0,1]
	v_pk_fma_f32 v[12:13], v[60:61], s[14:15], v[12:13] op_sel_hi:[1,0,1]
	v_lshl_add_u64 v[20:21], v[128:129], 0, s[18:19]
	v_pk_fma_f32 v[34:35], v[38:39], s[14:15], v[34:35] op_sel_hi:[1,0,1]
	v_pk_fma_f32 v[26:27], v[42:43], s[14:15], v[26:27] op_sel_hi:[1,0,1]
	v_pk_fma_f32 v[24:25], v[40:41], s[14:15], v[24:25] op_sel_hi:[1,0,1]
	v_pk_fma_f32 v[18:19], v[54:55], s[14:15], v[18:19] op_sel_hi:[1,0,1]
	v_pk_fma_f32 v[16:17], v[52:53], s[14:15], v[16:17] op_sel_hi:[1,0,1]
	global_store_dwordx4 v[20:21], v[12:15], off offset:16
	v_pk_fma_f32 v[10:11], v[58:59], s[14:15], v[10:11] op_sel_hi:[1,0,1]
	v_pk_fma_f32 v[8:9], v[56:57], s[14:15], v[8:9] op_sel_hi:[1,0,1]
	v_lshl_add_u64 v[12:13], v[128:129], 0, s[34:35]
	v_pk_fma_f32 v[6:7], v[66:67], s[14:15], v[6:7] op_sel_hi:[1,0,1]
	v_pk_fma_f32 v[4:5], v[64:65], s[14:15], v[4:5] op_sel_hi:[1,0,1]
	s_and_b64 vcc, exec, s[6:7]
	s_mov_b32 s34, s4
	s_mov_b32 s12, s2
	s_mov_b64 s[14:15], s[10:11]
	s_mov_b64 s[16:17], s[8:9]
	global_store_dwordx4 v[70:71], v[32:35], off offset:512
	global_store_dwordx4 v[68:69], v[24:27], off offset:512
	global_store_dwordx4 v[72:73], v[16:19], off offset:512
	global_store_dwordx4 v[74:75], v[8:11], off offset:512
	global_store_dwordx4 v[12:13], v[4:7], off offset:16
	s_cbranch_vccz .LBB0_616
	s_waitcnt vmcnt(0)
	s_cmpk_gt_u32 s20, 0xff
	s_cbranch_scc1 .LBB0_623
	s_barrier
